# GEMM K loops: s_setprio 1 on the load segments instead of the MFMA segments
# speedup vs baseline: 1.0042x; 1.0009x over previous
; #define PG8_STAGE(bufoff, gbase, voff) do { _Pragma("unroll") for (int _i = 0; _i < 2; ++_i) \
;         __builtin_amdgcn_global_load_lds((const unsigned*)((const char*)(gbase) + (voff)[_i]), (PG8_LAS unsigned*)(lds + (bufoff) + ldsw + _i * 8192), 16, 0, 0); } while (0)
; #define PG8_LDA(dst, b, h) do { _Pragma("unroll") for (int m = 0; m < 4; ++m) _Pragma("unroll") for (int k = 0; k < 2; ++k) dst[m][k] = *(const PG8_LAS bf16x8*)(lds + PG8_SA(b, h) + aoff + m * 2048 + k * 1024); } while (0)
; #define PG8_LDB(dst, b, h) do { _Pragma("unroll") for (int n = 0; n < 2; ++n) _Pragma("unroll") for (int k = 0; k < 2; ++k) dst[n][k] = *(const PG8_LAS bf16x8*)(lds + PG8_SB(b, h) + boff + n * 2048 + k * 1024); } while (0)
; #define PG8_MMA(ai, bj, At, Bt) do { __builtin_amdgcn_s_setprio(1); _Pragma("unroll") for (int m = 0; m < 4; ++m) _Pragma("unroll") for (int n = 0; n < 2; ++n) _Pragma("unroll") for (int k = 0; k < 2; ++k) \
;         acc[ai][bj][m][n] = __builtin_amdgcn_mfma_f32_16x16x32_bf16(Bt[n][k], At[m][k], acc[ai][bj][m][n], 0, 0, 0); __builtin_amdgcn_s_setprio(0); } while (0)
; #define PG8_WAIT_V(n) asm volatile("s_waitcnt vmcnt(" #n ")" ::: "memory")
; #define PG8_WAIT_L(n) asm volatile("s_waitcnt lgkmcnt(" #n ")" ::: "memory")
; #define PG8_BAR __builtin_amdgcn_s_barrier()
; #define PG8_SCHED __builtin_amdgcn_sched_barrier(0)
; template <class Epi, class Sched, bool ALIGN_EPI = false, bool SP2 = false>
; __device__ __forceinline__ void gemm_phase(PG8_LAS unsigned char* lds, const Gemm g, const Sched& S, const Epi& E) {
;     ...
;             PG8_LDB(B0, 0, 0); PG8_LDB(B1, 0, 1); PG8_SCHED; PG8_LDA(At, 0, 0); PG8_STAGE(PG8_SA(1, 1), a1 + hstepA, voffA);
;             PG8_WAIT_V(8); PG8_WAIT_L(0); PG8_BAR; PG8_MMA(0, 0, At, B0); PG8_MMA(0, 1, At, B1); PG8_BAR; PG8_SCHED;
;             PG8_LDA(At, 0, 1); PG8_STAGE(PG8_SB(0, 0), b2, voffB); PG8_STAGE(PG8_SB(0, 1), b2 + hstepB, voffB); PG8_STAGE(PG8_SA(0, 0), a2, voffA);
.LBB0_156:
	s_setprio 1
	v_add_u32_e32 v156, s25, v149
	v_add_u32_e32 v172, s40, v149
	ds_read_b128 v[140:143], v156
	ds_read_b128 v[144:147], v156 offset:1024
	ds_read_b128 v[152:155], v156 offset:2048
	ds_read_b128 v[156:159], v156 offset:3072
	ds_read_b128 v[160:163], v172
	ds_read_b128 v[164:167], v172 offset:1024
	ds_read_b128 v[168:171], v172 offset:2048
	ds_read_b128 v[172:175], v172 offset:3072
	s_add_u32 s2, s26, 0xfffc0080
	s_addc_u32 s8, s27, -1
	s_cmp_eq_u32 s78, 12
	s_cselect_b32 s31, s19, s8
	s_cselect_b32 s30, s71, s2
	s_cselect_b32 s29, s17, s75
	s_cselect_b32 s28, s72, s74
	v_lshl_add_u64 v[226:227], s[26:27], 0, v[138:139]
	s_add_i32 m0, s43, 0xc000
	ds_read_b128 v[176:179], v151
	ds_read_b128 v[180:183], v151 offset:1024
	ds_read_b128 v[184:187], v151 offset:2048
	ds_read_b128 v[188:191], v151 offset:3072
	ds_read_b128 v[204:207], v151 offset:4096
	ds_read_b128 v[208:211], v151 offset:5120
	ds_read_b128 v[218:221], v151 offset:6144
	ds_read_b128 v[222:225], v151 offset:7168
	global_load_lds_dwordx4 v[226:227], off
	v_lshl_add_u64 v[226:227], s[26:27], 0, v[136:137]
	s_add_i32 m0, s43, 0xe000
	s_nop 0
	global_load_lds_dwordx4 v[226:227], off
	s_waitcnt vmcnt(8)
	s_waitcnt lgkmcnt(0)
	s_setprio 0
	s_barrier
	s_waitcnt lgkmcnt(0)
	v_mfma_f32_16x16x32_bf16 v[116:119], v[140:143], v[176:179], v[116:119]
	v_mfma_f32_16x16x32_bf16 v[112:115], v[152:155], v[176:179], v[112:115]
	v_mfma_f32_16x16x32_bf16 v[108:111], v[140:143], v[184:187], v[108:111]
	v_mfma_f32_16x16x32_bf16 v[104:107], v[152:155], v[184:187], v[104:107]
	v_mfma_f32_16x16x32_bf16 v[92:95], v[140:143], v[204:207], v[92:95]
	v_mfma_f32_16x16x32_bf16 v[88:91], v[152:155], v[204:207], v[88:91]
	v_mfma_f32_16x16x32_bf16 v[76:79], v[140:143], v[218:221], v[76:79]
	v_mfma_f32_16x16x32_bf16 v[72:75], v[152:155], v[218:221], v[72:75]
	v_mfma_f32_16x16x32_bf16 v[116:119], v[144:147], v[180:183], v[116:119]
	v_mfma_f32_16x16x32_bf16 v[112:115], v[156:159], v[180:183], v[112:115]
	v_mfma_f32_16x16x32_bf16 v[108:111], v[144:147], v[188:191], v[108:111]
	v_mfma_f32_16x16x32_bf16 v[104:107], v[156:159], v[188:191], v[104:107]
	v_mfma_f32_16x16x32_bf16 v[92:95], v[144:147], v[208:211], v[92:95]
	v_mfma_f32_16x16x32_bf16 v[88:91], v[156:159], v[208:211], v[88:91]
	v_mfma_f32_16x16x32_bf16 v[76:79], v[144:147], v[222:225], v[76:79]
	v_mfma_f32_16x16x32_bf16 v[72:75], v[156:159], v[222:225], v[72:75]
	v_mfma_f32_16x16x32_bf16 v[124:127], v[160:163], v[176:179], v[124:127]
	v_mfma_f32_16x16x32_bf16 v[120:123], v[168:171], v[176:179], v[120:123]
	v_mfma_f32_16x16x32_bf16 v[100:103], v[160:163], v[184:187], v[100:103]
	v_mfma_f32_16x16x32_bf16 v[96:99], v[168:171], v[184:187], v[96:99]
	v_mfma_f32_16x16x32_bf16 v[84:87], v[160:163], v[204:207], v[84:87]
	v_mfma_f32_16x16x32_bf16 v[80:83], v[168:171], v[204:207], v[80:83]
	v_mfma_f32_16x16x32_bf16 v[68:71], v[160:163], v[218:221], v[68:71]
	v_mfma_f32_16x16x32_bf16 v[64:67], v[168:171], v[218:221], v[64:67]
	v_mfma_f32_16x16x32_bf16 v[124:127], v[164:167], v[180:183], v[124:127]
	v_mfma_f32_16x16x32_bf16 v[120:123], v[172:175], v[180:183], v[120:123]
	v_mfma_f32_16x16x32_bf16 v[100:103], v[164:167], v[188:191], v[100:103]
	v_mfma_f32_16x16x32_bf16 v[96:99], v[172:175], v[188:191], v[96:99]
	v_mfma_f32_16x16x32_bf16 v[84:87], v[164:167], v[208:211], v[84:87]
	v_mfma_f32_16x16x32_bf16 v[80:83], v[172:175], v[208:211], v[80:83]
	v_mfma_f32_16x16x32_bf16 v[68:71], v[164:167], v[222:225], v[68:71]
	v_mfma_f32_16x16x32_bf16 v[64:67], v[172:175], v[222:225], v[64:67]
	s_barrier
	s_setprio 1
	s_mov_b32 m0, s38
	v_lshl_add_u64 v[226:227], s[28:29], 0, v[192:193]
	s_add_u32 s8, s28, 0x40000
	ds_read_b128 v[176:179], v151 offset:16384
	ds_read_b128 v[180:183], v151 offset:17408
	ds_read_b128 v[184:187], v151 offset:18432
	ds_read_b128 v[188:191], v151 offset:19456
	ds_read_b128 v[204:207], v151 offset:20480
	ds_read_b128 v[208:211], v151 offset:21504
	ds_read_b128 v[218:221], v151 offset:22528
	ds_read_b128 v[222:225], v151 offset:23552
	global_load_lds_dwordx4 v[226:227], off
	v_lshl_add_u64 v[228:229], s[28:29], 0, v[128:129]
	s_mov_b32 m0, s39
	s_addc_u32 s9, s29, 0
	global_load_lds_dwordx4 v[228:229], off
	v_lshl_add_u64 v[230:231], s[8:9], 0, v[192:193]
	s_mov_b32 m0, s41
	v_lshl_add_u64 v[232:233], s[30:31], 0, v[130:131]
	global_load_lds_dwordx4 v[230:231], off
	v_lshl_add_u64 v[230:231], s[8:9], 0, v[128:129]
	s_mov_b32 m0, s42
	s_nop 0
	global_load_lds_dwordx4 v[230:231], off
	v_lshl_add_u64 v[230:231], s[30:31], 0, v[132:133]
	s_mov_b32 m0, s43
	s_nop 0
	global_load_lds_dwordx4 v[230:231], off
	s_mov_b32 m0, s44
	s_nop 0
	global_load_lds_dwordx4 v[232:233], off
	s_waitcnt vmcnt(8)
	s_waitcnt lgkmcnt(0)
	s_setprio 0
	s_barrier
; #define PG8_STAGE(bufoff, gbase, voff) do { _Pragma("unroll") for (int _i = 0; _i < 2; ++_i) \
;         __builtin_amdgcn_global_load_lds((const unsigned*)((const char*)(gbase) + (voff)[_i]), (PG8_LAS unsigned*)(lds + (bufoff) + ldsw + _i * 8192), 16, 0, 0); } while (0)
; #define PG8_LDA(dst, b, h) do { _Pragma("unroll") for (int m = 0; m < 4; ++m) _Pragma("unroll") for (int k = 0; k < 2; ++k) dst[m][k] = *(const PG8_LAS bf16x8*)(lds + PG8_SA(b, h) + aoff + m * 2048 + k * 1024); } while (0)
; #define PG8_LDB(dst, b, h) do { _Pragma("unroll") for (int n = 0; n < 2; ++n) _Pragma("unroll") for (int k = 0; k < 2; ++k) dst[n][k] = *(const PG8_LAS bf16x8*)(lds + PG8_SB(b, h) + boff + n * 2048 + k * 1024); } while (0)
; #define PG8_MMA(ai, bj, At, Bt) do { __builtin_amdgcn_s_setprio(1); _Pragma("unroll") for (int m = 0; m < 4; ++m) _Pragma("unroll") for (int n = 0; n < 2; ++n) _Pragma("unroll") for (int k = 0; k < 2; ++k) \
;         acc[ai][bj][m][n] = __builtin_amdgcn_mfma_f32_16x16x32_bf16(Bt[n][k], At[m][k], acc[ai][bj][m][n], 0, 0, 0); __builtin_amdgcn_s_setprio(0); } while (0)
; #define PG8_WAIT_V(n) asm volatile("s_waitcnt vmcnt(" #n ")" ::: "memory")
; #define PG8_WAIT_L(n) asm volatile("s_waitcnt lgkmcnt(" #n ")" ::: "memory")
; #define PG8_BAR __builtin_amdgcn_s_barrier()
; #define PG8_SCHED __builtin_amdgcn_sched_barrier(0)
; template <class Epi, class Sched, bool ALIGN_EPI = false, bool SP2 = false>
; __device__ __forceinline__ void gemm_phase(PG8_LAS unsigned char* lds, const Gemm g, const Sched& S, const Epi& E) {
;     ...
;             PG8_WAIT_V(8); PG8_WAIT_L(0); PG8_BAR; PG8_MMA(1, 0, At, B0); PG8_MMA(1, 1, At, B1); PG8_BAR; PG8_SCHED;
;             PG8_LDB(B0, 1, 0); PG8_LDB(B1, 1, 1); PG8_SCHED; PG8_LDA(At, 1, 0); PG8_STAGE(PG8_SA(0, 1), a2 + hstepA, voffA);
;             PG8_WAIT_V(8); PG8_WAIT_L(0); PG8_BAR; PG8_MMA(0, 0, At, B0); PG8_MMA(0, 1, At, B1); PG8_BAR; PG8_SCHED;
	s_waitcnt lgkmcnt(0)
	v_mfma_f32_16x16x32_bf16 v[60:63], v[140:143], v[176:179], v[60:63]
	v_mfma_f32_16x16x32_bf16 v[56:59], v[152:155], v[176:179], v[56:59]
	v_mfma_f32_16x16x32_bf16 v[44:47], v[140:143], v[184:187], v[44:47]
	v_mfma_f32_16x16x32_bf16 v[40:43], v[152:155], v[184:187], v[40:43]
	v_mfma_f32_16x16x32_bf16 v[28:31], v[140:143], v[204:207], v[28:31]
	v_mfma_f32_16x16x32_bf16 v[24:27], v[152:155], v[204:207], v[24:27]
	v_mfma_f32_16x16x32_bf16 v[12:15], v[140:143], v[218:221], v[12:15]
	v_mfma_f32_16x16x32_bf16 v[8:11], v[152:155], v[218:221], v[8:11]
	v_mfma_f32_16x16x32_bf16 v[60:63], v[144:147], v[180:183], v[60:63]
	v_mfma_f32_16x16x32_bf16 v[56:59], v[156:159], v[180:183], v[56:59]
	v_mfma_f32_16x16x32_bf16 v[44:47], v[144:147], v[188:191], v[44:47]
	v_mfma_f32_16x16x32_bf16 v[40:43], v[156:159], v[188:191], v[40:43]
	v_mfma_f32_16x16x32_bf16 v[28:31], v[144:147], v[208:211], v[28:31]
	v_mfma_f32_16x16x32_bf16 v[24:27], v[156:159], v[208:211], v[24:27]
	v_mfma_f32_16x16x32_bf16 v[12:15], v[144:147], v[222:225], v[12:15]
	v_mfma_f32_16x16x32_bf16 v[8:11], v[156:159], v[222:225], v[8:11]
	v_mfma_f32_16x16x32_bf16 v[52:55], v[160:163], v[176:179], v[52:55]
	v_mfma_f32_16x16x32_bf16 v[48:51], v[168:171], v[176:179], v[48:51]
	v_mfma_f32_16x16x32_bf16 v[36:39], v[160:163], v[184:187], v[36:39]
	v_mfma_f32_16x16x32_bf16 v[32:35], v[168:171], v[184:187], v[32:35]
	v_mfma_f32_16x16x32_bf16 v[20:23], v[160:163], v[204:207], v[20:23]
	v_mfma_f32_16x16x32_bf16 v[16:19], v[168:171], v[204:207], v[16:19]
	v_mfma_f32_16x16x32_bf16 v[4:7], v[160:163], v[218:221], v[4:7]
	v_mfma_f32_16x16x32_bf16 v[0:3], v[168:171], v[218:221], v[0:3]
	v_mfma_f32_16x16x32_bf16 v[52:55], v[164:167], v[180:183], v[52:55]
	v_mfma_f32_16x16x32_bf16 v[48:51], v[172:175], v[180:183], v[48:51]
	v_mfma_f32_16x16x32_bf16 v[36:39], v[164:167], v[188:191], v[36:39]
	v_mfma_f32_16x16x32_bf16 v[32:35], v[172:175], v[188:191], v[32:35]
	v_mfma_f32_16x16x32_bf16 v[20:23], v[164:167], v[208:211], v[20:23]
	v_mfma_f32_16x16x32_bf16 v[16:19], v[172:175], v[208:211], v[16:19]
	v_mfma_f32_16x16x32_bf16 v[4:7], v[164:167], v[222:225], v[4:7]
	v_mfma_f32_16x16x32_bf16 v[0:3], v[172:175], v[222:225], v[0:3]
	s_barrier
	s_setprio 1
	v_add_u32_e32 v156, s49, v149
	v_add_u32_e32 v172, s64, v149
	ds_read_b128 v[140:143], v156
	ds_read_b128 v[144:147], v156 offset:1024
	ds_read_b128 v[152:155], v156 offset:2048
	ds_read_b128 v[156:159], v156 offset:3072
	ds_read_b128 v[160:163], v172
	ds_read_b128 v[164:167], v172 offset:1024
	ds_read_b128 v[168:171], v172 offset:2048
	ds_read_b128 v[172:175], v172 offset:3072
	s_add_u32 s8, s30, 0x40000
	s_addc_u32 s9, s31, 0
	s_mov_b32 m0, s45
	v_lshl_add_u64 v[234:235], s[8:9], 0, v[132:133]
	ds_read_b128 v[176:179], v151 offset:32768
	ds_read_b128 v[180:183], v151 offset:33792
	ds_read_b128 v[184:187], v151 offset:34816
	ds_read_b128 v[188:191], v151 offset:35840
	ds_read_b128 v[204:207], v151 offset:36864
	ds_read_b128 v[208:211], v151 offset:37888
	ds_read_b128 v[218:221], v151 offset:38912
	ds_read_b128 v[222:225], v151 offset:39936
	global_load_lds_dwordx4 v[234:235], off
	v_lshl_add_u64 v[234:235], s[8:9], 0, v[130:131]
	s_mov_b32 m0, s48
	s_nop 0
	global_load_lds_dwordx4 v[234:235], off
	s_waitcnt vmcnt(8)
	s_waitcnt lgkmcnt(0)
	s_setprio 0
	s_barrier
	s_waitcnt lgkmcnt(0)
	v_mfma_f32_16x16x32_bf16 v[116:119], v[140:143], v[176:179], v[116:119]
	v_mfma_f32_16x16x32_bf16 v[112:115], v[152:155], v[176:179], v[112:115]
	v_mfma_f32_16x16x32_bf16 v[108:111], v[140:143], v[184:187], v[108:111]
	v_mfma_f32_16x16x32_bf16 v[104:107], v[152:155], v[184:187], v[104:107]
	v_mfma_f32_16x16x32_bf16 v[92:95], v[140:143], v[204:207], v[92:95]
	v_mfma_f32_16x16x32_bf16 v[88:91], v[152:155], v[204:207], v[88:91]
	v_mfma_f32_16x16x32_bf16 v[76:79], v[140:143], v[218:221], v[76:79]
	v_mfma_f32_16x16x32_bf16 v[72:75], v[152:155], v[218:221], v[72:75]
	v_mfma_f32_16x16x32_bf16 v[116:119], v[144:147], v[180:183], v[116:119]
	v_mfma_f32_16x16x32_bf16 v[112:115], v[156:159], v[180:183], v[112:115]
	v_mfma_f32_16x16x32_bf16 v[108:111], v[144:147], v[188:191], v[108:111]
	v_mfma_f32_16x16x32_bf16 v[104:107], v[156:159], v[188:191], v[104:107]
	v_mfma_f32_16x16x32_bf16 v[92:95], v[144:147], v[208:211], v[92:95]
	v_mfma_f32_16x16x32_bf16 v[88:91], v[156:159], v[208:211], v[88:91]
	v_mfma_f32_16x16x32_bf16 v[76:79], v[144:147], v[222:225], v[76:79]
	v_mfma_f32_16x16x32_bf16 v[72:75], v[156:159], v[222:225], v[72:75]
	v_mfma_f32_16x16x32_bf16 v[124:127], v[160:163], v[176:179], v[124:127]
	v_mfma_f32_16x16x32_bf16 v[120:123], v[168:171], v[176:179], v[120:123]
	v_mfma_f32_16x16x32_bf16 v[100:103], v[160:163], v[184:187], v[100:103]
	v_mfma_f32_16x16x32_bf16 v[96:99], v[168:171], v[184:187], v[96:99]
	v_mfma_f32_16x16x32_bf16 v[84:87], v[160:163], v[204:207], v[84:87]
	v_mfma_f32_16x16x32_bf16 v[80:83], v[168:171], v[204:207], v[80:83]
	v_mfma_f32_16x16x32_bf16 v[68:71], v[160:163], v[218:221], v[68:71]
	v_mfma_f32_16x16x32_bf16 v[64:67], v[168:171], v[218:221], v[64:67]
	v_mfma_f32_16x16x32_bf16 v[124:127], v[164:167], v[180:183], v[124:127]
	v_mfma_f32_16x16x32_bf16 v[120:123], v[172:175], v[180:183], v[120:123]
	v_mfma_f32_16x16x32_bf16 v[100:103], v[164:167], v[188:191], v[100:103]
	v_mfma_f32_16x16x32_bf16 v[96:99], v[172:175], v[188:191], v[96:99]
	v_mfma_f32_16x16x32_bf16 v[84:87], v[164:167], v[208:211], v[84:87]
	v_mfma_f32_16x16x32_bf16 v[80:83], v[172:175], v[208:211], v[80:83]
	v_mfma_f32_16x16x32_bf16 v[68:71], v[164:167], v[222:225], v[68:71]
	v_mfma_f32_16x16x32_bf16 v[64:67], v[172:175], v[222:225], v[64:67]
	s_barrier
; #define PG8_STAGE(bufoff, gbase, voff) do { _Pragma("unroll") for (int _i = 0; _i < 2; ++_i) \
;         __builtin_amdgcn_global_load_lds((const unsigned*)((const char*)(gbase) + (voff)[_i]), (PG8_LAS unsigned*)(lds + (bufoff) + ldsw + _i * 8192), 16, 0, 0); } while (0)
; #define PG8_LDA(dst, b, h) do { _Pragma("unroll") for (int m = 0; m < 4; ++m) _Pragma("unroll") for (int k = 0; k < 2; ++k) dst[m][k] = *(const PG8_LAS bf16x8*)(lds + PG8_SA(b, h) + aoff + m * 2048 + k * 1024); } while (0)
; #define PG8_MMA(ai, bj, At, Bt) do { __builtin_amdgcn_s_setprio(1); _Pragma("unroll") for (int m = 0; m < 4; ++m) _Pragma("unroll") for (int n = 0; n < 2; ++n) _Pragma("unroll") for (int k = 0; k < 2; ++k) \
;         acc[ai][bj][m][n] = __builtin_amdgcn_mfma_f32_16x16x32_bf16(Bt[n][k], At[m][k], acc[ai][bj][m][n], 0, 0, 0); __builtin_amdgcn_s_setprio(0); } while (0)
; #define PG8_WAIT_V(n) asm volatile("s_waitcnt vmcnt(" #n ")" ::: "memory")
; #define PG8_WAIT_L(n) asm volatile("s_waitcnt lgkmcnt(" #n ")" ::: "memory")
; #define PG8_BAR __builtin_amdgcn_s_barrier()
; #define PG8_SCHED __builtin_amdgcn_sched_barrier(0)
; template <class Epi, class Sched, bool ALIGN_EPI = false, bool SP2 = false>
; __device__ __forceinline__ void gemm_phase(PG8_LAS unsigned char* lds, const Gemm g, const Sched& S, const Epi& E) {
;     ...
;             PG8_LDA(At, 1, 1); PG8_STAGE(PG8_SB(1, 0), b3, voffB); PG8_STAGE(PG8_SB(1, 1), b3 + hstepB, voffB); PG8_STAGE(PG8_SA(1, 0), a3, voffA);
;             PG8_WAIT_V(8); PG8_WAIT_L(0); PG8_BAR; PG8_MMA(1, 0, At, B0); PG8_MMA(1, 1, At, B1); PG8_BAR; PG8_SCHED;
;     ...
;         if constexpr (ALIGN_EPI) { if (wr == 0) PG8_BAR; }
	s_setprio 1
	s_mov_b32 m0, s50
	v_lshl_add_u64 v[226:227], v[226:227], 0, s[76:77]
	s_add_u32 s8, s28, 0x40080
	ds_read_b128 v[176:179], v151 offset:49152
	ds_read_b128 v[180:183], v151 offset:50176
	ds_read_b128 v[184:187], v151 offset:51200
	ds_read_b128 v[188:191], v151 offset:52224
	ds_read_b128 v[204:207], v151 offset:53248
	ds_read_b128 v[208:211], v151 offset:54272
	ds_read_b128 v[218:221], v151 offset:55296
	ds_read_b128 v[222:225], v151 offset:56320
	global_load_lds_dwordx4 v[226:227], off
	v_lshl_add_u64 v[226:227], v[228:229], 0, s[76:77]
	s_mov_b32 m0, s51
	s_addc_u32 s9, s29, 0
	global_load_lds_dwordx4 v[226:227], off
	v_lshl_add_u64 v[226:227], s[8:9], 0, v[192:193]
	s_mov_b32 m0, s65
	s_nop 0
	global_load_lds_dwordx4 v[226:227], off
	v_lshl_add_u64 v[226:227], s[8:9], 0, v[128:129]
	s_mov_b32 m0, s66
	s_nop 0
	global_load_lds_dwordx4 v[226:227], off
	v_lshl_add_u64 v[226:227], v[230:231], 0, s[76:77]
	s_mov_b32 m0, s60
	s_nop 0
	global_load_lds_dwordx4 v[226:227], off
	v_lshl_add_u64 v[226:227], v[232:233], 0, s[76:77]
	s_mov_b32 m0, s61
	s_nop 0
	global_load_lds_dwordx4 v[226:227], off
	s_waitcnt vmcnt(8)
	s_waitcnt lgkmcnt(0)
	s_setprio 0
	s_barrier
	s_waitcnt lgkmcnt(0)
	v_mfma_f32_16x16x32_bf16 v[60:63], v[140:143], v[176:179], v[60:63]
	v_mfma_f32_16x16x32_bf16 v[56:59], v[152:155], v[176:179], v[56:59]
	v_mfma_f32_16x16x32_bf16 v[44:47], v[140:143], v[184:187], v[44:47]
	v_mfma_f32_16x16x32_bf16 v[40:43], v[152:155], v[184:187], v[40:43]
	v_mfma_f32_16x16x32_bf16 v[28:31], v[140:143], v[204:207], v[28:31]
	v_mfma_f32_16x16x32_bf16 v[24:27], v[152:155], v[204:207], v[24:27]
	v_mfma_f32_16x16x32_bf16 v[12:15], v[140:143], v[218:221], v[12:15]
	v_mfma_f32_16x16x32_bf16 v[8:11], v[152:155], v[218:221], v[8:11]
	v_mfma_f32_16x16x32_bf16 v[60:63], v[144:147], v[180:183], v[60:63]
	v_mfma_f32_16x16x32_bf16 v[56:59], v[156:159], v[180:183], v[56:59]
	v_mfma_f32_16x16x32_bf16 v[44:47], v[144:147], v[188:191], v[44:47]
	v_mfma_f32_16x16x32_bf16 v[40:43], v[156:159], v[188:191], v[40:43]
	v_mfma_f32_16x16x32_bf16 v[28:31], v[144:147], v[208:211], v[28:31]
	v_mfma_f32_16x16x32_bf16 v[24:27], v[156:159], v[208:211], v[24:27]
	v_mfma_f32_16x16x32_bf16 v[12:15], v[144:147], v[222:225], v[12:15]
	v_mfma_f32_16x16x32_bf16 v[8:11], v[156:159], v[222:225], v[8:11]
	v_mfma_f32_16x16x32_bf16 v[52:55], v[160:163], v[176:179], v[52:55]
	v_mfma_f32_16x16x32_bf16 v[48:51], v[168:171], v[176:179], v[48:51]
	v_mfma_f32_16x16x32_bf16 v[36:39], v[160:163], v[184:187], v[36:39]
	v_mfma_f32_16x16x32_bf16 v[32:35], v[168:171], v[184:187], v[32:35]
	v_mfma_f32_16x16x32_bf16 v[20:23], v[160:163], v[204:207], v[20:23]
	v_mfma_f32_16x16x32_bf16 v[16:19], v[168:171], v[204:207], v[16:19]
	v_mfma_f32_16x16x32_bf16 v[4:7], v[160:163], v[218:221], v[4:7]
	v_mfma_f32_16x16x32_bf16 v[0:3], v[168:171], v[218:221], v[0:3]
	v_mfma_f32_16x16x32_bf16 v[52:55], v[164:167], v[180:183], v[52:55]
	v_mfma_f32_16x16x32_bf16 v[48:51], v[172:175], v[180:183], v[48:51]
	v_mfma_f32_16x16x32_bf16 v[36:39], v[164:167], v[188:191], v[36:39]
	v_mfma_f32_16x16x32_bf16 v[32:35], v[172:175], v[188:191], v[32:35]
	v_mfma_f32_16x16x32_bf16 v[20:23], v[164:167], v[208:211], v[20:23]
	v_mfma_f32_16x16x32_bf16 v[16:19], v[172:175], v[208:211], v[16:19]
	v_mfma_f32_16x16x32_bf16 v[4:7], v[164:167], v[222:225], v[4:7]
	v_mfma_f32_16x16x32_bf16 v[0:3], v[172:175], v[222:225], v[0:3]
	s_barrier
	s_setprio 1
	s_add_i32 s78, s78, 2
	s_add_u32 s74, s74, 0x100
	s_addc_u32 s75, s75, 0
	s_add_u32 s26, s26, 0x100
	s_addc_u32 s27, s27, 0
	s_cmp_gt_u32 s78, 13
	s_cbranch_scc0 .LBB0_156
	s_setprio 0
	s_and_b64 vcc, exec, s[14:15]
	s_cbranch_vccz .LBB0_159
	s_barrier

; #define PG8_STAGE(bufoff, gbase, voff) do { _Pragma("unroll") for (int _i = 0; _i < 2; ++_i) \
;         __builtin_amdgcn_global_load_lds((const unsigned*)((const char*)(gbase) + (voff)[_i]), (PG8_LAS unsigned*)(lds + (bufoff) + ldsw + _i * 8192), 16, 0, 0); } while (0)
; #define PG8_LDA(dst, b, h) do { _Pragma("unroll") for (int m = 0; m < 4; ++m) _Pragma("unroll") for (int k = 0; k < 2; ++k) dst[m][k] = *(const PG8_LAS bf16x8*)(lds + PG8_SA(b, h) + aoff + m * 2048 + k * 1024); } while (0)
; #define PG8_LDB(dst, b, h) do { _Pragma("unroll") for (int n = 0; n < 2; ++n) _Pragma("unroll") for (int k = 0; k < 2; ++k) dst[n][k] = *(const PG8_LAS bf16x8*)(lds + PG8_SB(b, h) + boff + n * 2048 + k * 1024); } while (0)
; #define PG8_MMA(ai, bj, At, Bt) do { __builtin_amdgcn_s_setprio(1); _Pragma("unroll") for (int m = 0; m < 4; ++m) _Pragma("unroll") for (int n = 0; n < 2; ++n) _Pragma("unroll") for (int k = 0; k < 2; ++k) \
;         acc[ai][bj][m][n] = __builtin_amdgcn_mfma_f32_16x16x32_bf16(Bt[n][k], At[m][k], acc[ai][bj][m][n], 0, 0, 0); __builtin_amdgcn_s_setprio(0); } while (0)
; #define PG8_WAIT_V(n) asm volatile("s_waitcnt vmcnt(" #n ")" ::: "memory")
; #define PG8_WAIT_L(n) asm volatile("s_waitcnt lgkmcnt(" #n ")" ::: "memory")
; #define PG8_BAR __builtin_amdgcn_s_barrier()
; #define PG8_SCHED __builtin_amdgcn_sched_barrier(0)
; template <class Epi, class Sched, bool ALIGN_EPI = false, bool SP2 = false>
; __device__ __forceinline__ void gemm_phase(PG8_LAS unsigned char* lds, const Gemm g, const Sched& S, const Epi& E) {
;     ...
;             PG8_LDB(B0, 0, 0); PG8_LDB(B1, 0, 1); PG8_SCHED; PG8_LDA(At, 0, 0); PG8_STAGE(PG8_SA(1, 1), a1 + hstepA, voffA);
;             PG8_WAIT_V(8); PG8_WAIT_L(0); PG8_BAR; PG8_MMA(0, 0, At, B0); PG8_MMA(0, 1, At, B1); PG8_BAR; PG8_SCHED;
;             PG8_LDA(At, 0, 1); PG8_STAGE(PG8_SB(0, 0), b2, voffB); PG8_STAGE(PG8_SB(0, 1), b2 + hstepB, voffB); PG8_STAGE(PG8_SA(0, 0), a2, voffA);
.LBB0_180:
	s_setprio 1
	v_add_u32_e32 v154, s38, v139
	v_add_u32_e32 v170, s41, v139
	ds_read_b128 v[142:145], v154
	ds_read_b128 v[146:149], v154 offset:1024
	ds_read_b128 v[150:153], v154 offset:2048
	ds_read_b128 v[154:157], v154 offset:3072
	ds_read_b128 v[158:161], v170
	ds_read_b128 v[162:165], v170 offset:1024
	ds_read_b128 v[166:169], v170 offset:2048
	ds_read_b128 v[170:173], v170 offset:3072
	s_add_u32 s2, s24, 0xfffc0080
	s_addc_u32 s8, s25, -1
	s_cmp_eq_u32 s75, 12
	s_cselect_b32 s29, s1, s8
	s_cselect_b32 s28, s19, s2
	s_cselect_b32 s27, s17, s74
	s_cselect_b32 s26, s71, s72
	v_lshl_add_u64 v[190:191], s[24:25], 0, v[136:137]
	s_add_i32 m0, s44, 0xc000
	ds_read_b128 v[174:177], v141
	ds_read_b128 v[178:181], v141 offset:1024
	ds_read_b128 v[182:185], v141 offset:2048
	ds_read_b128 v[186:189], v141 offset:3072
	ds_read_b128 v[204:207], v141 offset:4096
	ds_read_b128 v[208:211], v141 offset:5120
	ds_read_b128 v[218:221], v141 offset:6144
	ds_read_b128 v[222:225], v141 offset:7168
	global_load_lds_dwordx4 v[190:191], off
	v_lshl_add_u64 v[190:191], s[24:25], 0, v[134:135]
	s_add_i32 m0, s44, 0xe000
	s_nop 0
	global_load_lds_dwordx4 v[190:191], off
	s_waitcnt vmcnt(8)
	s_waitcnt lgkmcnt(0)
	s_setprio 0
	s_barrier
	s_waitcnt lgkmcnt(0)
	v_mfma_f32_16x16x32_bf16 v[124:127], v[142:145], v[174:177], v[124:127]
	v_mfma_f32_16x16x32_bf16 v[120:123], v[150:153], v[174:177], v[120:123]
	v_mfma_f32_16x16x32_bf16 v[116:119], v[142:145], v[182:185], v[116:119]
	v_mfma_f32_16x16x32_bf16 v[112:115], v[150:153], v[182:185], v[112:115]
	v_mfma_f32_16x16x32_bf16 v[100:103], v[142:145], v[204:207], v[100:103]
	v_mfma_f32_16x16x32_bf16 v[96:99], v[150:153], v[204:207], v[96:99]
	v_mfma_f32_16x16x32_bf16 v[84:87], v[142:145], v[218:221], v[84:87]
	v_mfma_f32_16x16x32_bf16 v[80:83], v[150:153], v[218:221], v[80:83]
	v_mfma_f32_16x16x32_bf16 v[124:127], v[146:149], v[178:181], v[124:127]
	v_mfma_f32_16x16x32_bf16 v[120:123], v[154:157], v[178:181], v[120:123]
	v_mfma_f32_16x16x32_bf16 v[116:119], v[146:149], v[186:189], v[116:119]
	v_mfma_f32_16x16x32_bf16 v[112:115], v[154:157], v[186:189], v[112:115]
	v_mfma_f32_16x16x32_bf16 v[100:103], v[146:149], v[208:211], v[100:103]
	v_mfma_f32_16x16x32_bf16 v[96:99], v[154:157], v[208:211], v[96:99]
	v_mfma_f32_16x16x32_bf16 v[84:87], v[146:149], v[222:225], v[84:87]
	v_mfma_f32_16x16x32_bf16 v[80:83], v[154:157], v[222:225], v[80:83]
	v_mfma_f32_16x16x32_bf16 v[108:111], v[158:161], v[174:177], v[108:111]
	v_mfma_f32_16x16x32_bf16 v[104:107], v[166:169], v[174:177], v[104:107]
	v_mfma_f32_16x16x32_bf16 v[92:95], v[158:161], v[182:185], v[92:95]
	v_mfma_f32_16x16x32_bf16 v[88:91], v[166:169], v[182:185], v[88:91]
	v_mfma_f32_16x16x32_bf16 v[76:79], v[158:161], v[204:207], v[76:79]
	v_mfma_f32_16x16x32_bf16 v[72:75], v[166:169], v[204:207], v[72:75]
	v_mfma_f32_16x16x32_bf16 v[68:71], v[158:161], v[218:221], v[68:71]
	v_mfma_f32_16x16x32_bf16 v[64:67], v[166:169], v[218:221], v[64:67]
	v_mfma_f32_16x16x32_bf16 v[108:111], v[162:165], v[178:181], v[108:111]
	v_mfma_f32_16x16x32_bf16 v[104:107], v[170:173], v[178:181], v[104:107]
	v_mfma_f32_16x16x32_bf16 v[92:95], v[162:165], v[186:189], v[92:95]
	v_mfma_f32_16x16x32_bf16 v[88:91], v[170:173], v[186:189], v[88:91]
	v_mfma_f32_16x16x32_bf16 v[76:79], v[162:165], v[208:211], v[76:79]
	v_mfma_f32_16x16x32_bf16 v[72:75], v[170:173], v[208:211], v[72:75]
	v_mfma_f32_16x16x32_bf16 v[68:71], v[162:165], v[222:225], v[68:71]
	v_mfma_f32_16x16x32_bf16 v[64:67], v[170:173], v[222:225], v[64:67]
	s_barrier
	s_setprio 1
	s_mov_b32 m0, s39
	v_lshl_add_u64 v[190:191], s[26:27], 0, v[192:193]
	s_add_u32 s8, s26, 0x40000
	ds_read_b128 v[174:177], v141 offset:16384
	ds_read_b128 v[178:181], v141 offset:17408
	ds_read_b128 v[182:185], v141 offset:18432
	ds_read_b128 v[186:189], v141 offset:19456
	ds_read_b128 v[204:207], v141 offset:20480
	ds_read_b128 v[208:211], v141 offset:21504
	ds_read_b128 v[218:221], v141 offset:22528
	ds_read_b128 v[222:225], v141 offset:23552
	global_load_lds_dwordx4 v[190:191], off
	v_lshl_add_u64 v[226:227], s[26:27], 0, v[132:133]
	s_mov_b32 m0, s40
	s_addc_u32 s9, s27, 0
	global_load_lds_dwordx4 v[226:227], off
	v_lshl_add_u64 v[228:229], s[8:9], 0, v[192:193]
	s_mov_b32 m0, s42
	v_lshl_add_u64 v[230:231], s[28:29], 0, v[130:131]
	global_load_lds_dwordx4 v[228:229], off
	v_lshl_add_u64 v[228:229], s[8:9], 0, v[132:133]
	s_mov_b32 m0, s43
	s_nop 0
	global_load_lds_dwordx4 v[228:229], off
	v_lshl_add_u64 v[228:229], s[28:29], 0, v[128:129]
	s_mov_b32 m0, s44
	s_nop 0
	global_load_lds_dwordx4 v[228:229], off
	s_mov_b32 m0, s45
	s_nop 0
	global_load_lds_dwordx4 v[230:231], off
	s_waitcnt vmcnt(8)
	s_waitcnt lgkmcnt(0)
	s_setprio 0
	s_barrier
; #define PG8_STAGE(bufoff, gbase, voff) do { _Pragma("unroll") for (int _i = 0; _i < 2; ++_i) \
;         __builtin_amdgcn_global_load_lds((const unsigned*)((const char*)(gbase) + (voff)[_i]), (PG8_LAS unsigned*)(lds + (bufoff) + ldsw + _i * 8192), 16, 0, 0); } while (0)
; #define PG8_LDA(dst, b, h) do { _Pragma("unroll") for (int m = 0; m < 4; ++m) _Pragma("unroll") for (int k = 0; k < 2; ++k) dst[m][k] = *(const PG8_LAS bf16x8*)(lds + PG8_SA(b, h) + aoff + m * 2048 + k * 1024); } while (0)
; #define PG8_LDB(dst, b, h) do { _Pragma("unroll") for (int n = 0; n < 2; ++n) _Pragma("unroll") for (int k = 0; k < 2; ++k) dst[n][k] = *(const PG8_LAS bf16x8*)(lds + PG8_SB(b, h) + boff + n * 2048 + k * 1024); } while (0)
; #define PG8_MMA(ai, bj, At, Bt) do { __builtin_amdgcn_s_setprio(1); _Pragma("unroll") for (int m = 0; m < 4; ++m) _Pragma("unroll") for (int n = 0; n < 2; ++n) _Pragma("unroll") for (int k = 0; k < 2; ++k) \
;         acc[ai][bj][m][n] = __builtin_amdgcn_mfma_f32_16x16x32_bf16(Bt[n][k], At[m][k], acc[ai][bj][m][n], 0, 0, 0); __builtin_amdgcn_s_setprio(0); } while (0)
; #define PG8_WAIT_V(n) asm volatile("s_waitcnt vmcnt(" #n ")" ::: "memory")
; #define PG8_WAIT_L(n) asm volatile("s_waitcnt lgkmcnt(" #n ")" ::: "memory")
; #define PG8_BAR __builtin_amdgcn_s_barrier()
; #define PG8_SCHED __builtin_amdgcn_sched_barrier(0)
; template <class Epi, class Sched, bool ALIGN_EPI = false, bool SP2 = false>
; __device__ __forceinline__ void gemm_phase(PG8_LAS unsigned char* lds, const Gemm g, const Sched& S, const Epi& E) {
;     ...
;             PG8_WAIT_V(8); PG8_WAIT_L(0); PG8_BAR; PG8_MMA(1, 0, At, B0); PG8_MMA(1, 1, At, B1); PG8_BAR; PG8_SCHED;
;             PG8_LDB(B0, 1, 0); PG8_LDB(B1, 1, 1); PG8_SCHED; PG8_LDA(At, 1, 0); PG8_STAGE(PG8_SA(0, 1), a2 + hstepA, voffA);
;             PG8_WAIT_V(8); PG8_WAIT_L(0); PG8_BAR; PG8_MMA(0, 0, At, B0); PG8_MMA(0, 1, At, B1); PG8_BAR; PG8_SCHED;
	s_waitcnt lgkmcnt(0)
	v_mfma_f32_16x16x32_bf16 v[60:63], v[142:145], v[174:177], v[60:63]
	v_mfma_f32_16x16x32_bf16 v[56:59], v[150:153], v[174:177], v[56:59]
	v_mfma_f32_16x16x32_bf16 v[52:55], v[142:145], v[182:185], v[52:55]
	v_mfma_f32_16x16x32_bf16 v[48:51], v[150:153], v[182:185], v[48:51]
	v_mfma_f32_16x16x32_bf16 v[36:39], v[142:145], v[204:207], v[36:39]
	v_mfma_f32_16x16x32_bf16 v[32:35], v[150:153], v[204:207], v[32:35]
	v_mfma_f32_16x16x32_bf16 v[20:23], v[142:145], v[218:221], v[20:23]
	v_mfma_f32_16x16x32_bf16 v[16:19], v[150:153], v[218:221], v[16:19]
	v_mfma_f32_16x16x32_bf16 v[60:63], v[146:149], v[178:181], v[60:63]
	v_mfma_f32_16x16x32_bf16 v[56:59], v[154:157], v[178:181], v[56:59]
	v_mfma_f32_16x16x32_bf16 v[52:55], v[146:149], v[186:189], v[52:55]
	v_mfma_f32_16x16x32_bf16 v[48:51], v[154:157], v[186:189], v[48:51]
	v_mfma_f32_16x16x32_bf16 v[36:39], v[146:149], v[208:211], v[36:39]
	v_mfma_f32_16x16x32_bf16 v[32:35], v[154:157], v[208:211], v[32:35]
	v_mfma_f32_16x16x32_bf16 v[20:23], v[146:149], v[222:225], v[20:23]
	v_mfma_f32_16x16x32_bf16 v[16:19], v[154:157], v[222:225], v[16:19]
	v_mfma_f32_16x16x32_bf16 v[44:47], v[158:161], v[174:177], v[44:47]
	v_mfma_f32_16x16x32_bf16 v[40:43], v[166:169], v[174:177], v[40:43]
	v_mfma_f32_16x16x32_bf16 v[28:31], v[158:161], v[182:185], v[28:31]
	v_mfma_f32_16x16x32_bf16 v[24:27], v[166:169], v[182:185], v[24:27]
	v_mfma_f32_16x16x32_bf16 v[12:15], v[158:161], v[204:207], v[12:15]
	v_mfma_f32_16x16x32_bf16 v[8:11], v[166:169], v[204:207], v[8:11]
	v_mfma_f32_16x16x32_bf16 v[4:7], v[158:161], v[218:221], v[4:7]
	v_mfma_f32_16x16x32_bf16 v[0:3], v[166:169], v[218:221], v[0:3]
	v_mfma_f32_16x16x32_bf16 v[44:47], v[162:165], v[178:181], v[44:47]
	v_mfma_f32_16x16x32_bf16 v[40:43], v[170:173], v[178:181], v[40:43]
	v_mfma_f32_16x16x32_bf16 v[28:31], v[162:165], v[186:189], v[28:31]
	v_mfma_f32_16x16x32_bf16 v[24:27], v[170:173], v[186:189], v[24:27]
	v_mfma_f32_16x16x32_bf16 v[12:15], v[162:165], v[208:211], v[12:15]
	v_mfma_f32_16x16x32_bf16 v[8:11], v[170:173], v[208:211], v[8:11]
	v_mfma_f32_16x16x32_bf16 v[4:7], v[162:165], v[222:225], v[4:7]
	v_mfma_f32_16x16x32_bf16 v[0:3], v[170:173], v[222:225], v[0:3]
	s_barrier
	s_setprio 1
	v_add_u32_e32 v154, s50, v139
	v_add_u32_e32 v170, s65, v139
	ds_read_b128 v[142:145], v154
	ds_read_b128 v[146:149], v154 offset:1024
	ds_read_b128 v[150:153], v154 offset:2048
	ds_read_b128 v[154:157], v154 offset:3072
	ds_read_b128 v[158:161], v170
	ds_read_b128 v[162:165], v170 offset:1024
	ds_read_b128 v[166:169], v170 offset:2048
	ds_read_b128 v[170:173], v170 offset:3072
	s_add_u32 s8, s28, 0x40000
	s_addc_u32 s9, s29, 0
	s_mov_b32 m0, s48
	v_lshl_add_u64 v[232:233], s[8:9], 0, v[128:129]
	ds_read_b128 v[174:177], v141 offset:32768
	ds_read_b128 v[178:181], v141 offset:33792
	ds_read_b128 v[182:185], v141 offset:34816
	ds_read_b128 v[186:189], v141 offset:35840
	ds_read_b128 v[204:207], v141 offset:36864
	ds_read_b128 v[208:211], v141 offset:37888
	ds_read_b128 v[218:221], v141 offset:38912
	ds_read_b128 v[222:225], v141 offset:39936
	global_load_lds_dwordx4 v[232:233], off
	v_lshl_add_u64 v[232:233], s[8:9], 0, v[130:131]
	s_mov_b32 m0, s49
	s_nop 0
	global_load_lds_dwordx4 v[232:233], off
	s_waitcnt vmcnt(8)
	s_waitcnt lgkmcnt(0)
	s_setprio 0
	s_barrier
	s_waitcnt lgkmcnt(0)
	v_mfma_f32_16x16x32_bf16 v[124:127], v[142:145], v[174:177], v[124:127]
	v_mfma_f32_16x16x32_bf16 v[120:123], v[150:153], v[174:177], v[120:123]
	v_mfma_f32_16x16x32_bf16 v[116:119], v[142:145], v[182:185], v[116:119]
	v_mfma_f32_16x16x32_bf16 v[112:115], v[150:153], v[182:185], v[112:115]
	v_mfma_f32_16x16x32_bf16 v[100:103], v[142:145], v[204:207], v[100:103]
	v_mfma_f32_16x16x32_bf16 v[96:99], v[150:153], v[204:207], v[96:99]
	v_mfma_f32_16x16x32_bf16 v[84:87], v[142:145], v[218:221], v[84:87]
	v_mfma_f32_16x16x32_bf16 v[80:83], v[150:153], v[218:221], v[80:83]
	v_mfma_f32_16x16x32_bf16 v[124:127], v[146:149], v[178:181], v[124:127]
	v_mfma_f32_16x16x32_bf16 v[120:123], v[154:157], v[178:181], v[120:123]
	v_mfma_f32_16x16x32_bf16 v[116:119], v[146:149], v[186:189], v[116:119]
	v_mfma_f32_16x16x32_bf16 v[112:115], v[154:157], v[186:189], v[112:115]
	v_mfma_f32_16x16x32_bf16 v[100:103], v[146:149], v[208:211], v[100:103]
	v_mfma_f32_16x16x32_bf16 v[96:99], v[154:157], v[208:211], v[96:99]
	v_mfma_f32_16x16x32_bf16 v[84:87], v[146:149], v[222:225], v[84:87]
	v_mfma_f32_16x16x32_bf16 v[80:83], v[154:157], v[222:225], v[80:83]
	v_mfma_f32_16x16x32_bf16 v[108:111], v[158:161], v[174:177], v[108:111]
	v_mfma_f32_16x16x32_bf16 v[104:107], v[166:169], v[174:177], v[104:107]
	v_mfma_f32_16x16x32_bf16 v[92:95], v[158:161], v[182:185], v[92:95]
	v_mfma_f32_16x16x32_bf16 v[88:91], v[166:169], v[182:185], v[88:91]
	v_mfma_f32_16x16x32_bf16 v[76:79], v[158:161], v[204:207], v[76:79]
	v_mfma_f32_16x16x32_bf16 v[72:75], v[166:169], v[204:207], v[72:75]
	v_mfma_f32_16x16x32_bf16 v[68:71], v[158:161], v[218:221], v[68:71]
	v_mfma_f32_16x16x32_bf16 v[64:67], v[166:169], v[218:221], v[64:67]
	v_mfma_f32_16x16x32_bf16 v[108:111], v[162:165], v[178:181], v[108:111]
	v_mfma_f32_16x16x32_bf16 v[104:107], v[170:173], v[178:181], v[104:107]
	v_mfma_f32_16x16x32_bf16 v[92:95], v[162:165], v[186:189], v[92:95]
	v_mfma_f32_16x16x32_bf16 v[88:91], v[170:173], v[186:189], v[88:91]
	v_mfma_f32_16x16x32_bf16 v[76:79], v[162:165], v[208:211], v[76:79]
	v_mfma_f32_16x16x32_bf16 v[72:75], v[170:173], v[208:211], v[72:75]
	v_mfma_f32_16x16x32_bf16 v[68:71], v[162:165], v[222:225], v[68:71]
	v_mfma_f32_16x16x32_bf16 v[64:67], v[170:173], v[222:225], v[64:67]
	s_barrier
; #define PG8_STAGE(bufoff, gbase, voff) do { _Pragma("unroll") for (int _i = 0; _i < 2; ++_i) \
;         __builtin_amdgcn_global_load_lds((const unsigned*)((const char*)(gbase) + (voff)[_i]), (PG8_LAS unsigned*)(lds + (bufoff) + ldsw + _i * 8192), 16, 0, 0); } while (0)
; #define PG8_LDA(dst, b, h) do { _Pragma("unroll") for (int m = 0; m < 4; ++m) _Pragma("unroll") for (int k = 0; k < 2; ++k) dst[m][k] = *(const PG8_LAS bf16x8*)(lds + PG8_SA(b, h) + aoff + m * 2048 + k * 1024); } while (0)
; #define PG8_MMA(ai, bj, At, Bt) do { __builtin_amdgcn_s_setprio(1); _Pragma("unroll") for (int m = 0; m < 4; ++m) _Pragma("unroll") for (int n = 0; n < 2; ++n) _Pragma("unroll") for (int k = 0; k < 2; ++k) \
;         acc[ai][bj][m][n] = __builtin_amdgcn_mfma_f32_16x16x32_bf16(Bt[n][k], At[m][k], acc[ai][bj][m][n], 0, 0, 0); __builtin_amdgcn_s_setprio(0); } while (0)
; #define PG8_WAIT_V(n) asm volatile("s_waitcnt vmcnt(" #n ")" ::: "memory")
; #define PG8_WAIT_L(n) asm volatile("s_waitcnt lgkmcnt(" #n ")" ::: "memory")
; #define PG8_BAR __builtin_amdgcn_s_barrier()
; #define PG8_SCHED __builtin_amdgcn_sched_barrier(0)
; template <class Epi, class Sched, bool ALIGN_EPI = false, bool SP2 = false>
; __device__ __forceinline__ void gemm_phase(PG8_LAS unsigned char* lds, const Gemm g, const Sched& S, const Epi& E) {
;     ...
;             PG8_LDA(At, 1, 1); PG8_STAGE(PG8_SB(1, 0), b3, voffB); PG8_STAGE(PG8_SB(1, 1), b3 + hstepB, voffB); PG8_STAGE(PG8_SA(1, 0), a3, voffA);
;             PG8_WAIT_V(8); PG8_WAIT_L(0); PG8_BAR; PG8_MMA(1, 0, At, B0); PG8_MMA(1, 1, At, B1); PG8_BAR; PG8_SCHED;
;     ...
;         if constexpr (ALIGN_EPI) { if (wr == 0) PG8_BAR; }
	s_setprio 1
	s_mov_b32 m0, s51
	v_lshl_add_u64 v[190:191], v[190:191], 0, s[76:77]
	s_add_u32 s8, s26, 0x40080
	ds_read_b128 v[174:177], v141 offset:49152
	ds_read_b128 v[178:181], v141 offset:50176
	ds_read_b128 v[182:185], v141 offset:51200
	ds_read_b128 v[186:189], v141 offset:52224
	ds_read_b128 v[204:207], v141 offset:53248
	ds_read_b128 v[208:211], v141 offset:54272
	ds_read_b128 v[218:221], v141 offset:55296
	ds_read_b128 v[222:225], v141 offset:56320
	global_load_lds_dwordx4 v[190:191], off
	v_lshl_add_u64 v[190:191], v[226:227], 0, s[76:77]
	s_mov_b32 m0, s60
	s_addc_u32 s9, s27, 0
	global_load_lds_dwordx4 v[190:191], off
	v_lshl_add_u64 v[190:191], s[8:9], 0, v[192:193]
	s_mov_b32 m0, s66
	s_nop 0
	global_load_lds_dwordx4 v[190:191], off
	v_lshl_add_u64 v[190:191], s[8:9], 0, v[132:133]
	s_mov_b32 m0, s67
	s_nop 0
	global_load_lds_dwordx4 v[190:191], off
	v_lshl_add_u64 v[190:191], v[228:229], 0, s[76:77]
	s_mov_b32 m0, s61
	s_nop 0
	global_load_lds_dwordx4 v[190:191], off
	v_lshl_add_u64 v[190:191], v[230:231], 0, s[76:77]
	s_mov_b32 m0, s64
	s_nop 0
	global_load_lds_dwordx4 v[190:191], off
	s_waitcnt vmcnt(8)
	s_waitcnt lgkmcnt(0)
	s_setprio 0
	s_barrier
	s_waitcnt lgkmcnt(0)
	v_mfma_f32_16x16x32_bf16 v[60:63], v[142:145], v[174:177], v[60:63]
	v_mfma_f32_16x16x32_bf16 v[56:59], v[150:153], v[174:177], v[56:59]
	v_mfma_f32_16x16x32_bf16 v[52:55], v[142:145], v[182:185], v[52:55]
	v_mfma_f32_16x16x32_bf16 v[48:51], v[150:153], v[182:185], v[48:51]
	v_mfma_f32_16x16x32_bf16 v[36:39], v[142:145], v[204:207], v[36:39]
	v_mfma_f32_16x16x32_bf16 v[32:35], v[150:153], v[204:207], v[32:35]
	v_mfma_f32_16x16x32_bf16 v[20:23], v[142:145], v[218:221], v[20:23]
	v_mfma_f32_16x16x32_bf16 v[16:19], v[150:153], v[218:221], v[16:19]
	v_mfma_f32_16x16x32_bf16 v[60:63], v[146:149], v[178:181], v[60:63]
	v_mfma_f32_16x16x32_bf16 v[56:59], v[154:157], v[178:181], v[56:59]
	v_mfma_f32_16x16x32_bf16 v[52:55], v[146:149], v[186:189], v[52:55]
	v_mfma_f32_16x16x32_bf16 v[48:51], v[154:157], v[186:189], v[48:51]
	v_mfma_f32_16x16x32_bf16 v[36:39], v[146:149], v[208:211], v[36:39]
	v_mfma_f32_16x16x32_bf16 v[32:35], v[154:157], v[208:211], v[32:35]
	v_mfma_f32_16x16x32_bf16 v[20:23], v[146:149], v[222:225], v[20:23]
	v_mfma_f32_16x16x32_bf16 v[16:19], v[154:157], v[222:225], v[16:19]
	v_mfma_f32_16x16x32_bf16 v[44:47], v[158:161], v[174:177], v[44:47]
	v_mfma_f32_16x16x32_bf16 v[40:43], v[166:169], v[174:177], v[40:43]
	v_mfma_f32_16x16x32_bf16 v[28:31], v[158:161], v[182:185], v[28:31]
	v_mfma_f32_16x16x32_bf16 v[24:27], v[166:169], v[182:185], v[24:27]
	v_mfma_f32_16x16x32_bf16 v[12:15], v[158:161], v[204:207], v[12:15]
	v_mfma_f32_16x16x32_bf16 v[8:11], v[166:169], v[204:207], v[8:11]
	v_mfma_f32_16x16x32_bf16 v[4:7], v[158:161], v[218:221], v[4:7]
	v_mfma_f32_16x16x32_bf16 v[0:3], v[166:169], v[218:221], v[0:3]
	v_mfma_f32_16x16x32_bf16 v[44:47], v[162:165], v[178:181], v[44:47]
	v_mfma_f32_16x16x32_bf16 v[40:43], v[170:173], v[178:181], v[40:43]
	v_mfma_f32_16x16x32_bf16 v[28:31], v[162:165], v[186:189], v[28:31]
	v_mfma_f32_16x16x32_bf16 v[24:27], v[170:173], v[186:189], v[24:27]
	v_mfma_f32_16x16x32_bf16 v[12:15], v[162:165], v[208:211], v[12:15]
	v_mfma_f32_16x16x32_bf16 v[8:11], v[170:173], v[208:211], v[8:11]
	v_mfma_f32_16x16x32_bf16 v[4:7], v[162:165], v[222:225], v[4:7]
	v_mfma_f32_16x16x32_bf16 v[0:3], v[170:173], v[222:225], v[0:3]
	s_barrier
	s_setprio 1
	s_add_i32 s75, s75, 2
	s_add_u32 s72, s72, 0x100
	s_addc_u32 s74, s74, 0
	s_add_u32 s24, s24, 0x100
	s_addc_u32 s25, s25, 0
	s_cmp_gt_u32 s75, 13
	s_cbranch_scc0 .LBB0_180
	s_setprio 0
	s_and_b64 vcc, exec, s[10:11]
	s_cbranch_vccz .LBB0_183
	s_barrier

; #define PG8_STAGE(bufoff, gbase, voff) do { _Pragma("unroll") for (int _i = 0; _i < 2; ++_i) \
;         __builtin_amdgcn_global_load_lds((const unsigned*)((const char*)(gbase) + (voff)[_i]), (PG8_LAS unsigned*)(lds + (bufoff) + ldsw + _i * 8192), 16, 0, 0); } while (0)
; #define PG8_LDA(dst, b, h) do { _Pragma("unroll") for (int m = 0; m < 4; ++m) _Pragma("unroll") for (int k = 0; k < 2; ++k) dst[m][k] = *(const PG8_LAS bf16x8*)(lds + PG8_SA(b, h) + aoff + m * 2048 + k * 1024); } while (0)
; #define PG8_LDB(dst, b, h) do { _Pragma("unroll") for (int n = 0; n < 2; ++n) _Pragma("unroll") for (int k = 0; k < 2; ++k) dst[n][k] = *(const PG8_LAS bf16x8*)(lds + PG8_SB(b, h) + boff + n * 2048 + k * 1024); } while (0)
; #define PG8_MMA(ai, bj, At, Bt) do { __builtin_amdgcn_s_setprio(1); _Pragma("unroll") for (int m = 0; m < 4; ++m) _Pragma("unroll") for (int n = 0; n < 2; ++n) _Pragma("unroll") for (int k = 0; k < 2; ++k) \
;         acc[ai][bj][m][n] = __builtin_amdgcn_mfma_f32_16x16x32_bf16(Bt[n][k], At[m][k], acc[ai][bj][m][n], 0, 0, 0); __builtin_amdgcn_s_setprio(0); } while (0)
; #define PG8_WAIT_V(n) asm volatile("s_waitcnt vmcnt(" #n ")" ::: "memory")
; #define PG8_WAIT_L(n) asm volatile("s_waitcnt lgkmcnt(" #n ")" ::: "memory")
; #define PG8_BAR __builtin_amdgcn_s_barrier()
; #define PG8_SCHED __builtin_amdgcn_sched_barrier(0)
; template <class Epi, class Sched, bool ALIGN_EPI = false, bool SP2 = false>
; __device__ __forceinline__ void gemm_phase(PG8_LAS unsigned char* lds, const Gemm g, const Sched& S, const Epi& E) {
;     ...
;             PG8_LDB(B0, 0, 0); PG8_LDB(B1, 0, 1); PG8_SCHED; PG8_LDA(At, 0, 0); PG8_STAGE(PG8_SA(1, 1), a1 + hstepA, voffA);
;             PG8_WAIT_V(8); PG8_WAIT_L(0); PG8_BAR; PG8_MMA(0, 0, At, B0); PG8_MMA(0, 1, At, B1); PG8_BAR; PG8_SCHED;
;             PG8_LDA(At, 0, 1); PG8_STAGE(PG8_SB(0, 0), b2, voffB); PG8_STAGE(PG8_SB(0, 1), b2 + hstepB, voffB); PG8_STAGE(PG8_SA(0, 0), a2, voffA);
.LBB0_278:
	s_setprio 1
	v_add_u32_e32 v142, s35, v145
	ds_read_b128 v[138:141], v142
	ds_read_b128 v[148:151], v142 offset:1024
	ds_read_b128 v[152:155], v142 offset:2048
	ds_read_b128 v[156:159], v142 offset:3072
	v_add_u32_e32 v142, s38, v145
	ds_read_b128 v[160:163], v142
	ds_read_b128 v[164:167], v142 offset:1024
	ds_read_b128 v[168:171], v142 offset:2048
	ds_read_b128 v[172:175], v142 offset:3072
	s_add_u32 s22, s20, 0x100
	s_addc_u32 s23, s21, 0
	s_cmp_eq_u32 s78, 40
	s_cselect_b32 s27, s9, s23
	s_cselect_b32 s26, s8, s22
	s_cselect_b32 s25, s19, s75
	s_cselect_b32 s24, s18, s74
	v_lshl_add_u64 v[142:143], s[20:21], 0, v[136:137]
	s_add_i32 m0, s41, 0xc000
	ds_read_b128 v[176:179], v147
	ds_read_b128 v[180:183], v147 offset:1024
	ds_read_b128 v[184:187], v147 offset:2048
	ds_read_b128 v[188:191], v147 offset:3072
	ds_read_b128 v[204:207], v147 offset:4096
	ds_read_b128 v[208:211], v147 offset:5120
	ds_read_b128 v[218:221], v147 offset:6144
	ds_read_b128 v[222:225], v147 offset:7168
	global_load_lds_dwordx4 v[142:143], off
	v_lshl_add_u64 v[142:143], s[20:21], 0, v[134:135]
	s_add_i32 m0, s41, 0xe000
	s_nop 0
	global_load_lds_dwordx4 v[142:143], off
	s_waitcnt vmcnt(8)
	s_waitcnt lgkmcnt(0)
	s_setprio 0
	s_barrier
	s_waitcnt lgkmcnt(0)
	v_mfma_f32_16x16x32_bf16 v[124:127], v[138:141], v[176:179], v[124:127]
	v_mfma_f32_16x16x32_bf16 v[120:123], v[152:155], v[176:179], v[120:123]
	v_mfma_f32_16x16x32_bf16 v[108:111], v[138:141], v[184:187], v[108:111]
	v_mfma_f32_16x16x32_bf16 v[104:107], v[152:155], v[184:187], v[104:107]
	v_mfma_f32_16x16x32_bf16 v[92:95], v[138:141], v[204:207], v[92:95]
	v_mfma_f32_16x16x32_bf16 v[88:91], v[152:155], v[204:207], v[88:91]
	v_mfma_f32_16x16x32_bf16 v[76:79], v[138:141], v[218:221], v[76:79]
	v_mfma_f32_16x16x32_bf16 v[72:75], v[152:155], v[218:221], v[72:75]
	v_mfma_f32_16x16x32_bf16 v[124:127], v[148:151], v[180:183], v[124:127]
	v_mfma_f32_16x16x32_bf16 v[120:123], v[156:159], v[180:183], v[120:123]
	v_mfma_f32_16x16x32_bf16 v[108:111], v[148:151], v[188:191], v[108:111]
	v_mfma_f32_16x16x32_bf16 v[104:107], v[156:159], v[188:191], v[104:107]
	v_mfma_f32_16x16x32_bf16 v[92:95], v[148:151], v[208:211], v[92:95]
	v_mfma_f32_16x16x32_bf16 v[88:91], v[156:159], v[208:211], v[88:91]
	v_mfma_f32_16x16x32_bf16 v[76:79], v[148:151], v[222:225], v[76:79]
	v_mfma_f32_16x16x32_bf16 v[72:75], v[156:159], v[222:225], v[72:75]
	v_mfma_f32_16x16x32_bf16 v[116:119], v[160:163], v[176:179], v[116:119]
	v_mfma_f32_16x16x32_bf16 v[112:115], v[168:171], v[176:179], v[112:115]
	v_mfma_f32_16x16x32_bf16 v[100:103], v[160:163], v[184:187], v[100:103]
	v_mfma_f32_16x16x32_bf16 v[96:99], v[168:171], v[184:187], v[96:99]
	v_mfma_f32_16x16x32_bf16 v[84:87], v[160:163], v[204:207], v[84:87]
	v_mfma_f32_16x16x32_bf16 v[80:83], v[168:171], v[204:207], v[80:83]
	v_mfma_f32_16x16x32_bf16 v[68:71], v[160:163], v[218:221], v[68:71]
	v_mfma_f32_16x16x32_bf16 v[64:67], v[168:171], v[218:221], v[64:67]
	v_mfma_f32_16x16x32_bf16 v[116:119], v[164:167], v[180:183], v[116:119]
	v_mfma_f32_16x16x32_bf16 v[112:115], v[172:175], v[180:183], v[112:115]
	v_mfma_f32_16x16x32_bf16 v[100:103], v[164:167], v[188:191], v[100:103]
	v_mfma_f32_16x16x32_bf16 v[96:99], v[172:175], v[188:191], v[96:99]
	v_mfma_f32_16x16x32_bf16 v[84:87], v[164:167], v[208:211], v[84:87]
	v_mfma_f32_16x16x32_bf16 v[80:83], v[172:175], v[208:211], v[80:83]
	v_mfma_f32_16x16x32_bf16 v[68:71], v[164:167], v[222:225], v[68:71]
	v_mfma_f32_16x16x32_bf16 v[64:67], v[172:175], v[222:225], v[64:67]
	s_barrier
	s_setprio 1
	s_mov_b32 m0, s36
	v_lshl_add_u64 v[142:143], s[24:25], 0, v[192:193]
	s_add_u32 s20, s24, 0xb0000
	ds_read_b128 v[176:179], v147 offset:16384
	ds_read_b128 v[180:183], v147 offset:17408
	ds_read_b128 v[184:187], v147 offset:18432
	ds_read_b128 v[188:191], v147 offset:19456
	ds_read_b128 v[204:207], v147 offset:20480
	ds_read_b128 v[208:211], v147 offset:21504
	ds_read_b128 v[218:221], v147 offset:22528
	ds_read_b128 v[222:225], v147 offset:23552
	global_load_lds_dwordx4 v[142:143], off
	v_lshl_add_u64 v[226:227], s[24:25], 0, v[132:133]
	s_mov_b32 m0, s37
	s_addc_u32 s21, s25, 0
	global_load_lds_dwordx4 v[226:227], off
	v_lshl_add_u64 v[228:229], s[20:21], 0, v[192:193]
	s_mov_b32 m0, s39
	v_lshl_add_u64 v[230:231], s[26:27], 0, v[130:131]
	global_load_lds_dwordx4 v[228:229], off
	v_lshl_add_u64 v[228:229], s[20:21], 0, v[132:133]
	s_mov_b32 m0, s40
	s_nop 0
	global_load_lds_dwordx4 v[228:229], off
	v_lshl_add_u64 v[228:229], s[26:27], 0, v[128:129]
	s_mov_b32 m0, s41
	s_nop 0
	global_load_lds_dwordx4 v[228:229], off
	s_mov_b32 m0, s42
	s_nop 0
	global_load_lds_dwordx4 v[230:231], off
	s_waitcnt vmcnt(8)
	s_waitcnt lgkmcnt(0)
	s_setprio 0
	s_barrier
; #define PG8_STAGE(bufoff, gbase, voff) do { _Pragma("unroll") for (int _i = 0; _i < 2; ++_i) \
;         __builtin_amdgcn_global_load_lds((const unsigned*)((const char*)(gbase) + (voff)[_i]), (PG8_LAS unsigned*)(lds + (bufoff) + ldsw + _i * 8192), 16, 0, 0); } while (0)
; #define PG8_LDA(dst, b, h) do { _Pragma("unroll") for (int m = 0; m < 4; ++m) _Pragma("unroll") for (int k = 0; k < 2; ++k) dst[m][k] = *(const PG8_LAS bf16x8*)(lds + PG8_SA(b, h) + aoff + m * 2048 + k * 1024); } while (0)
; #define PG8_LDB(dst, b, h) do { _Pragma("unroll") for (int n = 0; n < 2; ++n) _Pragma("unroll") for (int k = 0; k < 2; ++k) dst[n][k] = *(const PG8_LAS bf16x8*)(lds + PG8_SB(b, h) + boff + n * 2048 + k * 1024); } while (0)
; #define PG8_MMA(ai, bj, At, Bt) do { __builtin_amdgcn_s_setprio(1); _Pragma("unroll") for (int m = 0; m < 4; ++m) _Pragma("unroll") for (int n = 0; n < 2; ++n) _Pragma("unroll") for (int k = 0; k < 2; ++k) \
;         acc[ai][bj][m][n] = __builtin_amdgcn_mfma_f32_16x16x32_bf16(Bt[n][k], At[m][k], acc[ai][bj][m][n], 0, 0, 0); __builtin_amdgcn_s_setprio(0); } while (0)
; #define PG8_WAIT_V(n) asm volatile("s_waitcnt vmcnt(" #n ")" ::: "memory")
; #define PG8_WAIT_L(n) asm volatile("s_waitcnt lgkmcnt(" #n ")" ::: "memory")
; #define PG8_BAR __builtin_amdgcn_s_barrier()
; #define PG8_SCHED __builtin_amdgcn_sched_barrier(0)
; template <class Epi, class Sched, bool ALIGN_EPI = false, bool SP2 = false>
; __device__ __forceinline__ void gemm_phase(PG8_LAS unsigned char* lds, const Gemm g, const Sched& S, const Epi& E) {
;     ...
;             PG8_WAIT_V(8); PG8_WAIT_L(0); PG8_BAR; PG8_MMA(1, 0, At, B0); PG8_MMA(1, 1, At, B1); PG8_BAR; PG8_SCHED;
;             PG8_LDB(B0, 1, 0); PG8_LDB(B1, 1, 1); PG8_SCHED; PG8_LDA(At, 1, 0); PG8_STAGE(PG8_SA(0, 1), a2 + hstepA, voffA);
;             PG8_WAIT_V(8); PG8_WAIT_L(0); PG8_BAR; PG8_MMA(0, 0, At, B0); PG8_MMA(0, 1, At, B1); PG8_BAR; PG8_SCHED;
	s_waitcnt lgkmcnt(0)
	v_mfma_f32_16x16x32_bf16 v[60:63], v[138:141], v[176:179], v[60:63]
	v_mfma_f32_16x16x32_bf16 v[56:59], v[152:155], v[176:179], v[56:59]
	v_mfma_f32_16x16x32_bf16 v[44:47], v[138:141], v[184:187], v[44:47]
	v_mfma_f32_16x16x32_bf16 v[40:43], v[152:155], v[184:187], v[40:43]
	v_mfma_f32_16x16x32_bf16 v[28:31], v[138:141], v[204:207], v[28:31]
	v_mfma_f32_16x16x32_bf16 v[24:27], v[152:155], v[204:207], v[24:27]
	v_mfma_f32_16x16x32_bf16 v[12:15], v[138:141], v[218:221], v[12:15]
	v_mfma_f32_16x16x32_bf16 v[8:11], v[152:155], v[218:221], v[8:11]
	v_mfma_f32_16x16x32_bf16 v[60:63], v[148:151], v[180:183], v[60:63]
	v_mfma_f32_16x16x32_bf16 v[56:59], v[156:159], v[180:183], v[56:59]
	v_mfma_f32_16x16x32_bf16 v[44:47], v[148:151], v[188:191], v[44:47]
	v_mfma_f32_16x16x32_bf16 v[40:43], v[156:159], v[188:191], v[40:43]
	v_mfma_f32_16x16x32_bf16 v[28:31], v[148:151], v[208:211], v[28:31]
	v_mfma_f32_16x16x32_bf16 v[24:27], v[156:159], v[208:211], v[24:27]
	v_mfma_f32_16x16x32_bf16 v[12:15], v[148:151], v[222:225], v[12:15]
	v_mfma_f32_16x16x32_bf16 v[8:11], v[156:159], v[222:225], v[8:11]
	v_mfma_f32_16x16x32_bf16 v[52:55], v[160:163], v[176:179], v[52:55]
	v_mfma_f32_16x16x32_bf16 v[48:51], v[168:171], v[176:179], v[48:51]
	v_mfma_f32_16x16x32_bf16 v[36:39], v[160:163], v[184:187], v[36:39]
	v_mfma_f32_16x16x32_bf16 v[32:35], v[168:171], v[184:187], v[32:35]
	v_mfma_f32_16x16x32_bf16 v[20:23], v[160:163], v[204:207], v[20:23]
	v_mfma_f32_16x16x32_bf16 v[16:19], v[168:171], v[204:207], v[16:19]
	v_mfma_f32_16x16x32_bf16 v[4:7], v[160:163], v[218:221], v[4:7]
	v_mfma_f32_16x16x32_bf16 v[0:3], v[168:171], v[218:221], v[0:3]
	v_mfma_f32_16x16x32_bf16 v[52:55], v[164:167], v[180:183], v[52:55]
	v_mfma_f32_16x16x32_bf16 v[48:51], v[172:175], v[180:183], v[48:51]
	v_mfma_f32_16x16x32_bf16 v[36:39], v[164:167], v[188:191], v[36:39]
	v_mfma_f32_16x16x32_bf16 v[32:35], v[172:175], v[188:191], v[32:35]
	v_mfma_f32_16x16x32_bf16 v[20:23], v[164:167], v[208:211], v[20:23]
	v_mfma_f32_16x16x32_bf16 v[16:19], v[172:175], v[208:211], v[16:19]
	v_mfma_f32_16x16x32_bf16 v[4:7], v[164:167], v[222:225], v[4:7]
	v_mfma_f32_16x16x32_bf16 v[0:3], v[172:175], v[222:225], v[0:3]
	s_barrier
	s_setprio 1
	v_add_u32_e32 v156, s48, v145
	v_add_u32_e32 v172, s61, v145
	ds_read_b128 v[138:141], v156
	ds_read_b128 v[148:151], v156 offset:1024
	ds_read_b128 v[152:155], v156 offset:2048
	ds_read_b128 v[156:159], v156 offset:3072
	ds_read_b128 v[160:163], v172
	ds_read_b128 v[164:167], v172 offset:1024
	ds_read_b128 v[168:171], v172 offset:2048
	ds_read_b128 v[172:175], v172 offset:3072
	s_add_u32 s20, s26, 0xb0000
	s_addc_u32 s21, s27, 0
	s_mov_b32 m0, s43
	v_lshl_add_u64 v[232:233], s[20:21], 0, v[128:129]
	ds_read_b128 v[176:179], v147 offset:32768
	ds_read_b128 v[180:183], v147 offset:33792
	ds_read_b128 v[184:187], v147 offset:34816
	ds_read_b128 v[188:191], v147 offset:35840
	ds_read_b128 v[204:207], v147 offset:36864
	ds_read_b128 v[208:211], v147 offset:37888
	ds_read_b128 v[218:221], v147 offset:38912
	ds_read_b128 v[222:225], v147 offset:39936
	global_load_lds_dwordx4 v[232:233], off
	v_lshl_add_u64 v[232:233], s[20:21], 0, v[130:131]
	s_mov_b32 m0, s44
	s_nop 0
	global_load_lds_dwordx4 v[232:233], off
	s_waitcnt vmcnt(8)
	s_waitcnt lgkmcnt(0)
	s_setprio 0
	s_barrier
	s_waitcnt lgkmcnt(0)
	v_mfma_f32_16x16x32_bf16 v[124:127], v[138:141], v[176:179], v[124:127]
	v_mfma_f32_16x16x32_bf16 v[120:123], v[152:155], v[176:179], v[120:123]
	v_mfma_f32_16x16x32_bf16 v[108:111], v[138:141], v[184:187], v[108:111]
	v_mfma_f32_16x16x32_bf16 v[104:107], v[152:155], v[184:187], v[104:107]
	v_mfma_f32_16x16x32_bf16 v[92:95], v[138:141], v[204:207], v[92:95]
	v_mfma_f32_16x16x32_bf16 v[88:91], v[152:155], v[204:207], v[88:91]
	v_mfma_f32_16x16x32_bf16 v[76:79], v[138:141], v[218:221], v[76:79]
	v_mfma_f32_16x16x32_bf16 v[72:75], v[152:155], v[218:221], v[72:75]
	v_mfma_f32_16x16x32_bf16 v[124:127], v[148:151], v[180:183], v[124:127]
	v_mfma_f32_16x16x32_bf16 v[120:123], v[156:159], v[180:183], v[120:123]
	v_mfma_f32_16x16x32_bf16 v[108:111], v[148:151], v[188:191], v[108:111]
	v_mfma_f32_16x16x32_bf16 v[104:107], v[156:159], v[188:191], v[104:107]
	v_mfma_f32_16x16x32_bf16 v[92:95], v[148:151], v[208:211], v[92:95]
	v_mfma_f32_16x16x32_bf16 v[88:91], v[156:159], v[208:211], v[88:91]
	v_mfma_f32_16x16x32_bf16 v[76:79], v[148:151], v[222:225], v[76:79]
	v_mfma_f32_16x16x32_bf16 v[72:75], v[156:159], v[222:225], v[72:75]
	v_mfma_f32_16x16x32_bf16 v[116:119], v[160:163], v[176:179], v[116:119]
	v_mfma_f32_16x16x32_bf16 v[112:115], v[168:171], v[176:179], v[112:115]
	v_mfma_f32_16x16x32_bf16 v[100:103], v[160:163], v[184:187], v[100:103]
	v_mfma_f32_16x16x32_bf16 v[96:99], v[168:171], v[184:187], v[96:99]
	v_mfma_f32_16x16x32_bf16 v[84:87], v[160:163], v[204:207], v[84:87]
	v_mfma_f32_16x16x32_bf16 v[80:83], v[168:171], v[204:207], v[80:83]
	v_mfma_f32_16x16x32_bf16 v[68:71], v[160:163], v[218:221], v[68:71]
	v_mfma_f32_16x16x32_bf16 v[64:67], v[168:171], v[218:221], v[64:67]
	v_mfma_f32_16x16x32_bf16 v[116:119], v[164:167], v[180:183], v[116:119]
	v_mfma_f32_16x16x32_bf16 v[112:115], v[172:175], v[180:183], v[112:115]
	v_mfma_f32_16x16x32_bf16 v[100:103], v[164:167], v[188:191], v[100:103]
	v_mfma_f32_16x16x32_bf16 v[96:99], v[172:175], v[188:191], v[96:99]
	v_mfma_f32_16x16x32_bf16 v[84:87], v[164:167], v[208:211], v[84:87]
	v_mfma_f32_16x16x32_bf16 v[80:83], v[172:175], v[208:211], v[80:83]
	v_mfma_f32_16x16x32_bf16 v[68:71], v[164:167], v[222:225], v[68:71]
	v_mfma_f32_16x16x32_bf16 v[64:67], v[172:175], v[222:225], v[64:67]
	s_barrier
; #define PG8_STAGE(bufoff, gbase, voff) do { _Pragma("unroll") for (int _i = 0; _i < 2; ++_i) \
;         __builtin_amdgcn_global_load_lds((const unsigned*)((const char*)(gbase) + (voff)[_i]), (PG8_LAS unsigned*)(lds + (bufoff) + ldsw + _i * 8192), 16, 0, 0); } while (0)
; #define PG8_LDA(dst, b, h) do { _Pragma("unroll") for (int m = 0; m < 4; ++m) _Pragma("unroll") for (int k = 0; k < 2; ++k) dst[m][k] = *(const PG8_LAS bf16x8*)(lds + PG8_SA(b, h) + aoff + m * 2048 + k * 1024); } while (0)
; #define PG8_MMA(ai, bj, At, Bt) do { __builtin_amdgcn_s_setprio(1); _Pragma("unroll") for (int m = 0; m < 4; ++m) _Pragma("unroll") for (int n = 0; n < 2; ++n) _Pragma("unroll") for (int k = 0; k < 2; ++k) \
;         acc[ai][bj][m][n] = __builtin_amdgcn_mfma_f32_16x16x32_bf16(Bt[n][k], At[m][k], acc[ai][bj][m][n], 0, 0, 0); __builtin_amdgcn_s_setprio(0); } while (0)
; #define PG8_WAIT_V(n) asm volatile("s_waitcnt vmcnt(" #n ")" ::: "memory")
; #define PG8_WAIT_L(n) asm volatile("s_waitcnt lgkmcnt(" #n ")" ::: "memory")
; #define PG8_BAR __builtin_amdgcn_s_barrier()
; #define PG8_SCHED __builtin_amdgcn_sched_barrier(0)
; template <class Epi, class Sched, bool ALIGN_EPI = false, bool SP2 = false>
; __device__ __forceinline__ void gemm_phase(PG8_LAS unsigned char* lds, const Gemm g, const Sched& S, const Epi& E) {
;     ...
;             PG8_LDA(At, 1, 1); PG8_STAGE(PG8_SB(1, 0), b3, voffB); PG8_STAGE(PG8_SB(1, 1), b3 + hstepB, voffB); PG8_STAGE(PG8_SA(1, 0), a3, voffA);
;             PG8_WAIT_V(8); PG8_WAIT_L(0); PG8_BAR; PG8_MMA(1, 0, At, B0); PG8_MMA(1, 1, At, B1); PG8_BAR; PG8_SCHED;
;     __device__ __forceinline__ void operator()(const f32x4 (&acc)[2][2][4][2], const pg8::Unit& u, int wr, int wc, int fr, int fq) const {
;     ...
; #pragma unroll
;         for (int ai = 0; ai < 2; ++ai)
; #pragma unroll
;             for (int m = 0; m < 4; ++m) {
;                 const int row = row0 + ai * 128 + m * 16; float ss = 0.f;
; #pragma unroll
;                 for (int bj = 0; bj < 2; ++bj) {
;                     const size_t off = (size_t)row * DM + col0 + bj * 128;
;                     const v4u b = *(const v4u*)(xb + off);
	s_setprio 1
	s_mov_b32 m0, s49
	v_lshl_add_u64 v[142:143], v[142:143], 0, s[76:77]
	s_add_u32 s20, s24, 0xb0080
	ds_read_b128 v[176:179], v147 offset:49152
	ds_read_b128 v[180:183], v147 offset:50176
	ds_read_b128 v[184:187], v147 offset:51200
	ds_read_b128 v[188:191], v147 offset:52224
	ds_read_b128 v[204:207], v147 offset:53248
	ds_read_b128 v[208:211], v147 offset:54272
	ds_read_b128 v[218:221], v147 offset:55296
	ds_read_b128 v[222:225], v147 offset:56320
	global_load_lds_dwordx4 v[142:143], off
	v_lshl_add_u64 v[142:143], v[226:227], 0, s[76:77]
	s_mov_b32 m0, s50
	s_addc_u32 s21, s25, 0
	global_load_lds_dwordx4 v[142:143], off
	v_lshl_add_u64 v[142:143], s[20:21], 0, v[192:193]
	s_mov_b32 m0, s64
	s_nop 0
	global_load_lds_dwordx4 v[142:143], off
	v_lshl_add_u64 v[142:143], s[20:21], 0, v[132:133]
	s_mov_b32 m0, s65
	s_nop 0
	global_load_lds_dwordx4 v[142:143], off
	v_lshl_add_u64 v[142:143], v[228:229], 0, s[76:77]
	s_mov_b32 m0, s51
	s_nop 0
	global_load_lds_dwordx4 v[142:143], off
	v_lshl_add_u64 v[142:143], v[230:231], 0, s[76:77]
	s_mov_b32 m0, s60
	s_nop 0
	global_load_lds_dwordx4 v[142:143], off
	s_waitcnt vmcnt(8)
	s_waitcnt lgkmcnt(0)
	s_setprio 0
	s_barrier
	s_waitcnt lgkmcnt(0)
	v_mfma_f32_16x16x32_bf16 v[60:63], v[138:141], v[176:179], v[60:63]
	v_mfma_f32_16x16x32_bf16 v[56:59], v[152:155], v[176:179], v[56:59]
	v_mfma_f32_16x16x32_bf16 v[44:47], v[138:141], v[184:187], v[44:47]
	v_mfma_f32_16x16x32_bf16 v[40:43], v[152:155], v[184:187], v[40:43]
	v_mfma_f32_16x16x32_bf16 v[28:31], v[138:141], v[204:207], v[28:31]
	v_mfma_f32_16x16x32_bf16 v[24:27], v[152:155], v[204:207], v[24:27]
	v_mfma_f32_16x16x32_bf16 v[12:15], v[138:141], v[218:221], v[12:15]
	v_mfma_f32_16x16x32_bf16 v[8:11], v[152:155], v[218:221], v[8:11]
	v_mfma_f32_16x16x32_bf16 v[60:63], v[148:151], v[180:183], v[60:63]
	v_mfma_f32_16x16x32_bf16 v[56:59], v[156:159], v[180:183], v[56:59]
	v_mfma_f32_16x16x32_bf16 v[44:47], v[148:151], v[188:191], v[44:47]
	v_mfma_f32_16x16x32_bf16 v[40:43], v[156:159], v[188:191], v[40:43]
	v_mfma_f32_16x16x32_bf16 v[28:31], v[148:151], v[208:211], v[28:31]
	v_mfma_f32_16x16x32_bf16 v[24:27], v[156:159], v[208:211], v[24:27]
	v_mfma_f32_16x16x32_bf16 v[12:15], v[148:151], v[222:225], v[12:15]
	v_mfma_f32_16x16x32_bf16 v[8:11], v[156:159], v[222:225], v[8:11]
	v_mfma_f32_16x16x32_bf16 v[52:55], v[160:163], v[176:179], v[52:55]
	v_mfma_f32_16x16x32_bf16 v[48:51], v[168:171], v[176:179], v[48:51]
	v_mfma_f32_16x16x32_bf16 v[36:39], v[160:163], v[184:187], v[36:39]
	v_mfma_f32_16x16x32_bf16 v[32:35], v[168:171], v[184:187], v[32:35]
	v_mfma_f32_16x16x32_bf16 v[20:23], v[160:163], v[204:207], v[20:23]
	v_mfma_f32_16x16x32_bf16 v[16:19], v[168:171], v[204:207], v[16:19]
	v_mfma_f32_16x16x32_bf16 v[4:7], v[160:163], v[218:221], v[4:7]
	v_mfma_f32_16x16x32_bf16 v[0:3], v[168:171], v[218:221], v[0:3]
	v_mfma_f32_16x16x32_bf16 v[52:55], v[164:167], v[180:183], v[52:55]
	v_mfma_f32_16x16x32_bf16 v[48:51], v[172:175], v[180:183], v[48:51]
	v_mfma_f32_16x16x32_bf16 v[36:39], v[164:167], v[188:191], v[36:39]
	v_mfma_f32_16x16x32_bf16 v[32:35], v[172:175], v[188:191], v[32:35]
	v_mfma_f32_16x16x32_bf16 v[20:23], v[164:167], v[208:211], v[20:23]
	v_mfma_f32_16x16x32_bf16 v[16:19], v[172:175], v[208:211], v[16:19]
	v_mfma_f32_16x16x32_bf16 v[4:7], v[164:167], v[222:225], v[4:7]
	v_mfma_f32_16x16x32_bf16 v[0:3], v[172:175], v[222:225], v[0:3]
	s_barrier
	s_setprio 1
	s_add_i32 s78, s78, 2
	s_add_u32 s74, s74, 0x100
	s_addc_u32 s75, s75, 0
	s_cmp_gt_u32 s78, 41
	s_mov_b64 s[20:21], s[22:23]
	s_cbranch_scc0 .LBB0_278
	s_setprio 0
	v_lshl_add_u32 v159, s68, 8, v144
	v_lshl_or_b32 v158, s34, 8, v146
	v_lshlrev_b32_e32 v159, 11, v159
	v_lshl_add_u32 v159, v158, 1, v159
	v_add_u32_e32 v218, 0x8000, v159
	v_add_u32_e32 v219, 0x10000, v159
	v_add_u32_e32 v240, 0x18000, v159
	v_add_u32_e32 v241, 0x40000, v159
	v_add_u32_e32 v245, 0x48000, v159
	v_add_u32_e32 v246, 0x50000, v159
	v_add_u32_e32 v247, 0x58000, v159
	global_load_dwordx4 v[160:163], v159, s[12:13]
	global_load_dwordx4 v[164:167], v159, s[12:13] offset:256
	global_load_dwordx4 v[168:171], v218, s[12:13]
	global_load_dwordx4 v[172:175], v218, s[12:13] offset:256
	global_load_dwordx4 v[176:179], v219, s[12:13]
	global_load_dwordx4 v[180:183], v219, s[12:13] offset:256
	global_load_dwordx4 v[184:187], v240, s[12:13]
	global_load_dwordx4 v[188:191], v240, s[12:13] offset:256
	global_load_dwordx4 v[204:207], v241, s[12:13]
	global_load_dwordx4 v[208:211], v241, s[12:13] offset:256
	global_load_dwordx4 v[220:223], v245, s[12:13]
	global_load_dwordx4 v[224:227], v245, s[12:13] offset:256
	global_load_dwordx4 v[228:231], v246, s[12:13]
	global_load_dwordx4 v[232:235], v246, s[12:13] offset:256
	global_load_dwordx4 v[236:239], v247, s[12:13]
	global_load_dwordx4 v[248:251], v247, s[12:13] offset:256
	s_and_b64 vcc, exec, s[16:17]
	s_cbranch_vccz .LBB0_281
	s_barrier

; #define PG8_STAGE(bufoff, gbase, voff) do { _Pragma("unroll") for (int _i = 0; _i < 2; ++_i) \
;         __builtin_amdgcn_global_load_lds((const unsigned*)((const char*)(gbase) + (voff)[_i]), (PG8_LAS unsigned*)(lds + (bufoff) + ldsw + _i * 8192), 16, 0, 0); } while (0)
; #define PG8_LDA(dst, b, h) do { _Pragma("unroll") for (int m = 0; m < 4; ++m) _Pragma("unroll") for (int k = 0; k < 2; ++k) dst[m][k] = *(const PG8_LAS bf16x8*)(lds + PG8_SA(b, h) + aoff + m * 2048 + k * 1024); } while (0)
; #define PG8_LDB(dst, b, h) do { _Pragma("unroll") for (int n = 0; n < 2; ++n) _Pragma("unroll") for (int k = 0; k < 2; ++k) dst[n][k] = *(const PG8_LAS bf16x8*)(lds + PG8_SB(b, h) + boff + n * 2048 + k * 1024); } while (0)
; #define PG8_MMA(ai, bj, At, Bt) do { __builtin_amdgcn_s_setprio(1); _Pragma("unroll") for (int m = 0; m < 4; ++m) _Pragma("unroll") for (int n = 0; n < 2; ++n) _Pragma("unroll") for (int k = 0; k < 2; ++k) \
;         acc[ai][bj][m][n] = __builtin_amdgcn_mfma_f32_16x16x32_bf16(Bt[n][k], At[m][k], acc[ai][bj][m][n], 0, 0, 0); __builtin_amdgcn_s_setprio(0); } while (0)
; #define PG8_WAIT_V(n) asm volatile("s_waitcnt vmcnt(" #n ")" ::: "memory")
; #define PG8_WAIT_L(n) asm volatile("s_waitcnt lgkmcnt(" #n ")" ::: "memory")
; #define PG8_BAR __builtin_amdgcn_s_barrier()
; #define PG8_SCHED __builtin_amdgcn_sched_barrier(0)
; template <class Epi, class Sched, bool ALIGN_EPI = false, bool SP2 = false>
; __device__ __forceinline__ void gemm_phase(PG8_LAS unsigned char* lds, const Gemm g, const Sched& S, const Epi& E) {
;     ...
;             PG8_LDB(B0, 0, 0); PG8_LDB(B1, 0, 1); PG8_SCHED; PG8_LDA(At, 0, 0); PG8_STAGE(PG8_SA(1, 1), a1 + hstepA, voffA);
;             PG8_WAIT_V(8); PG8_WAIT_L(0); PG8_BAR; PG8_MMA(0, 0, At, B0); PG8_MMA(0, 1, At, B1); PG8_BAR; PG8_SCHED;
;             PG8_LDA(At, 0, 1); PG8_STAGE(PG8_SB(0, 0), b2, voffB); PG8_STAGE(PG8_SB(0, 1), b2 + hstepB, voffB); PG8_STAGE(PG8_SA(0, 0), a2, voffA);
;             PG8_WAIT_V(8); PG8_WAIT_L(0); PG8_BAR; PG8_MMA(1, 0, At, B0); PG8_MMA(1, 1, At, B1); PG8_BAR; PG8_SCHED;
.LBB0_380:
	s_setprio 1
	v_add_u32_e32 v140, s85, v173
	v_add_u32_e32 v170, s78, v173
	ds_read_b128 v[128:131], v140
	ds_read_b128 v[132:135], v140 offset:1024
	ds_read_b128 v[136:139], v140 offset:2048
	ds_read_b128 v[140:143], v140 offset:3072
	ds_read_b128 v[144:147], v170
	ds_read_b128 v[148:151], v170 offset:1024
	ds_read_b128 v[166:169], v170 offset:2048
	ds_read_b128 v[176:179], v170 offset:3072
	s_add_u32 s2, s12, 0xfffc0080
	s_addc_u32 s14, s13, -1
	s_cmp_eq_u32 s22, 12
	s_cselect_b32 s17, s9, s14
	s_cselect_b32 s16, s11, s2
	s_cselect_b32 s15, s18, s21
	s_cselect_b32 s14, s19, s20
	v_lshl_add_u64 v[170:171], s[12:13], 0, v[164:165]
	s_add_i32 m0, s61, 0xc000
	ds_read_b128 v[180:183], v175
	ds_read_b128 v[184:187], v175 offset:1024
	ds_read_b128 v[188:191], v175 offset:2048
	ds_read_b128 v[204:207], v175 offset:3072
	ds_read_b128 v[208:211], v175 offset:4096
	ds_read_b128 v[218:221], v175 offset:5120
	ds_read_b128 v[222:225], v175 offset:6144
	ds_read_b128 v[226:229], v175 offset:7168
	global_load_lds_dwordx4 v[170:171], off
	v_lshl_add_u64 v[170:171], s[12:13], 0, v[162:163]
	s_add_i32 m0, s61, 0xe000
	s_nop 0
	global_load_lds_dwordx4 v[170:171], off
	s_waitcnt vmcnt(8)
	s_waitcnt lgkmcnt(0)
	s_setprio 0
	s_barrier
	s_waitcnt lgkmcnt(0)
	v_mfma_f32_16x16x32_bf16 v[60:63], v[128:131], v[180:183], v[60:63]
	v_mfma_f32_16x16x32_bf16 v[56:59], v[136:139], v[180:183], v[56:59]
	v_mfma_f32_16x16x32_bf16 v[52:55], v[128:131], v[188:191], v[52:55]
	v_mfma_f32_16x16x32_bf16 v[48:51], v[136:139], v[188:191], v[48:51]
	v_mfma_f32_16x16x32_bf16 v[44:47], v[128:131], v[208:211], v[44:47]
	v_mfma_f32_16x16x32_bf16 v[40:43], v[136:139], v[208:211], v[40:43]
	v_mfma_f32_16x16x32_bf16 v[36:39], v[128:131], v[222:225], v[36:39]
	v_mfma_f32_16x16x32_bf16 v[32:35], v[136:139], v[222:225], v[32:35]
	v_mfma_f32_16x16x32_bf16 v[60:63], v[132:135], v[184:187], v[60:63]
	v_mfma_f32_16x16x32_bf16 v[56:59], v[140:143], v[184:187], v[56:59]
	v_mfma_f32_16x16x32_bf16 v[52:55], v[132:135], v[204:207], v[52:55]
	v_mfma_f32_16x16x32_bf16 v[48:51], v[140:143], v[204:207], v[48:51]
	v_mfma_f32_16x16x32_bf16 v[44:47], v[132:135], v[218:221], v[44:47]
	v_mfma_f32_16x16x32_bf16 v[40:43], v[140:143], v[218:221], v[40:43]
	v_mfma_f32_16x16x32_bf16 v[36:39], v[132:135], v[226:229], v[36:39]
	v_mfma_f32_16x16x32_bf16 v[32:35], v[140:143], v[226:229], v[32:35]
	v_mfma_f32_16x16x32_bf16 v[124:127], v[144:147], v[180:183], v[124:127]
	v_mfma_f32_16x16x32_bf16 v[120:123], v[166:169], v[180:183], v[120:123]
	v_mfma_f32_16x16x32_bf16 v[116:119], v[144:147], v[188:191], v[116:119]
	v_mfma_f32_16x16x32_bf16 v[112:115], v[166:169], v[188:191], v[112:115]
	v_mfma_f32_16x16x32_bf16 v[108:111], v[144:147], v[208:211], v[108:111]
	v_mfma_f32_16x16x32_bf16 v[104:107], v[166:169], v[208:211], v[104:107]
	v_mfma_f32_16x16x32_bf16 v[100:103], v[144:147], v[222:225], v[100:103]
	v_mfma_f32_16x16x32_bf16 v[96:99], v[166:169], v[222:225], v[96:99]
	v_mfma_f32_16x16x32_bf16 v[124:127], v[148:151], v[184:187], v[124:127]
	v_mfma_f32_16x16x32_bf16 v[120:123], v[176:179], v[184:187], v[120:123]
	v_mfma_f32_16x16x32_bf16 v[116:119], v[148:151], v[204:207], v[116:119]
	v_mfma_f32_16x16x32_bf16 v[112:115], v[176:179], v[204:207], v[112:115]
	v_mfma_f32_16x16x32_bf16 v[108:111], v[148:151], v[218:221], v[108:111]
	v_mfma_f32_16x16x32_bf16 v[104:107], v[176:179], v[218:221], v[104:107]
	v_mfma_f32_16x16x32_bf16 v[100:103], v[148:151], v[226:229], v[100:103]
	v_mfma_f32_16x16x32_bf16 v[96:99], v[176:179], v[226:229], v[96:99]
	s_barrier
	s_setprio 1
	s_mov_b32 m0, s70
	v_lshl_add_u64 v[170:171], s[14:15], 0, v[154:155]
	s_add_u32 s24, s14, 0x40000
	ds_read_b128 v[180:183], v175 offset:16384
	ds_read_b128 v[184:187], v175 offset:17408
	ds_read_b128 v[188:191], v175 offset:18432
	ds_read_b128 v[204:207], v175 offset:19456
	ds_read_b128 v[208:211], v175 offset:20480
	ds_read_b128 v[218:221], v175 offset:21504
	ds_read_b128 v[222:225], v175 offset:22528
	ds_read_b128 v[226:229], v175 offset:23552
	global_load_lds_dwordx4 v[170:171], off
	v_lshl_add_u64 v[230:231], s[14:15], 0, v[158:159]
	s_mov_b32 m0, s71
	s_addc_u32 s25, s15, 0
	global_load_lds_dwordx4 v[230:231], off
	v_lshl_add_u64 v[232:233], s[24:25], 0, v[154:155]
	s_mov_b32 m0, s79
	v_lshl_add_u64 v[234:235], s[16:17], 0, v[156:157]
	global_load_lds_dwordx4 v[232:233], off
	v_lshl_add_u64 v[232:233], s[24:25], 0, v[158:159]
	s_mov_b32 m0, s60
	s_nop 0
	global_load_lds_dwordx4 v[232:233], off
	v_lshl_add_u64 v[232:233], s[16:17], 0, v[152:153]
	s_mov_b32 m0, s61
	s_nop 0
	global_load_lds_dwordx4 v[232:233], off
	s_mov_b32 m0, s75
	s_nop 0
	global_load_lds_dwordx4 v[234:235], off
	s_waitcnt vmcnt(8)
	s_waitcnt lgkmcnt(0)
	s_setprio 0
	s_barrier
; #define PG8_STAGE(bufoff, gbase, voff) do { _Pragma("unroll") for (int _i = 0; _i < 2; ++_i) \
;         __builtin_amdgcn_global_load_lds((const unsigned*)((const char*)(gbase) + (voff)[_i]), (PG8_LAS unsigned*)(lds + (bufoff) + ldsw + _i * 8192), 16, 0, 0); } while (0)
; #define PG8_LDA(dst, b, h) do { _Pragma("unroll") for (int m = 0; m < 4; ++m) _Pragma("unroll") for (int k = 0; k < 2; ++k) dst[m][k] = *(const PG8_LAS bf16x8*)(lds + PG8_SA(b, h) + aoff + m * 2048 + k * 1024); } while (0)
; #define PG8_LDB(dst, b, h) do { _Pragma("unroll") for (int n = 0; n < 2; ++n) _Pragma("unroll") for (int k = 0; k < 2; ++k) dst[n][k] = *(const PG8_LAS bf16x8*)(lds + PG8_SB(b, h) + boff + n * 2048 + k * 1024); } while (0)
; #define PG8_MMA(ai, bj, At, Bt) do { __builtin_amdgcn_s_setprio(1); _Pragma("unroll") for (int m = 0; m < 4; ++m) _Pragma("unroll") for (int n = 0; n < 2; ++n) _Pragma("unroll") for (int k = 0; k < 2; ++k) \
;         acc[ai][bj][m][n] = __builtin_amdgcn_mfma_f32_16x16x32_bf16(Bt[n][k], At[m][k], acc[ai][bj][m][n], 0, 0, 0); __builtin_amdgcn_s_setprio(0); } while (0)
; #define PG8_WAIT_V(n) asm volatile("s_waitcnt vmcnt(" #n ")" ::: "memory")
; #define PG8_WAIT_L(n) asm volatile("s_waitcnt lgkmcnt(" #n ")" ::: "memory")
; #define PG8_BAR __builtin_amdgcn_s_barrier()
; #define PG8_SCHED __builtin_amdgcn_sched_barrier(0)
; template <class Epi, class Sched, bool ALIGN_EPI = false, bool SP2 = false>
; __device__ __forceinline__ void gemm_phase(PG8_LAS unsigned char* lds, const Gemm g, const Sched& S, const Epi& E) {
;     ...
;             PG8_WAIT_V(8); PG8_WAIT_L(0); PG8_BAR; PG8_MMA(1, 0, At, B0); PG8_MMA(1, 1, At, B1); PG8_BAR; PG8_SCHED;
;             PG8_LDB(B0, 1, 0); PG8_LDB(B1, 1, 1); PG8_SCHED; PG8_LDA(At, 1, 0); PG8_STAGE(PG8_SA(0, 1), a2 + hstepA, voffA);
;             PG8_WAIT_V(8); PG8_WAIT_L(0); PG8_BAR; PG8_MMA(0, 0, At, B0); PG8_MMA(0, 1, At, B1); PG8_BAR; PG8_SCHED;
	s_waitcnt lgkmcnt(0)
	v_mfma_f32_16x16x32_bf16 v[28:31], v[128:131], v[180:183], v[28:31]
	v_mfma_f32_16x16x32_bf16 v[24:27], v[136:139], v[180:183], v[24:27]
	v_mfma_f32_16x16x32_bf16 v[20:23], v[128:131], v[188:191], v[20:23]
	v_mfma_f32_16x16x32_bf16 v[16:19], v[136:139], v[188:191], v[16:19]
	v_mfma_f32_16x16x32_bf16 v[12:15], v[128:131], v[208:211], v[12:15]
	v_mfma_f32_16x16x32_bf16 v[8:11], v[136:139], v[208:211], v[8:11]
	v_mfma_f32_16x16x32_bf16 v[4:7], v[128:131], v[222:225], v[4:7]
	v_mfma_f32_16x16x32_bf16 v[0:3], v[136:139], v[222:225], v[0:3]
	v_mfma_f32_16x16x32_bf16 v[28:31], v[132:135], v[184:187], v[28:31]
	v_mfma_f32_16x16x32_bf16 v[24:27], v[140:143], v[184:187], v[24:27]
	v_mfma_f32_16x16x32_bf16 v[20:23], v[132:135], v[204:207], v[20:23]
	v_mfma_f32_16x16x32_bf16 v[16:19], v[140:143], v[204:207], v[16:19]
	v_mfma_f32_16x16x32_bf16 v[12:15], v[132:135], v[218:221], v[12:15]
	v_mfma_f32_16x16x32_bf16 v[8:11], v[140:143], v[218:221], v[8:11]
	v_mfma_f32_16x16x32_bf16 v[4:7], v[132:135], v[226:229], v[4:7]
	v_mfma_f32_16x16x32_bf16 v[0:3], v[140:143], v[226:229], v[0:3]
	v_mfma_f32_16x16x32_bf16 v[92:95], v[144:147], v[180:183], v[92:95]
	v_mfma_f32_16x16x32_bf16 v[88:91], v[166:169], v[180:183], v[88:91]
	v_mfma_f32_16x16x32_bf16 v[84:87], v[144:147], v[188:191], v[84:87]
	v_mfma_f32_16x16x32_bf16 v[80:83], v[166:169], v[188:191], v[80:83]
	v_mfma_f32_16x16x32_bf16 v[76:79], v[144:147], v[208:211], v[76:79]
	v_mfma_f32_16x16x32_bf16 v[72:75], v[166:169], v[208:211], v[72:75]
	v_mfma_f32_16x16x32_bf16 v[68:71], v[144:147], v[222:225], v[68:71]
	v_mfma_f32_16x16x32_bf16 v[64:67], v[166:169], v[222:225], v[64:67]
	v_mfma_f32_16x16x32_bf16 v[92:95], v[148:151], v[184:187], v[92:95]
	v_mfma_f32_16x16x32_bf16 v[88:91], v[176:179], v[184:187], v[88:91]
	v_mfma_f32_16x16x32_bf16 v[84:87], v[148:151], v[204:207], v[84:87]
	v_mfma_f32_16x16x32_bf16 v[80:83], v[176:179], v[204:207], v[80:83]
	v_mfma_f32_16x16x32_bf16 v[76:79], v[148:151], v[218:221], v[76:79]
	v_mfma_f32_16x16x32_bf16 v[72:75], v[176:179], v[218:221], v[72:75]
	v_mfma_f32_16x16x32_bf16 v[68:71], v[148:151], v[226:229], v[68:71]
	v_mfma_f32_16x16x32_bf16 v[64:67], v[176:179], v[226:229], v[64:67]
	s_barrier
	s_setprio 1
	v_add_u32_e32 v140, s68, v173
	v_add_u32_e32 v176, s1, v173
	ds_read_b128 v[128:131], v140
	ds_read_b128 v[132:135], v140 offset:1024
	ds_read_b128 v[136:139], v140 offset:2048
	ds_read_b128 v[140:143], v140 offset:3072
	ds_read_b128 v[144:147], v176
	ds_read_b128 v[148:151], v176 offset:1024
	ds_read_b128 v[166:169], v176 offset:2048
	ds_read_b128 v[176:179], v176 offset:3072
	s_add_u32 s16, s16, 0x40000
	s_addc_u32 s17, s17, 0
	s_mov_b32 m0, s4
	v_lshl_add_u64 v[236:237], s[16:17], 0, v[152:153]
	ds_read_b128 v[180:183], v175 offset:32768
	ds_read_b128 v[184:187], v175 offset:33792
	ds_read_b128 v[188:191], v175 offset:34816
	ds_read_b128 v[204:207], v175 offset:35840
	ds_read_b128 v[208:211], v175 offset:36864
	ds_read_b128 v[218:221], v175 offset:37888
	ds_read_b128 v[222:225], v175 offset:38912
	ds_read_b128 v[226:229], v175 offset:39936
	global_load_lds_dwordx4 v[236:237], off
	v_lshl_add_u64 v[236:237], s[16:17], 0, v[156:157]
	s_mov_b32 m0, s5
	s_nop 0
	global_load_lds_dwordx4 v[236:237], off
	s_waitcnt vmcnt(8)
	s_waitcnt lgkmcnt(0)
	s_setprio 0
	s_barrier
	s_waitcnt lgkmcnt(0)
	v_mfma_f32_16x16x32_bf16 v[60:63], v[128:131], v[180:183], v[60:63]
	v_mfma_f32_16x16x32_bf16 v[56:59], v[136:139], v[180:183], v[56:59]
	v_mfma_f32_16x16x32_bf16 v[52:55], v[128:131], v[188:191], v[52:55]
	v_mfma_f32_16x16x32_bf16 v[48:51], v[136:139], v[188:191], v[48:51]
	v_mfma_f32_16x16x32_bf16 v[44:47], v[128:131], v[208:211], v[44:47]
	v_mfma_f32_16x16x32_bf16 v[40:43], v[136:139], v[208:211], v[40:43]
	v_mfma_f32_16x16x32_bf16 v[36:39], v[128:131], v[222:225], v[36:39]
	v_mfma_f32_16x16x32_bf16 v[32:35], v[136:139], v[222:225], v[32:35]
	v_mfma_f32_16x16x32_bf16 v[60:63], v[132:135], v[184:187], v[60:63]
	v_mfma_f32_16x16x32_bf16 v[56:59], v[140:143], v[184:187], v[56:59]
	v_mfma_f32_16x16x32_bf16 v[52:55], v[132:135], v[204:207], v[52:55]
	v_mfma_f32_16x16x32_bf16 v[48:51], v[140:143], v[204:207], v[48:51]
	v_mfma_f32_16x16x32_bf16 v[44:47], v[132:135], v[218:221], v[44:47]
	v_mfma_f32_16x16x32_bf16 v[40:43], v[140:143], v[218:221], v[40:43]
	v_mfma_f32_16x16x32_bf16 v[36:39], v[132:135], v[226:229], v[36:39]
	v_mfma_f32_16x16x32_bf16 v[32:35], v[140:143], v[226:229], v[32:35]
	v_mfma_f32_16x16x32_bf16 v[124:127], v[144:147], v[180:183], v[124:127]
	v_mfma_f32_16x16x32_bf16 v[120:123], v[166:169], v[180:183], v[120:123]
	v_mfma_f32_16x16x32_bf16 v[116:119], v[144:147], v[188:191], v[116:119]
	v_mfma_f32_16x16x32_bf16 v[112:115], v[166:169], v[188:191], v[112:115]
	v_mfma_f32_16x16x32_bf16 v[108:111], v[144:147], v[208:211], v[108:111]
	v_mfma_f32_16x16x32_bf16 v[104:107], v[166:169], v[208:211], v[104:107]
	v_mfma_f32_16x16x32_bf16 v[100:103], v[144:147], v[222:225], v[100:103]
	v_mfma_f32_16x16x32_bf16 v[96:99], v[166:169], v[222:225], v[96:99]
	v_mfma_f32_16x16x32_bf16 v[124:127], v[148:151], v[184:187], v[124:127]
	v_mfma_f32_16x16x32_bf16 v[120:123], v[176:179], v[184:187], v[120:123]
	v_mfma_f32_16x16x32_bf16 v[116:119], v[148:151], v[204:207], v[116:119]
	v_mfma_f32_16x16x32_bf16 v[112:115], v[176:179], v[204:207], v[112:115]
	v_mfma_f32_16x16x32_bf16 v[108:111], v[148:151], v[218:221], v[108:111]
	v_mfma_f32_16x16x32_bf16 v[104:107], v[176:179], v[218:221], v[104:107]
	v_mfma_f32_16x16x32_bf16 v[100:103], v[148:151], v[226:229], v[100:103]
	v_mfma_f32_16x16x32_bf16 v[96:99], v[176:179], v[226:229], v[96:99]
	s_barrier
; #define PG8_STAGE(bufoff, gbase, voff) do { _Pragma("unroll") for (int _i = 0; _i < 2; ++_i) \
;         __builtin_amdgcn_global_load_lds((const unsigned*)((const char*)(gbase) + (voff)[_i]), (PG8_LAS unsigned*)(lds + (bufoff) + ldsw + _i * 8192), 16, 0, 0); } while (0)
; #define PG8_LDA(dst, b, h) do { _Pragma("unroll") for (int m = 0; m < 4; ++m) _Pragma("unroll") for (int k = 0; k < 2; ++k) dst[m][k] = *(const PG8_LAS bf16x8*)(lds + PG8_SA(b, h) + aoff + m * 2048 + k * 1024); } while (0)
; #define PG8_MMA(ai, bj, At, Bt) do { __builtin_amdgcn_s_setprio(1); _Pragma("unroll") for (int m = 0; m < 4; ++m) _Pragma("unroll") for (int n = 0; n < 2; ++n) _Pragma("unroll") for (int k = 0; k < 2; ++k) \
;         acc[ai][bj][m][n] = __builtin_amdgcn_mfma_f32_16x16x32_bf16(Bt[n][k], At[m][k], acc[ai][bj][m][n], 0, 0, 0); __builtin_amdgcn_s_setprio(0); } while (0)
; #define PG8_WAIT_V(n) asm volatile("s_waitcnt vmcnt(" #n ")" ::: "memory")
; #define PG8_WAIT_L(n) asm volatile("s_waitcnt lgkmcnt(" #n ")" ::: "memory")
; #define PG8_BAR __builtin_amdgcn_s_barrier()
; #define PG8_SCHED __builtin_amdgcn_sched_barrier(0)
; template <class Epi, class Sched, bool ALIGN_EPI = false, bool SP2 = false>
; __device__ __forceinline__ void gemm_phase(PG8_LAS unsigned char* lds, const Gemm g, const Sched& S, const Epi& E) {
;     ...
;             PG8_LDA(At, 1, 1); PG8_STAGE(PG8_SB(1, 0), b3, voffB); PG8_STAGE(PG8_SB(1, 1), b3 + hstepB, voffB); PG8_STAGE(PG8_SA(1, 0), a3, voffA);
;             PG8_WAIT_V(8); PG8_WAIT_L(0); PG8_BAR; PG8_MMA(1, 0, At, B0); PG8_MMA(1, 1, At, B1); PG8_BAR; PG8_SCHED;
; __device__ __forceinline__ float row_rstd(const float* ssq, int row, int fq) {
;     const f32x4 v = *(const f32x4*)(ssq + (size_t)row * 16 + fq * 4);
;     float s = (v[0] + v[1]) + (v[2] + v[3]);
	s_setprio 1
	s_mov_b32 m0, s84
	v_lshl_add_u64 v[170:171], v[170:171], 0, s[76:77]
	s_add_u32 s14, s14, 0x40080
	ds_read_b128 v[180:183], v175 offset:49152
	ds_read_b128 v[184:187], v175 offset:50176
	ds_read_b128 v[188:191], v175 offset:51200
	ds_read_b128 v[204:207], v175 offset:52224
	ds_read_b128 v[208:211], v175 offset:53248
	ds_read_b128 v[218:221], v175 offset:54272
	ds_read_b128 v[222:225], v175 offset:55296
	ds_read_b128 v[226:229], v175 offset:56320
	global_load_lds_dwordx4 v[170:171], off
	v_lshl_add_u64 v[170:171], v[230:231], 0, s[76:77]
	s_mov_b32 m0, s64
	s_addc_u32 s15, s15, 0
	global_load_lds_dwordx4 v[170:171], off
	v_lshl_add_u64 v[170:171], s[14:15], 0, v[154:155]
	s_mov_b32 m0, s48
	s_nop 0
	global_load_lds_dwordx4 v[170:171], off
	v_lshl_add_u64 v[170:171], s[14:15], 0, v[158:159]
	s_mov_b32 m0, s49
	s_nop 0
	global_load_lds_dwordx4 v[170:171], off
	v_lshl_add_u64 v[170:171], v[232:233], 0, s[76:77]
	s_mov_b32 m0, s65
	s_nop 0
	global_load_lds_dwordx4 v[170:171], off
	v_lshl_add_u64 v[170:171], v[234:235], 0, s[76:77]
	s_mov_b32 m0, s0
	s_nop 0
	global_load_lds_dwordx4 v[170:171], off
	s_waitcnt vmcnt(8)
	s_waitcnt lgkmcnt(0)
	s_setprio 0
	s_barrier
	s_waitcnt lgkmcnt(0)
	v_mfma_f32_16x16x32_bf16 v[28:31], v[128:131], v[180:183], v[28:31]
	v_mfma_f32_16x16x32_bf16 v[24:27], v[136:139], v[180:183], v[24:27]
	v_mfma_f32_16x16x32_bf16 v[20:23], v[128:131], v[188:191], v[20:23]
	v_mfma_f32_16x16x32_bf16 v[16:19], v[136:139], v[188:191], v[16:19]
	v_mfma_f32_16x16x32_bf16 v[12:15], v[128:131], v[208:211], v[12:15]
	v_mfma_f32_16x16x32_bf16 v[8:11], v[136:139], v[208:211], v[8:11]
	v_mfma_f32_16x16x32_bf16 v[4:7], v[128:131], v[222:225], v[4:7]
	v_mfma_f32_16x16x32_bf16 v[0:3], v[136:139], v[222:225], v[0:3]
	v_mfma_f32_16x16x32_bf16 v[28:31], v[132:135], v[184:187], v[28:31]
	v_mfma_f32_16x16x32_bf16 v[24:27], v[140:143], v[184:187], v[24:27]
	v_mfma_f32_16x16x32_bf16 v[20:23], v[132:135], v[204:207], v[20:23]
	v_mfma_f32_16x16x32_bf16 v[16:19], v[140:143], v[204:207], v[16:19]
	v_mfma_f32_16x16x32_bf16 v[12:15], v[132:135], v[218:221], v[12:15]
	v_mfma_f32_16x16x32_bf16 v[8:11], v[140:143], v[218:221], v[8:11]
	v_mfma_f32_16x16x32_bf16 v[4:7], v[132:135], v[226:229], v[4:7]
	v_mfma_f32_16x16x32_bf16 v[0:3], v[140:143], v[226:229], v[0:3]
	v_mfma_f32_16x16x32_bf16 v[92:95], v[144:147], v[180:183], v[92:95]
	v_mfma_f32_16x16x32_bf16 v[88:91], v[166:169], v[180:183], v[88:91]
	v_mfma_f32_16x16x32_bf16 v[84:87], v[144:147], v[188:191], v[84:87]
	v_mfma_f32_16x16x32_bf16 v[80:83], v[166:169], v[188:191], v[80:83]
	v_mfma_f32_16x16x32_bf16 v[76:79], v[144:147], v[208:211], v[76:79]
	v_mfma_f32_16x16x32_bf16 v[72:75], v[166:169], v[208:211], v[72:75]
	v_mfma_f32_16x16x32_bf16 v[68:71], v[144:147], v[222:225], v[68:71]
	v_mfma_f32_16x16x32_bf16 v[64:67], v[166:169], v[222:225], v[64:67]
	v_mfma_f32_16x16x32_bf16 v[92:95], v[148:151], v[184:187], v[92:95]
	v_mfma_f32_16x16x32_bf16 v[88:91], v[176:179], v[184:187], v[88:91]
	v_mfma_f32_16x16x32_bf16 v[84:87], v[148:151], v[204:207], v[84:87]
	v_mfma_f32_16x16x32_bf16 v[80:83], v[176:179], v[204:207], v[80:83]
	v_mfma_f32_16x16x32_bf16 v[76:79], v[148:151], v[218:221], v[76:79]
	v_mfma_f32_16x16x32_bf16 v[72:75], v[176:179], v[218:221], v[72:75]
	v_mfma_f32_16x16x32_bf16 v[68:71], v[148:151], v[226:229], v[68:71]
	v_mfma_f32_16x16x32_bf16 v[64:67], v[176:179], v[226:229], v[64:67]
	s_barrier
	s_setprio 1
	s_add_i32 s22, s22, 2
	s_add_u32 s20, s20, 0x100
	s_addc_u32 s21, s21, 0
	s_add_u32 s12, s12, 0x100
	s_addc_u32 s13, s13, 0
	s_cmp_gt_u32 s22, 13
	s_cbranch_scc0 .LBB0_380
	s_setprio 0
	s_cmp_eq_u32 s10, 14
	s_cbranch_scc1 .Lewh_skip
	v_lshl_add_u32 v214, s8, 8, v172
	v_mov_b32_e32 v128, v214
	v_ashrrev_i32_e32 v129, 31, v128
	v_lshlrev_b64 v[128:129], 6, v[128:129]
	v_lshl_add_u64 v[128:129], v[160:161], 0, v[128:129]
	global_load_dwordx4 v[128:131], v[128:129], off
	v_add_u32_e32 v132, 16, v214
	v_ashrrev_i32_e32 v133, 31, v132
	v_lshlrev_b64 v[132:133], 6, v[132:133]
	v_lshl_add_u64 v[132:133], v[160:161], 0, v[132:133]
	global_load_dwordx4 v[132:135], v[132:133], off
	v_add_u32_e32 v136, 32, v214
	v_ashrrev_i32_e32 v137, 31, v136
	v_lshlrev_b64 v[136:137], 6, v[136:137]
	v_lshl_add_u64 v[136:137], v[160:161], 0, v[136:137]
	global_load_dwordx4 v[136:139], v[136:137], off
	v_add_u32_e32 v140, 48, v214
	v_ashrrev_i32_e32 v141, 31, v140
	v_lshlrev_b64 v[140:141], 6, v[140:141]
	v_lshl_add_u64 v[140:141], v[160:161], 0, v[140:141]
	global_load_dwordx4 v[140:143], v[140:141], off
	v_add_u32_e32 v144, 0x80, v214
	v_ashrrev_i32_e32 v145, 31, v144
	v_lshlrev_b64 v[144:145], 6, v[144:145]
	v_lshl_add_u64 v[144:145], v[160:161], 0, v[144:145]
	global_load_dwordx4 v[144:147], v[144:145], off
	v_add_u32_e32 v148, 0x90, v214
	v_ashrrev_i32_e32 v149, 31, v148
	v_lshlrev_b64 v[148:149], 6, v[148:149]
	v_lshl_add_u64 v[148:149], v[160:161], 0, v[148:149]
	global_load_dwordx4 v[148:151], v[148:149], off
	v_add_u32_e32 v236, 0xa0, v214
	v_ashrrev_i32_e32 v237, 31, v236
	v_lshlrev_b64 v[236:237], 6, v[236:237]
	v_lshl_add_u64 v[236:237], v[160:161], 0, v[236:237]
	global_load_dwordx4 v[236:239], v[236:237], off
	v_add_u32_e32 v246, 0xb0, v214
	v_ashrrev_i32_e32 v247, 31, v246
	v_lshlrev_b64 v[246:247], 6, v[246:247]
	v_lshl_add_u64 v[246:247], v[160:161], 0, v[246:247]
	global_load_dwordx4 v[246:249], v[246:247], off

; #define PG8_STAGE(bufoff, gbase, voff) do { _Pragma("unroll") for (int _i = 0; _i < 2; ++_i) \
;         __builtin_amdgcn_global_load_lds((const unsigned*)((const char*)(gbase) + (voff)[_i]), (PG8_LAS unsigned*)(lds + (bufoff) + ldsw + _i * 8192), 16, 0, 0); } while (0)
; #define PG8_LDA(dst, b, h) do { _Pragma("unroll") for (int m = 0; m < 4; ++m) _Pragma("unroll") for (int k = 0; k < 2; ++k) dst[m][k] = *(const PG8_LAS bf16x8*)(lds + PG8_SA(b, h) + aoff + m * 2048 + k * 1024); } while (0)
; #define PG8_LDB(dst, b, h) do { _Pragma("unroll") for (int n = 0; n < 2; ++n) _Pragma("unroll") for (int k = 0; k < 2; ++k) dst[n][k] = *(const PG8_LAS bf16x8*)(lds + PG8_SB(b, h) + boff + n * 2048 + k * 1024); } while (0)
; #define PG8_MMA(ai, bj, At, Bt) do { __builtin_amdgcn_s_setprio(1); _Pragma("unroll") for (int m = 0; m < 4; ++m) _Pragma("unroll") for (int n = 0; n < 2; ++n) _Pragma("unroll") for (int k = 0; k < 2; ++k) \
;         acc[ai][bj][m][n] = __builtin_amdgcn_mfma_f32_16x16x32_bf16(Bt[n][k], At[m][k], acc[ai][bj][m][n], 0, 0, 0); __builtin_amdgcn_s_setprio(0); } while (0)
; #define PG8_WAIT_V(n) asm volatile("s_waitcnt vmcnt(" #n ")" ::: "memory")
; #define PG8_WAIT_L(n) asm volatile("s_waitcnt lgkmcnt(" #n ")" ::: "memory")
; #define PG8_BAR __builtin_amdgcn_s_barrier()
; #define PG8_SCHED __builtin_amdgcn_sched_barrier(0)
; template <class Epi, class Sched, bool ALIGN_EPI = false, bool SP2 = false>
; __device__ __forceinline__ void gemm_phase(PG8_LAS unsigned char* lds, const Gemm g, const Sched& S, const Epi& E) {
;     ...
;             PG8_LDB(B0, 0, 0); PG8_LDB(B1, 0, 1); PG8_SCHED; PG8_LDA(At, 0, 0); PG8_STAGE(PG8_SA(1, 1), a1 + hstepA, voffA);
;             PG8_WAIT_V(8); PG8_WAIT_L(0); PG8_BAR; PG8_MMA(0, 0, At, B0); PG8_MMA(0, 1, At, B1); PG8_BAR; PG8_SCHED;
;             PG8_LDA(At, 0, 1); PG8_STAGE(PG8_SB(0, 0), b2, voffB); PG8_STAGE(PG8_SB(0, 1), b2 + hstepB, voffB); PG8_STAGE(PG8_SA(0, 0), a2, voffA);
;             PG8_WAIT_V(8); PG8_WAIT_L(0); PG8_BAR; PG8_MMA(1, 0, At, B0); PG8_MMA(1, 1, At, B1); PG8_BAR; PG8_SCHED;
.LBB0_885:
	s_setprio 1
	v_add_u32_e32 v142, s9, v145
	ds_read_b128 v[138:141], v142
	ds_read_b128 v[148:151], v142 offset:1024
	ds_read_b128 v[152:155], v142 offset:2048
	ds_read_b128 v[156:159], v142 offset:3072
	v_add_u32_e32 v142, s42, v145
	ds_read_b128 v[160:163], v142
	ds_read_b128 v[164:167], v142 offset:1024
	ds_read_b128 v[168:171], v142 offset:2048
	ds_read_b128 v[172:175], v142 offset:3072
	s_add_u32 s2, s28, 0xfffc0080
	s_addc_u32 s30, s29, -1
	s_cmp_eq_u32 s82, 12
	s_cselect_b32 s35, s21, s30
	s_cselect_b32 s34, s27, s2
	s_cselect_b32 s31, s19, s79
	s_cselect_b32 s30, s68, s78
	v_lshl_add_u64 v[142:143], s[28:29], 0, v[136:137]
	s_add_i32 m0, s45, 0xc000
	ds_read_b128 v[176:179], v147
	ds_read_b128 v[180:183], v147 offset:1024
	ds_read_b128 v[184:187], v147 offset:2048
	ds_read_b128 v[188:191], v147 offset:3072
	ds_read_b128 v[204:207], v147 offset:4096
	ds_read_b128 v[208:211], v147 offset:5120
	ds_read_b128 v[218:221], v147 offset:6144
	ds_read_b128 v[222:225], v147 offset:7168
	global_load_lds_dwordx4 v[142:143], off
	v_lshl_add_u64 v[142:143], s[28:29], 0, v[134:135]
	s_add_i32 m0, s45, 0xe000
	s_nop 0
	global_load_lds_dwordx4 v[142:143], off
	s_waitcnt vmcnt(8)
	s_waitcnt lgkmcnt(0)
	s_setprio 0
	s_barrier
	s_waitcnt lgkmcnt(0)
	v_mfma_f32_16x16x32_bf16 v[124:127], v[138:141], v[176:179], v[124:127]
	v_mfma_f32_16x16x32_bf16 v[120:123], v[152:155], v[176:179], v[120:123]
	v_mfma_f32_16x16x32_bf16 v[108:111], v[138:141], v[184:187], v[108:111]
	v_mfma_f32_16x16x32_bf16 v[104:107], v[152:155], v[184:187], v[104:107]
	v_mfma_f32_16x16x32_bf16 v[92:95], v[138:141], v[204:207], v[92:95]
	v_mfma_f32_16x16x32_bf16 v[88:91], v[152:155], v[204:207], v[88:91]
	v_mfma_f32_16x16x32_bf16 v[76:79], v[138:141], v[218:221], v[76:79]
	v_mfma_f32_16x16x32_bf16 v[72:75], v[152:155], v[218:221], v[72:75]
	v_mfma_f32_16x16x32_bf16 v[124:127], v[148:151], v[180:183], v[124:127]
	v_mfma_f32_16x16x32_bf16 v[120:123], v[156:159], v[180:183], v[120:123]
	v_mfma_f32_16x16x32_bf16 v[108:111], v[148:151], v[188:191], v[108:111]
	v_mfma_f32_16x16x32_bf16 v[104:107], v[156:159], v[188:191], v[104:107]
	v_mfma_f32_16x16x32_bf16 v[92:95], v[148:151], v[208:211], v[92:95]
	v_mfma_f32_16x16x32_bf16 v[88:91], v[156:159], v[208:211], v[88:91]
	v_mfma_f32_16x16x32_bf16 v[76:79], v[148:151], v[222:225], v[76:79]
	v_mfma_f32_16x16x32_bf16 v[72:75], v[156:159], v[222:225], v[72:75]
	v_mfma_f32_16x16x32_bf16 v[116:119], v[160:163], v[176:179], v[116:119]
	v_mfma_f32_16x16x32_bf16 v[112:115], v[168:171], v[176:179], v[112:115]
	v_mfma_f32_16x16x32_bf16 v[100:103], v[160:163], v[184:187], v[100:103]
	v_mfma_f32_16x16x32_bf16 v[96:99], v[168:171], v[184:187], v[96:99]
	v_mfma_f32_16x16x32_bf16 v[84:87], v[160:163], v[204:207], v[84:87]
	v_mfma_f32_16x16x32_bf16 v[80:83], v[168:171], v[204:207], v[80:83]
	v_mfma_f32_16x16x32_bf16 v[68:71], v[160:163], v[218:221], v[68:71]
	v_mfma_f32_16x16x32_bf16 v[64:67], v[168:171], v[218:221], v[64:67]
	v_mfma_f32_16x16x32_bf16 v[116:119], v[164:167], v[180:183], v[116:119]
	v_mfma_f32_16x16x32_bf16 v[112:115], v[172:175], v[180:183], v[112:115]
	v_mfma_f32_16x16x32_bf16 v[100:103], v[164:167], v[188:191], v[100:103]
	v_mfma_f32_16x16x32_bf16 v[96:99], v[172:175], v[188:191], v[96:99]
	v_mfma_f32_16x16x32_bf16 v[84:87], v[164:167], v[208:211], v[84:87]
	v_mfma_f32_16x16x32_bf16 v[80:83], v[172:175], v[208:211], v[80:83]
	v_mfma_f32_16x16x32_bf16 v[68:71], v[164:167], v[222:225], v[68:71]
	v_mfma_f32_16x16x32_bf16 v[64:67], v[172:175], v[222:225], v[64:67]
	s_barrier
	s_setprio 1
	s_mov_b32 m0, s40
	v_lshl_add_u64 v[142:143], s[30:31], 0, v[192:193]
	s_add_u32 s84, s30, 0x40000
	ds_read_b128 v[176:179], v147 offset:16384
	ds_read_b128 v[180:183], v147 offset:17408
	ds_read_b128 v[184:187], v147 offset:18432
	ds_read_b128 v[188:191], v147 offset:19456
	ds_read_b128 v[204:207], v147 offset:20480
	ds_read_b128 v[208:211], v147 offset:21504
	ds_read_b128 v[218:221], v147 offset:22528
	ds_read_b128 v[222:225], v147 offset:23552
	global_load_lds_dwordx4 v[142:143], off
	v_lshl_add_u64 v[226:227], s[30:31], 0, v[132:133]
	s_mov_b32 m0, s41
	s_addc_u32 s85, s31, 0
	global_load_lds_dwordx4 v[226:227], off
	v_lshl_add_u64 v[228:229], s[84:85], 0, v[192:193]
	s_mov_b32 m0, s43
	v_lshl_add_u64 v[230:231], s[34:35], 0, v[130:131]
	global_load_lds_dwordx4 v[228:229], off
	v_lshl_add_u64 v[228:229], s[84:85], 0, v[132:133]
	s_mov_b32 m0, s44
	s_nop 0
	global_load_lds_dwordx4 v[228:229], off
	v_lshl_add_u64 v[228:229], s[34:35], 0, v[128:129]
	s_mov_b32 m0, s45
	s_nop 0
	global_load_lds_dwordx4 v[228:229], off
	s_mov_b32 m0, s48
	s_nop 0
	global_load_lds_dwordx4 v[230:231], off
	s_waitcnt vmcnt(8)
	s_waitcnt lgkmcnt(0)
	s_setprio 0
	s_barrier
; #define PG8_STAGE(bufoff, gbase, voff) do { _Pragma("unroll") for (int _i = 0; _i < 2; ++_i) \
;         __builtin_amdgcn_global_load_lds((const unsigned*)((const char*)(gbase) + (voff)[_i]), (PG8_LAS unsigned*)(lds + (bufoff) + ldsw + _i * 8192), 16, 0, 0); } while (0)
; #define PG8_LDA(dst, b, h) do { _Pragma("unroll") for (int m = 0; m < 4; ++m) _Pragma("unroll") for (int k = 0; k < 2; ++k) dst[m][k] = *(const PG8_LAS bf16x8*)(lds + PG8_SA(b, h) + aoff + m * 2048 + k * 1024); } while (0)
; #define PG8_LDB(dst, b, h) do { _Pragma("unroll") for (int n = 0; n < 2; ++n) _Pragma("unroll") for (int k = 0; k < 2; ++k) dst[n][k] = *(const PG8_LAS bf16x8*)(lds + PG8_SB(b, h) + boff + n * 2048 + k * 1024); } while (0)
; #define PG8_MMA(ai, bj, At, Bt) do { __builtin_amdgcn_s_setprio(1); _Pragma("unroll") for (int m = 0; m < 4; ++m) _Pragma("unroll") for (int n = 0; n < 2; ++n) _Pragma("unroll") for (int k = 0; k < 2; ++k) \
;         acc[ai][bj][m][n] = __builtin_amdgcn_mfma_f32_16x16x32_bf16(Bt[n][k], At[m][k], acc[ai][bj][m][n], 0, 0, 0); __builtin_amdgcn_s_setprio(0); } while (0)
; #define PG8_WAIT_V(n) asm volatile("s_waitcnt vmcnt(" #n ")" ::: "memory")
; #define PG8_WAIT_L(n) asm volatile("s_waitcnt lgkmcnt(" #n ")" ::: "memory")
; #define PG8_BAR __builtin_amdgcn_s_barrier()
; #define PG8_SCHED __builtin_amdgcn_sched_barrier(0)
; template <class Epi, class Sched, bool ALIGN_EPI = false, bool SP2 = false>
; __device__ __forceinline__ void gemm_phase(PG8_LAS unsigned char* lds, const Gemm g, const Sched& S, const Epi& E) {
;     ...
;             PG8_WAIT_V(8); PG8_WAIT_L(0); PG8_BAR; PG8_MMA(1, 0, At, B0); PG8_MMA(1, 1, At, B1); PG8_BAR; PG8_SCHED;
;             PG8_LDB(B0, 1, 0); PG8_LDB(B1, 1, 1); PG8_SCHED; PG8_LDA(At, 1, 0); PG8_STAGE(PG8_SA(0, 1), a2 + hstepA, voffA);
;             PG8_WAIT_V(8); PG8_WAIT_L(0); PG8_BAR; PG8_MMA(0, 0, At, B0); PG8_MMA(0, 1, At, B1); PG8_BAR; PG8_SCHED;
	s_waitcnt lgkmcnt(0)
	v_mfma_f32_16x16x32_bf16 v[60:63], v[138:141], v[176:179], v[60:63]
	v_mfma_f32_16x16x32_bf16 v[56:59], v[152:155], v[176:179], v[56:59]
	v_mfma_f32_16x16x32_bf16 v[44:47], v[138:141], v[184:187], v[44:47]
	v_mfma_f32_16x16x32_bf16 v[40:43], v[152:155], v[184:187], v[40:43]
	v_mfma_f32_16x16x32_bf16 v[28:31], v[138:141], v[204:207], v[28:31]
	v_mfma_f32_16x16x32_bf16 v[24:27], v[152:155], v[204:207], v[24:27]
	v_mfma_f32_16x16x32_bf16 v[12:15], v[138:141], v[218:221], v[12:15]
	v_mfma_f32_16x16x32_bf16 v[8:11], v[152:155], v[218:221], v[8:11]
	v_mfma_f32_16x16x32_bf16 v[60:63], v[148:151], v[180:183], v[60:63]
	v_mfma_f32_16x16x32_bf16 v[56:59], v[156:159], v[180:183], v[56:59]
	v_mfma_f32_16x16x32_bf16 v[44:47], v[148:151], v[188:191], v[44:47]
	v_mfma_f32_16x16x32_bf16 v[40:43], v[156:159], v[188:191], v[40:43]
	v_mfma_f32_16x16x32_bf16 v[28:31], v[148:151], v[208:211], v[28:31]
	v_mfma_f32_16x16x32_bf16 v[24:27], v[156:159], v[208:211], v[24:27]
	v_mfma_f32_16x16x32_bf16 v[12:15], v[148:151], v[222:225], v[12:15]
	v_mfma_f32_16x16x32_bf16 v[8:11], v[156:159], v[222:225], v[8:11]
	v_mfma_f32_16x16x32_bf16 v[52:55], v[160:163], v[176:179], v[52:55]
	v_mfma_f32_16x16x32_bf16 v[48:51], v[168:171], v[176:179], v[48:51]
	v_mfma_f32_16x16x32_bf16 v[36:39], v[160:163], v[184:187], v[36:39]
	v_mfma_f32_16x16x32_bf16 v[32:35], v[168:171], v[184:187], v[32:35]
	v_mfma_f32_16x16x32_bf16 v[20:23], v[160:163], v[204:207], v[20:23]
	v_mfma_f32_16x16x32_bf16 v[16:19], v[168:171], v[204:207], v[16:19]
	v_mfma_f32_16x16x32_bf16 v[4:7], v[160:163], v[218:221], v[4:7]
	v_mfma_f32_16x16x32_bf16 v[0:3], v[168:171], v[218:221], v[0:3]
	v_mfma_f32_16x16x32_bf16 v[52:55], v[164:167], v[180:183], v[52:55]
	v_mfma_f32_16x16x32_bf16 v[48:51], v[172:175], v[180:183], v[48:51]
	v_mfma_f32_16x16x32_bf16 v[36:39], v[164:167], v[188:191], v[36:39]
	v_mfma_f32_16x16x32_bf16 v[32:35], v[172:175], v[188:191], v[32:35]
	v_mfma_f32_16x16x32_bf16 v[20:23], v[164:167], v[208:211], v[20:23]
	v_mfma_f32_16x16x32_bf16 v[16:19], v[172:175], v[208:211], v[16:19]
	v_mfma_f32_16x16x32_bf16 v[4:7], v[164:167], v[222:225], v[4:7]
	v_mfma_f32_16x16x32_bf16 v[0:3], v[172:175], v[222:225], v[0:3]
	s_barrier
	s_setprio 1
	v_add_u32_e32 v156, s60, v145
	v_add_u32_e32 v172, s67, v145
	ds_read_b128 v[138:141], v156
	ds_read_b128 v[148:151], v156 offset:1024
	ds_read_b128 v[152:155], v156 offset:2048
	ds_read_b128 v[156:159], v156 offset:3072
	ds_read_b128 v[160:163], v172
	ds_read_b128 v[164:167], v172 offset:1024
	ds_read_b128 v[168:171], v172 offset:2048
	ds_read_b128 v[172:175], v172 offset:3072
	s_add_u32 s34, s34, 0x40000
	s_addc_u32 s35, s35, 0
	s_mov_b32 m0, s49
	v_lshl_add_u64 v[232:233], s[34:35], 0, v[128:129]
	ds_read_b128 v[176:179], v147 offset:32768
	ds_read_b128 v[180:183], v147 offset:33792
	ds_read_b128 v[184:187], v147 offset:34816
	ds_read_b128 v[188:191], v147 offset:35840
	ds_read_b128 v[204:207], v147 offset:36864
	ds_read_b128 v[208:211], v147 offset:37888
	ds_read_b128 v[218:221], v147 offset:38912
	ds_read_b128 v[222:225], v147 offset:39936
	global_load_lds_dwordx4 v[232:233], off
	v_lshl_add_u64 v[232:233], s[34:35], 0, v[130:131]
	s_mov_b32 m0, s50
	s_nop 0
	global_load_lds_dwordx4 v[232:233], off
	s_waitcnt vmcnt(8)
	s_waitcnt lgkmcnt(0)
	s_setprio 0
	s_barrier
	s_waitcnt lgkmcnt(0)
	v_mfma_f32_16x16x32_bf16 v[124:127], v[138:141], v[176:179], v[124:127]
	v_mfma_f32_16x16x32_bf16 v[120:123], v[152:155], v[176:179], v[120:123]
	v_mfma_f32_16x16x32_bf16 v[108:111], v[138:141], v[184:187], v[108:111]
	v_mfma_f32_16x16x32_bf16 v[104:107], v[152:155], v[184:187], v[104:107]
	v_mfma_f32_16x16x32_bf16 v[92:95], v[138:141], v[204:207], v[92:95]
	v_mfma_f32_16x16x32_bf16 v[88:91], v[152:155], v[204:207], v[88:91]
	v_mfma_f32_16x16x32_bf16 v[76:79], v[138:141], v[218:221], v[76:79]
	v_mfma_f32_16x16x32_bf16 v[72:75], v[152:155], v[218:221], v[72:75]
	v_mfma_f32_16x16x32_bf16 v[124:127], v[148:151], v[180:183], v[124:127]
	v_mfma_f32_16x16x32_bf16 v[120:123], v[156:159], v[180:183], v[120:123]
	v_mfma_f32_16x16x32_bf16 v[108:111], v[148:151], v[188:191], v[108:111]
	v_mfma_f32_16x16x32_bf16 v[104:107], v[156:159], v[188:191], v[104:107]
	v_mfma_f32_16x16x32_bf16 v[92:95], v[148:151], v[208:211], v[92:95]
	v_mfma_f32_16x16x32_bf16 v[88:91], v[156:159], v[208:211], v[88:91]
	v_mfma_f32_16x16x32_bf16 v[76:79], v[148:151], v[222:225], v[76:79]
	v_mfma_f32_16x16x32_bf16 v[72:75], v[156:159], v[222:225], v[72:75]
	v_mfma_f32_16x16x32_bf16 v[116:119], v[160:163], v[176:179], v[116:119]
	v_mfma_f32_16x16x32_bf16 v[112:115], v[168:171], v[176:179], v[112:115]
	v_mfma_f32_16x16x32_bf16 v[100:103], v[160:163], v[184:187], v[100:103]
	v_mfma_f32_16x16x32_bf16 v[96:99], v[168:171], v[184:187], v[96:99]
	v_mfma_f32_16x16x32_bf16 v[84:87], v[160:163], v[204:207], v[84:87]
	v_mfma_f32_16x16x32_bf16 v[80:83], v[168:171], v[204:207], v[80:83]
	v_mfma_f32_16x16x32_bf16 v[68:71], v[160:163], v[218:221], v[68:71]
	v_mfma_f32_16x16x32_bf16 v[64:67], v[168:171], v[218:221], v[64:67]
	v_mfma_f32_16x16x32_bf16 v[116:119], v[164:167], v[180:183], v[116:119]
	v_mfma_f32_16x16x32_bf16 v[112:115], v[172:175], v[180:183], v[112:115]
	v_mfma_f32_16x16x32_bf16 v[100:103], v[164:167], v[188:191], v[100:103]
	v_mfma_f32_16x16x32_bf16 v[96:99], v[172:175], v[188:191], v[96:99]
	v_mfma_f32_16x16x32_bf16 v[84:87], v[164:167], v[208:211], v[84:87]
	v_mfma_f32_16x16x32_bf16 v[80:83], v[172:175], v[208:211], v[80:83]
	v_mfma_f32_16x16x32_bf16 v[68:71], v[164:167], v[222:225], v[68:71]
	v_mfma_f32_16x16x32_bf16 v[64:67], v[172:175], v[222:225], v[64:67]
	s_barrier
; #define PG8_STAGE(bufoff, gbase, voff) do { _Pragma("unroll") for (int _i = 0; _i < 2; ++_i) \
;         __builtin_amdgcn_global_load_lds((const unsigned*)((const char*)(gbase) + (voff)[_i]), (PG8_LAS unsigned*)(lds + (bufoff) + ldsw + _i * 8192), 16, 0, 0); } while (0)
; #define PG8_LDA(dst, b, h) do { _Pragma("unroll") for (int m = 0; m < 4; ++m) _Pragma("unroll") for (int k = 0; k < 2; ++k) dst[m][k] = *(const PG8_LAS bf16x8*)(lds + PG8_SA(b, h) + aoff + m * 2048 + k * 1024); } while (0)
; #define PG8_MMA(ai, bj, At, Bt) do { __builtin_amdgcn_s_setprio(1); _Pragma("unroll") for (int m = 0; m < 4; ++m) _Pragma("unroll") for (int n = 0; n < 2; ++n) _Pragma("unroll") for (int k = 0; k < 2; ++k) \
;         acc[ai][bj][m][n] = __builtin_amdgcn_mfma_f32_16x16x32_bf16(Bt[n][k], At[m][k], acc[ai][bj][m][n], 0, 0, 0); __builtin_amdgcn_s_setprio(0); } while (0)
; #define PG8_WAIT_V(n) asm volatile("s_waitcnt vmcnt(" #n ")" ::: "memory")
; #define PG8_WAIT_L(n) asm volatile("s_waitcnt lgkmcnt(" #n ")" ::: "memory")
; #define PG8_BAR __builtin_amdgcn_s_barrier()
; #define PG8_SCHED __builtin_amdgcn_sched_barrier(0)
; template <class Epi, class Sched, bool ALIGN_EPI = false, bool SP2 = false>
; __device__ __forceinline__ void gemm_phase(PG8_LAS unsigned char* lds, const Gemm g, const Sched& S, const Epi& E) {
;     ...
;             PG8_LDA(At, 1, 1); PG8_STAGE(PG8_SB(1, 0), b3, voffB); PG8_STAGE(PG8_SB(1, 1), b3 + hstepB, voffB); PG8_STAGE(PG8_SA(1, 0), a3, voffA);
;             PG8_WAIT_V(8); PG8_WAIT_L(0); PG8_BAR; PG8_MMA(1, 0, At, B0); PG8_MMA(1, 1, At, B1); PG8_BAR; PG8_SCHED;
;     __device__ __forceinline__ void operator()(const f32x4 (&acc)[2][2][4][2], const pg8::Unit& u, int wr, int wc, int fr, int fq) const {
;     ...
; #pragma unroll
;         for (int ai = 0; ai < 2; ++ai)
; #pragma unroll
;             for (int m = 0; m < 4; ++m) {
;                 const int row = row0 + ai * 128 + m * 16; float ss = 0.f;
; #pragma unroll
;                 for (int bj = 0; bj < 2; ++bj) {
;                     const size_t off = (size_t)row * DM + col0 + bj * 128;
;                     const v4u b = *(const v4u*)(xb + off);
	s_setprio 1
	s_mov_b32 m0, s61
	v_lshl_add_u64 v[142:143], v[142:143], 0, s[76:77]
	s_add_u32 s30, s30, 0x40080
	ds_read_b128 v[176:179], v147 offset:49152
	ds_read_b128 v[180:183], v147 offset:50176
	ds_read_b128 v[184:187], v147 offset:51200
	ds_read_b128 v[188:191], v147 offset:52224
	ds_read_b128 v[204:207], v147 offset:53248
	ds_read_b128 v[208:211], v147 offset:54272
	ds_read_b128 v[218:221], v147 offset:55296
	ds_read_b128 v[222:225], v147 offset:56320
	global_load_lds_dwordx4 v[142:143], off
	v_lshl_add_u64 v[142:143], v[226:227], 0, s[76:77]
	s_mov_b32 m0, s64
	s_addc_u32 s31, s31, 0
	global_load_lds_dwordx4 v[142:143], off
	v_lshl_add_u64 v[142:143], s[30:31], 0, v[192:193]
	s_mov_b32 m0, s70
	s_nop 0
	global_load_lds_dwordx4 v[142:143], off
	v_lshl_add_u64 v[142:143], s[30:31], 0, v[132:133]
	s_mov_b32 m0, s71
	s_nop 0
	global_load_lds_dwordx4 v[142:143], off
	v_lshl_add_u64 v[142:143], v[228:229], 0, s[76:77]
	s_mov_b32 m0, s65
	s_nop 0
	global_load_lds_dwordx4 v[142:143], off
	v_lshl_add_u64 v[142:143], v[230:231], 0, s[76:77]
	s_mov_b32 m0, s66
	s_nop 0
	global_load_lds_dwordx4 v[142:143], off
	s_waitcnt vmcnt(8)
	s_waitcnt lgkmcnt(0)
	s_setprio 0
	s_barrier
	s_waitcnt lgkmcnt(0)
	v_mfma_f32_16x16x32_bf16 v[60:63], v[138:141], v[176:179], v[60:63]
	v_mfma_f32_16x16x32_bf16 v[56:59], v[152:155], v[176:179], v[56:59]
	v_mfma_f32_16x16x32_bf16 v[44:47], v[138:141], v[184:187], v[44:47]
	v_mfma_f32_16x16x32_bf16 v[40:43], v[152:155], v[184:187], v[40:43]
	v_mfma_f32_16x16x32_bf16 v[28:31], v[138:141], v[204:207], v[28:31]
	v_mfma_f32_16x16x32_bf16 v[24:27], v[152:155], v[204:207], v[24:27]
	v_mfma_f32_16x16x32_bf16 v[12:15], v[138:141], v[218:221], v[12:15]
	v_mfma_f32_16x16x32_bf16 v[8:11], v[152:155], v[218:221], v[8:11]
	v_mfma_f32_16x16x32_bf16 v[60:63], v[148:151], v[180:183], v[60:63]
	v_mfma_f32_16x16x32_bf16 v[56:59], v[156:159], v[180:183], v[56:59]
	v_mfma_f32_16x16x32_bf16 v[44:47], v[148:151], v[188:191], v[44:47]
	v_mfma_f32_16x16x32_bf16 v[40:43], v[156:159], v[188:191], v[40:43]
	v_mfma_f32_16x16x32_bf16 v[28:31], v[148:151], v[208:211], v[28:31]
	v_mfma_f32_16x16x32_bf16 v[24:27], v[156:159], v[208:211], v[24:27]
	v_mfma_f32_16x16x32_bf16 v[12:15], v[148:151], v[222:225], v[12:15]
	v_mfma_f32_16x16x32_bf16 v[8:11], v[156:159], v[222:225], v[8:11]
	v_mfma_f32_16x16x32_bf16 v[52:55], v[160:163], v[176:179], v[52:55]
	v_mfma_f32_16x16x32_bf16 v[48:51], v[168:171], v[176:179], v[48:51]
	v_mfma_f32_16x16x32_bf16 v[36:39], v[160:163], v[184:187], v[36:39]
	v_mfma_f32_16x16x32_bf16 v[32:35], v[168:171], v[184:187], v[32:35]
	v_mfma_f32_16x16x32_bf16 v[20:23], v[160:163], v[204:207], v[20:23]
	v_mfma_f32_16x16x32_bf16 v[16:19], v[168:171], v[204:207], v[16:19]
	v_mfma_f32_16x16x32_bf16 v[4:7], v[160:163], v[218:221], v[4:7]
	v_mfma_f32_16x16x32_bf16 v[0:3], v[168:171], v[218:221], v[0:3]
	v_mfma_f32_16x16x32_bf16 v[52:55], v[164:167], v[180:183], v[52:55]
	v_mfma_f32_16x16x32_bf16 v[48:51], v[172:175], v[180:183], v[48:51]
	v_mfma_f32_16x16x32_bf16 v[36:39], v[164:167], v[188:191], v[36:39]
	v_mfma_f32_16x16x32_bf16 v[32:35], v[172:175], v[188:191], v[32:35]
	v_mfma_f32_16x16x32_bf16 v[20:23], v[164:167], v[208:211], v[20:23]
	v_mfma_f32_16x16x32_bf16 v[16:19], v[172:175], v[208:211], v[16:19]
	v_mfma_f32_16x16x32_bf16 v[4:7], v[164:167], v[222:225], v[4:7]
	v_mfma_f32_16x16x32_bf16 v[0:3], v[172:175], v[222:225], v[0:3]
	s_barrier
	s_setprio 1
	s_add_i32 s82, s82, 2
	s_add_u32 s78, s78, 0x100
	s_addc_u32 s79, s79, 0
	s_add_u32 s28, s28, 0x100
	s_addc_u32 s29, s29, 0
	s_cmp_gt_u32 s82, 13
	s_cbranch_scc0 .LBB0_885
	s_setprio 0
	v_lshl_add_u32 v159, s26, 8, v144
	v_lshl_or_b32 v158, s8, 8, v146
	v_lshlrev_b32_e32 v159, 11, v159
	v_lshl_add_u32 v159, v158, 1, v159
	v_add_u32_e32 v218, 0x8000, v159
	v_add_u32_e32 v219, 0x10000, v159
	v_add_u32_e32 v240, 0x18000, v159
	v_add_u32_e32 v241, 0x40000, v159
	v_add_u32_e32 v245, 0x48000, v159
	v_add_u32_e32 v246, 0x50000, v159
	v_add_u32_e32 v247, 0x58000, v159
	global_load_dwordx4 v[160:163], v159, s[12:13]
	global_load_dwordx4 v[164:167], v159, s[12:13] offset:256
	global_load_dwordx4 v[168:171], v218, s[12:13]
	global_load_dwordx4 v[172:175], v218, s[12:13] offset:256
	global_load_dwordx4 v[176:179], v219, s[12:13]
	global_load_dwordx4 v[180:183], v219, s[12:13] offset:256
	global_load_dwordx4 v[184:187], v240, s[12:13]
	global_load_dwordx4 v[188:191], v240, s[12:13] offset:256
	global_load_dwordx4 v[204:207], v241, s[12:13]
	global_load_dwordx4 v[208:211], v241, s[12:13] offset:256
	global_load_dwordx4 v[220:223], v245, s[12:13]
	global_load_dwordx4 v[224:227], v245, s[12:13] offset:256
	global_load_dwordx4 v[228:231], v246, s[12:13]
	global_load_dwordx4 v[232:235], v246, s[12:13] offset:256
	global_load_dwordx4 v[236:239], v247, s[12:13]
	global_load_dwordx4 v[248:251], v247, s[12:13] offset:256
	s_and_b64 vcc, exec, s[16:17]
	s_cbranch_vccz .LBB0_888
	s_barrier

; #define PG8_STAGE(bufoff, gbase, voff) do { _Pragma("unroll") for (int _i = 0; _i < 2; ++_i) \
;         __builtin_amdgcn_global_load_lds((const unsigned*)((const char*)(gbase) + (voff)[_i]), (PG8_LAS unsigned*)(lds + (bufoff) + ldsw + _i * 8192), 16, 0, 0); } while (0)
; #define PG8_LDA(dst, b, h) do { _Pragma("unroll") for (int m = 0; m < 4; ++m) _Pragma("unroll") for (int k = 0; k < 2; ++k) dst[m][k] = *(const PG8_LAS bf16x8*)(lds + PG8_SA(b, h) + aoff + m * 2048 + k * 1024); } while (0)
; #define PG8_LDB(dst, b, h) do { _Pragma("unroll") for (int n = 0; n < 2; ++n) _Pragma("unroll") for (int k = 0; k < 2; ++k) dst[n][k] = *(const PG8_LAS bf16x8*)(lds + PG8_SB(b, h) + boff + n * 2048 + k * 1024); } while (0)
; #define PG8_MMA(ai, bj, At, Bt) do { __builtin_amdgcn_s_setprio(1); _Pragma("unroll") for (int m = 0; m < 4; ++m) _Pragma("unroll") for (int n = 0; n < 2; ++n) _Pragma("unroll") for (int k = 0; k < 2; ++k) \
;         acc[ai][bj][m][n] = __builtin_amdgcn_mfma_f32_16x16x32_bf16(Bt[n][k], At[m][k], acc[ai][bj][m][n], 0, 0, 0); __builtin_amdgcn_s_setprio(0); } while (0)
; #define PG8_WAIT_V(n) asm volatile("s_waitcnt vmcnt(" #n ")" ::: "memory")
; #define PG8_WAIT_L(n) asm volatile("s_waitcnt lgkmcnt(" #n ")" ::: "memory")
; #define PG8_BAR __builtin_amdgcn_s_barrier()
; #define PG8_SCHED __builtin_amdgcn_sched_barrier(0)
; template <class Epi, class Sched, bool ALIGN_EPI = false, bool SP2 = false>
; __device__ __forceinline__ void gemm_phase(PG8_LAS unsigned char* lds, const Gemm g, const Sched& S, const Epi& E) {
;     ...
;             PG8_LDB(B0, 0, 0); PG8_LDB(B1, 0, 1); PG8_SCHED; PG8_LDA(At, 0, 0); PG8_STAGE(PG8_SA(1, 1), a1 + hstepA, voffA);
;             PG8_WAIT_V(8); PG8_WAIT_L(0); PG8_BAR; PG8_MMA(0, 0, At, B0); PG8_MMA(0, 1, At, B1); PG8_BAR; PG8_SCHED;
;             PG8_LDA(At, 0, 1); PG8_STAGE(PG8_SB(0, 0), b2, voffB); PG8_STAGE(PG8_SB(0, 1), b2 + hstepB, voffB); PG8_STAGE(PG8_SA(0, 0), a2, voffA);
;             PG8_WAIT_V(8); PG8_WAIT_L(0); PG8_BAR; PG8_MMA(1, 0, At, B0); PG8_MMA(1, 1, At, B1); PG8_BAR; PG8_SCHED;
.LBB0_995:
	s_setprio 1
	v_add_u32_e32 v154, s38, v175
	v_add_u32_e32 v170, s41, v175
	ds_read_b128 v[142:145], v154
	ds_read_b128 v[146:149], v154 offset:1024
	ds_read_b128 v[150:153], v154 offset:2048
	ds_read_b128 v[154:157], v154 offset:3072
	ds_read_b128 v[158:161], v170
	ds_read_b128 v[162:165], v170 offset:1024
	ds_read_b128 v[166:169], v170 offset:2048
	ds_read_b128 v[170:173], v170 offset:3072
	s_add_u32 s2, s26, 0xfffc0080
	s_addc_u32 s28, s27, -1
	s_cmp_eq_u32 s82, 12
	s_cselect_b32 s31, s17, s28
	s_cselect_b32 s30, s23, s2
	s_cselect_b32 s29, s15, s79
	s_cselect_b32 s28, s25, s78
	v_lshl_add_u64 v[246:247], s[26:27], 0, v[140:141]
	s_add_i32 m0, s44, 0xc000
	ds_read_b128 v[208:211], v207
	ds_read_b128 v[218:221], v207 offset:1024
	ds_read_b128 v[222:225], v207 offset:2048
	ds_read_b128 v[226:229], v207 offset:3072
	ds_read_b128 v[230:233], v207 offset:4096
	ds_read_b128 v[234:237], v207 offset:5120
	ds_read_b128 v[238:241], v207 offset:6144
	ds_read_b128 v[242:245], v207 offset:7168
	global_load_lds_dwordx4 v[246:247], off
	v_lshl_add_u64 v[246:247], s[26:27], 0, v[138:139]
	s_add_i32 m0, s44, 0xe000
	s_nop 0
	global_load_lds_dwordx4 v[246:247], off
	s_waitcnt vmcnt(8)
	s_waitcnt lgkmcnt(0)
	s_setprio 0
	s_barrier
	s_waitcnt lgkmcnt(0)
	v_mfma_f32_16x16x32_bf16 v[124:127], v[142:145], v[208:211], v[124:127]
	v_mfma_f32_16x16x32_bf16 v[120:123], v[150:153], v[208:211], v[120:123]
	v_mfma_f32_16x16x32_bf16 v[108:111], v[142:145], v[222:225], v[108:111]
	v_mfma_f32_16x16x32_bf16 v[104:107], v[150:153], v[222:225], v[104:107]
	v_mfma_f32_16x16x32_bf16 v[92:95], v[142:145], v[230:233], v[92:95]
	v_mfma_f32_16x16x32_bf16 v[88:91], v[150:153], v[230:233], v[88:91]
	v_mfma_f32_16x16x32_bf16 v[76:79], v[142:145], v[238:241], v[76:79]
	v_mfma_f32_16x16x32_bf16 v[72:75], v[150:153], v[238:241], v[72:75]
	v_mfma_f32_16x16x32_bf16 v[124:127], v[146:149], v[218:221], v[124:127]
	v_mfma_f32_16x16x32_bf16 v[120:123], v[154:157], v[218:221], v[120:123]
	v_mfma_f32_16x16x32_bf16 v[108:111], v[146:149], v[226:229], v[108:111]
	v_mfma_f32_16x16x32_bf16 v[104:107], v[154:157], v[226:229], v[104:107]
	v_mfma_f32_16x16x32_bf16 v[92:95], v[146:149], v[234:237], v[92:95]
	v_mfma_f32_16x16x32_bf16 v[88:91], v[154:157], v[234:237], v[88:91]
	v_mfma_f32_16x16x32_bf16 v[76:79], v[146:149], v[242:245], v[76:79]
	v_mfma_f32_16x16x32_bf16 v[72:75], v[154:157], v[242:245], v[72:75]
	v_mfma_f32_16x16x32_bf16 v[116:119], v[158:161], v[208:211], v[116:119]
	v_mfma_f32_16x16x32_bf16 v[112:115], v[166:169], v[208:211], v[112:115]
	v_mfma_f32_16x16x32_bf16 v[100:103], v[158:161], v[222:225], v[100:103]
	v_mfma_f32_16x16x32_bf16 v[96:99], v[166:169], v[222:225], v[96:99]
	v_mfma_f32_16x16x32_bf16 v[84:87], v[158:161], v[230:233], v[84:87]
	v_mfma_f32_16x16x32_bf16 v[80:83], v[166:169], v[230:233], v[80:83]
	v_mfma_f32_16x16x32_bf16 v[68:71], v[158:161], v[238:241], v[68:71]
	v_mfma_f32_16x16x32_bf16 v[64:67], v[166:169], v[238:241], v[64:67]
	v_mfma_f32_16x16x32_bf16 v[116:119], v[162:165], v[218:221], v[116:119]
	v_mfma_f32_16x16x32_bf16 v[112:115], v[170:173], v[218:221], v[112:115]
	v_mfma_f32_16x16x32_bf16 v[100:103], v[162:165], v[226:229], v[100:103]
	v_mfma_f32_16x16x32_bf16 v[96:99], v[170:173], v[226:229], v[96:99]
	v_mfma_f32_16x16x32_bf16 v[84:87], v[162:165], v[234:237], v[84:87]
	v_mfma_f32_16x16x32_bf16 v[80:83], v[170:173], v[234:237], v[80:83]
	v_mfma_f32_16x16x32_bf16 v[68:71], v[162:165], v[242:245], v[68:71]
	v_mfma_f32_16x16x32_bf16 v[64:67], v[170:173], v[242:245], v[64:67]
	s_barrier
	s_setprio 1
	s_mov_b32 m0, s39
	v_lshl_add_u64 v[246:247], s[28:29], 0, v[130:131]
	s_add_u32 s84, s28, 0x40000
	ds_read_b128 v[208:211], v207 offset:16384
	ds_read_b128 v[218:221], v207 offset:17408
	ds_read_b128 v[222:225], v207 offset:18432
	ds_read_b128 v[226:229], v207 offset:19456
	ds_read_b128 v[230:233], v207 offset:20480
	ds_read_b128 v[234:237], v207 offset:21504
	ds_read_b128 v[238:241], v207 offset:22528
	ds_read_b128 v[242:245], v207 offset:23552
	global_load_lds_dwordx4 v[246:247], off
	v_lshl_add_u64 v[248:249], s[28:29], 0, v[134:135]
	s_mov_b32 m0, s40
	s_addc_u32 s85, s29, 0
	global_load_lds_dwordx4 v[248:249], off
	v_lshl_add_u64 v[250:251], s[84:85], 0, v[130:131]
	s_mov_b32 m0, s42
	v_lshl_add_u64 v[252:253], s[30:31], 0, v[132:133]
	global_load_lds_dwordx4 v[250:251], off
	v_lshl_add_u64 v[250:251], s[84:85], 0, v[134:135]
	s_mov_b32 m0, s43
	s_nop 0
	global_load_lds_dwordx4 v[250:251], off
	v_lshl_add_u64 v[250:251], s[30:31], 0, v[128:129]
	s_mov_b32 m0, s44
	s_nop 0
	global_load_lds_dwordx4 v[250:251], off
	s_mov_b32 m0, s45
	s_nop 0
	global_load_lds_dwordx4 v[252:253], off
	s_waitcnt vmcnt(8)
	s_waitcnt lgkmcnt(0)
	s_setprio 0
	s_barrier
; #define PG8_STAGE(bufoff, gbase, voff) do { _Pragma("unroll") for (int _i = 0; _i < 2; ++_i) \
;         __builtin_amdgcn_global_load_lds((const unsigned*)((const char*)(gbase) + (voff)[_i]), (PG8_LAS unsigned*)(lds + (bufoff) + ldsw + _i * 8192), 16, 0, 0); } while (0)
; #define PG8_LDA(dst, b, h) do { _Pragma("unroll") for (int m = 0; m < 4; ++m) _Pragma("unroll") for (int k = 0; k < 2; ++k) dst[m][k] = *(const PG8_LAS bf16x8*)(lds + PG8_SA(b, h) + aoff + m * 2048 + k * 1024); } while (0)
; #define PG8_LDB(dst, b, h) do { _Pragma("unroll") for (int n = 0; n < 2; ++n) _Pragma("unroll") for (int k = 0; k < 2; ++k) dst[n][k] = *(const PG8_LAS bf16x8*)(lds + PG8_SB(b, h) + boff + n * 2048 + k * 1024); } while (0)
; #define PG8_MMA(ai, bj, At, Bt) do { __builtin_amdgcn_s_setprio(1); _Pragma("unroll") for (int m = 0; m < 4; ++m) _Pragma("unroll") for (int n = 0; n < 2; ++n) _Pragma("unroll") for (int k = 0; k < 2; ++k) \
;         acc[ai][bj][m][n] = __builtin_amdgcn_mfma_f32_16x16x32_bf16(Bt[n][k], At[m][k], acc[ai][bj][m][n], 0, 0, 0); __builtin_amdgcn_s_setprio(0); } while (0)
; #define PG8_WAIT_V(n) asm volatile("s_waitcnt vmcnt(" #n ")" ::: "memory")
; #define PG8_WAIT_L(n) asm volatile("s_waitcnt lgkmcnt(" #n ")" ::: "memory")
; #define PG8_BAR __builtin_amdgcn_s_barrier()
; #define PG8_SCHED __builtin_amdgcn_sched_barrier(0)
; template <class Epi, class Sched, bool ALIGN_EPI = false, bool SP2 = false>
; __device__ __forceinline__ void gemm_phase(PG8_LAS unsigned char* lds, const Gemm g, const Sched& S, const Epi& E) {
;     ...
;             PG8_WAIT_V(8); PG8_WAIT_L(0); PG8_BAR; PG8_MMA(1, 0, At, B0); PG8_MMA(1, 1, At, B1); PG8_BAR; PG8_SCHED;
;             PG8_LDB(B0, 1, 0); PG8_LDB(B1, 1, 1); PG8_SCHED; PG8_LDA(At, 1, 0); PG8_STAGE(PG8_SA(0, 1), a2 + hstepA, voffA);
;             PG8_WAIT_V(8); PG8_WAIT_L(0); PG8_BAR; PG8_MMA(0, 0, At, B0); PG8_MMA(0, 1, At, B1); PG8_BAR; PG8_SCHED;
	s_waitcnt lgkmcnt(0)
	v_mfma_f32_16x16x32_bf16 v[60:63], v[142:145], v[208:211], v[60:63]
	v_mfma_f32_16x16x32_bf16 v[56:59], v[150:153], v[208:211], v[56:59]
	v_mfma_f32_16x16x32_bf16 v[44:47], v[142:145], v[222:225], v[44:47]
	v_mfma_f32_16x16x32_bf16 v[40:43], v[150:153], v[222:225], v[40:43]
	v_mfma_f32_16x16x32_bf16 v[28:31], v[142:145], v[230:233], v[28:31]
	v_mfma_f32_16x16x32_bf16 v[24:27], v[150:153], v[230:233], v[24:27]
	v_mfma_f32_16x16x32_bf16 v[12:15], v[142:145], v[238:241], v[12:15]
	v_mfma_f32_16x16x32_bf16 v[8:11], v[150:153], v[238:241], v[8:11]
	v_mfma_f32_16x16x32_bf16 v[60:63], v[146:149], v[218:221], v[60:63]
	v_mfma_f32_16x16x32_bf16 v[56:59], v[154:157], v[218:221], v[56:59]
	v_mfma_f32_16x16x32_bf16 v[44:47], v[146:149], v[226:229], v[44:47]
	v_mfma_f32_16x16x32_bf16 v[40:43], v[154:157], v[226:229], v[40:43]
	v_mfma_f32_16x16x32_bf16 v[28:31], v[146:149], v[234:237], v[28:31]
	v_mfma_f32_16x16x32_bf16 v[24:27], v[154:157], v[234:237], v[24:27]
	v_mfma_f32_16x16x32_bf16 v[12:15], v[146:149], v[242:245], v[12:15]
	v_mfma_f32_16x16x32_bf16 v[8:11], v[154:157], v[242:245], v[8:11]
	v_mfma_f32_16x16x32_bf16 v[52:55], v[158:161], v[208:211], v[52:55]
	v_mfma_f32_16x16x32_bf16 v[48:51], v[166:169], v[208:211], v[48:51]
	v_mfma_f32_16x16x32_bf16 v[36:39], v[158:161], v[222:225], v[36:39]
	v_mfma_f32_16x16x32_bf16 v[32:35], v[166:169], v[222:225], v[32:35]
	v_mfma_f32_16x16x32_bf16 v[20:23], v[158:161], v[230:233], v[20:23]
	v_mfma_f32_16x16x32_bf16 v[16:19], v[166:169], v[230:233], v[16:19]
	v_mfma_f32_16x16x32_bf16 v[4:7], v[158:161], v[238:241], v[4:7]
	v_mfma_f32_16x16x32_bf16 v[0:3], v[166:169], v[238:241], v[0:3]
	v_mfma_f32_16x16x32_bf16 v[52:55], v[162:165], v[218:221], v[52:55]
	v_mfma_f32_16x16x32_bf16 v[48:51], v[170:173], v[218:221], v[48:51]
	v_mfma_f32_16x16x32_bf16 v[36:39], v[162:165], v[226:229], v[36:39]
	v_mfma_f32_16x16x32_bf16 v[32:35], v[170:173], v[226:229], v[32:35]
	v_mfma_f32_16x16x32_bf16 v[20:23], v[162:165], v[234:237], v[20:23]
	v_mfma_f32_16x16x32_bf16 v[16:19], v[170:173], v[234:237], v[16:19]
	v_mfma_f32_16x16x32_bf16 v[4:7], v[162:165], v[242:245], v[4:7]
	v_mfma_f32_16x16x32_bf16 v[0:3], v[170:173], v[242:245], v[0:3]
	s_barrier
	s_setprio 1
	v_add_u32_e32 v154, s50, v175
	v_add_u32_e32 v170, s65, v175
	ds_read_b128 v[142:145], v154
	ds_read_b128 v[146:149], v154 offset:1024
	ds_read_b128 v[150:153], v154 offset:2048
	ds_read_b128 v[154:157], v154 offset:3072
	ds_read_b128 v[158:161], v170
	ds_read_b128 v[162:165], v170 offset:1024
	ds_read_b128 v[166:169], v170 offset:2048
	ds_read_b128 v[170:173], v170 offset:3072
	s_add_u32 s30, s30, 0x40000
	s_addc_u32 s31, s31, 0
	s_mov_b32 m0, s48
	v_lshl_add_u64 v[194:195], s[30:31], 0, v[128:129]
	ds_read_b128 v[208:211], v207 offset:32768
	ds_read_b128 v[218:221], v207 offset:33792
	ds_read_b128 v[222:225], v207 offset:34816
	ds_read_b128 v[226:229], v207 offset:35840
	ds_read_b128 v[230:233], v207 offset:36864
	ds_read_b128 v[234:237], v207 offset:37888
	ds_read_b128 v[238:241], v207 offset:38912
	ds_read_b128 v[242:245], v207 offset:39936
	global_load_lds_dwordx4 v[194:195], off
	v_lshl_add_u64 v[194:195], s[30:31], 0, v[132:133]
	s_mov_b32 m0, s49
	s_nop 0
	global_load_lds_dwordx4 v[194:195], off
	s_waitcnt vmcnt(8)
	s_waitcnt lgkmcnt(0)
	s_setprio 0
	s_barrier
	s_waitcnt lgkmcnt(0)
	v_mfma_f32_16x16x32_bf16 v[124:127], v[142:145], v[208:211], v[124:127]
	v_mfma_f32_16x16x32_bf16 v[120:123], v[150:153], v[208:211], v[120:123]
	v_mfma_f32_16x16x32_bf16 v[108:111], v[142:145], v[222:225], v[108:111]
	v_mfma_f32_16x16x32_bf16 v[104:107], v[150:153], v[222:225], v[104:107]
	v_mfma_f32_16x16x32_bf16 v[92:95], v[142:145], v[230:233], v[92:95]
	v_mfma_f32_16x16x32_bf16 v[88:91], v[150:153], v[230:233], v[88:91]
	v_mfma_f32_16x16x32_bf16 v[76:79], v[142:145], v[238:241], v[76:79]
	v_mfma_f32_16x16x32_bf16 v[72:75], v[150:153], v[238:241], v[72:75]
	v_mfma_f32_16x16x32_bf16 v[124:127], v[146:149], v[218:221], v[124:127]
	v_mfma_f32_16x16x32_bf16 v[120:123], v[154:157], v[218:221], v[120:123]
	v_mfma_f32_16x16x32_bf16 v[108:111], v[146:149], v[226:229], v[108:111]
	v_mfma_f32_16x16x32_bf16 v[104:107], v[154:157], v[226:229], v[104:107]
	v_mfma_f32_16x16x32_bf16 v[92:95], v[146:149], v[234:237], v[92:95]
	v_mfma_f32_16x16x32_bf16 v[88:91], v[154:157], v[234:237], v[88:91]
	v_mfma_f32_16x16x32_bf16 v[76:79], v[146:149], v[242:245], v[76:79]
	v_mfma_f32_16x16x32_bf16 v[72:75], v[154:157], v[242:245], v[72:75]
	v_mfma_f32_16x16x32_bf16 v[116:119], v[158:161], v[208:211], v[116:119]
	v_mfma_f32_16x16x32_bf16 v[112:115], v[166:169], v[208:211], v[112:115]
	v_mfma_f32_16x16x32_bf16 v[100:103], v[158:161], v[222:225], v[100:103]
	v_mfma_f32_16x16x32_bf16 v[96:99], v[166:169], v[222:225], v[96:99]
	v_mfma_f32_16x16x32_bf16 v[84:87], v[158:161], v[230:233], v[84:87]
	v_mfma_f32_16x16x32_bf16 v[80:83], v[166:169], v[230:233], v[80:83]
	v_mfma_f32_16x16x32_bf16 v[68:71], v[158:161], v[238:241], v[68:71]
	v_mfma_f32_16x16x32_bf16 v[64:67], v[166:169], v[238:241], v[64:67]
	v_mfma_f32_16x16x32_bf16 v[116:119], v[162:165], v[218:221], v[116:119]
	v_mfma_f32_16x16x32_bf16 v[112:115], v[170:173], v[218:221], v[112:115]
	v_mfma_f32_16x16x32_bf16 v[100:103], v[162:165], v[226:229], v[100:103]
	v_mfma_f32_16x16x32_bf16 v[96:99], v[170:173], v[226:229], v[96:99]
	v_mfma_f32_16x16x32_bf16 v[84:87], v[162:165], v[234:237], v[84:87]
	v_mfma_f32_16x16x32_bf16 v[80:83], v[170:173], v[234:237], v[80:83]
	v_mfma_f32_16x16x32_bf16 v[68:71], v[162:165], v[242:245], v[68:71]
	v_mfma_f32_16x16x32_bf16 v[64:67], v[170:173], v[242:245], v[64:67]
	s_barrier
; #define PG8_STAGE(bufoff, gbase, voff) do { _Pragma("unroll") for (int _i = 0; _i < 2; ++_i) \
;         __builtin_amdgcn_global_load_lds((const unsigned*)((const char*)(gbase) + (voff)[_i]), (PG8_LAS unsigned*)(lds + (bufoff) + ldsw + _i * 8192), 16, 0, 0); } while (0)
; #define PG8_LDA(dst, b, h) do { _Pragma("unroll") for (int m = 0; m < 4; ++m) _Pragma("unroll") for (int k = 0; k < 2; ++k) dst[m][k] = *(const PG8_LAS bf16x8*)(lds + PG8_SA(b, h) + aoff + m * 2048 + k * 1024); } while (0)
; #define PG8_MMA(ai, bj, At, Bt) do { __builtin_amdgcn_s_setprio(1); _Pragma("unroll") for (int m = 0; m < 4; ++m) _Pragma("unroll") for (int n = 0; n < 2; ++n) _Pragma("unroll") for (int k = 0; k < 2; ++k) \
;         acc[ai][bj][m][n] = __builtin_amdgcn_mfma_f32_16x16x32_bf16(Bt[n][k], At[m][k], acc[ai][bj][m][n], 0, 0, 0); __builtin_amdgcn_s_setprio(0); } while (0)
; #define PG8_WAIT_V(n) asm volatile("s_waitcnt vmcnt(" #n ")" ::: "memory")
; #define PG8_WAIT_L(n) asm volatile("s_waitcnt lgkmcnt(" #n ")" ::: "memory")
; #define PG8_BAR __builtin_amdgcn_s_barrier()
; #define PG8_SCHED __builtin_amdgcn_sched_barrier(0)
; template <class Epi, class Sched, bool ALIGN_EPI = false, bool SP2 = false>
; __device__ __forceinline__ void gemm_phase(PG8_LAS unsigned char* lds, const Gemm g, const Sched& S, const Epi& E) {
;     ...
;             PG8_LDA(At, 1, 1); PG8_STAGE(PG8_SB(1, 0), b3, voffB); PG8_STAGE(PG8_SB(1, 1), b3 + hstepB, voffB); PG8_STAGE(PG8_SA(1, 0), a3, voffA);
;             PG8_WAIT_V(8); PG8_WAIT_L(0); PG8_BAR; PG8_MMA(1, 0, At, B0); PG8_MMA(1, 1, At, B1); PG8_BAR; PG8_SCHED;
; __device__ __forceinline__ float row_rstd(const float* ssq, int row, int fq) {
;     const f32x4 v = *(const f32x4*)(ssq + (size_t)row * 16 + fq * 4);
;     float s = (v[0] + v[1]) + (v[2] + v[3]);
;     s += __shfl_xor(s, 16); s += __shfl_xor(s, 32);
;     return __builtin_amdgcn_rsqf(s * (1.f / DM) + EPS);
	s_setprio 1
	s_mov_b32 m0, s51
	v_lshl_add_u64 v[194:195], v[246:247], 0, s[76:77]
	s_add_u32 s28, s28, 0x40080
	ds_read_b128 v[208:211], v207 offset:49152
	ds_read_b128 v[218:221], v207 offset:50176
	ds_read_b128 v[222:225], v207 offset:51200
	ds_read_b128 v[226:229], v207 offset:52224
	ds_read_b128 v[230:233], v207 offset:53248
	ds_read_b128 v[234:237], v207 offset:54272
	ds_read_b128 v[238:241], v207 offset:55296
	ds_read_b128 v[242:245], v207 offset:56320
	global_load_lds_dwordx4 v[194:195], off
	v_lshl_add_u64 v[194:195], v[248:249], 0, s[76:77]
	s_mov_b32 m0, s60
	s_addc_u32 s29, s29, 0
	global_load_lds_dwordx4 v[194:195], off
	v_lshl_add_u64 v[194:195], s[28:29], 0, v[130:131]
	s_mov_b32 m0, s66
	s_nop 0
	global_load_lds_dwordx4 v[194:195], off
	v_lshl_add_u64 v[194:195], s[28:29], 0, v[134:135]
	s_mov_b32 m0, s67
	s_nop 0
	global_load_lds_dwordx4 v[194:195], off
	v_lshl_add_u64 v[194:195], v[250:251], 0, s[76:77]
	s_mov_b32 m0, s61
	s_nop 0
	global_load_lds_dwordx4 v[194:195], off
	v_lshl_add_u64 v[194:195], v[252:253], 0, s[76:77]
	s_mov_b32 m0, s64
	s_nop 0
	global_load_lds_dwordx4 v[194:195], off
	s_waitcnt vmcnt(8)
	s_waitcnt lgkmcnt(0)
	s_setprio 0
	s_barrier
	s_waitcnt lgkmcnt(0)
	v_mfma_f32_16x16x32_bf16 v[60:63], v[142:145], v[208:211], v[60:63]
	v_mfma_f32_16x16x32_bf16 v[56:59], v[150:153], v[208:211], v[56:59]
	v_mfma_f32_16x16x32_bf16 v[44:47], v[142:145], v[222:225], v[44:47]
	v_mfma_f32_16x16x32_bf16 v[40:43], v[150:153], v[222:225], v[40:43]
	v_mfma_f32_16x16x32_bf16 v[28:31], v[142:145], v[230:233], v[28:31]
	v_mfma_f32_16x16x32_bf16 v[24:27], v[150:153], v[230:233], v[24:27]
	v_mfma_f32_16x16x32_bf16 v[12:15], v[142:145], v[238:241], v[12:15]
	v_mfma_f32_16x16x32_bf16 v[8:11], v[150:153], v[238:241], v[8:11]
	v_mfma_f32_16x16x32_bf16 v[60:63], v[146:149], v[218:221], v[60:63]
	v_mfma_f32_16x16x32_bf16 v[56:59], v[154:157], v[218:221], v[56:59]
	v_mfma_f32_16x16x32_bf16 v[44:47], v[146:149], v[226:229], v[44:47]
	v_mfma_f32_16x16x32_bf16 v[40:43], v[154:157], v[226:229], v[40:43]
	v_mfma_f32_16x16x32_bf16 v[28:31], v[146:149], v[234:237], v[28:31]
	v_mfma_f32_16x16x32_bf16 v[24:27], v[154:157], v[234:237], v[24:27]
	v_mfma_f32_16x16x32_bf16 v[12:15], v[146:149], v[242:245], v[12:15]
	v_mfma_f32_16x16x32_bf16 v[8:11], v[154:157], v[242:245], v[8:11]
	v_mfma_f32_16x16x32_bf16 v[52:55], v[158:161], v[208:211], v[52:55]
	v_mfma_f32_16x16x32_bf16 v[48:51], v[166:169], v[208:211], v[48:51]
	v_mfma_f32_16x16x32_bf16 v[36:39], v[158:161], v[222:225], v[36:39]
	v_mfma_f32_16x16x32_bf16 v[32:35], v[166:169], v[222:225], v[32:35]
	v_mfma_f32_16x16x32_bf16 v[20:23], v[158:161], v[230:233], v[20:23]
	v_mfma_f32_16x16x32_bf16 v[16:19], v[166:169], v[230:233], v[16:19]
	v_mfma_f32_16x16x32_bf16 v[4:7], v[158:161], v[238:241], v[4:7]
	v_mfma_f32_16x16x32_bf16 v[0:3], v[166:169], v[238:241], v[0:3]
	v_mfma_f32_16x16x32_bf16 v[52:55], v[162:165], v[218:221], v[52:55]
	v_mfma_f32_16x16x32_bf16 v[48:51], v[170:173], v[218:221], v[48:51]
	v_mfma_f32_16x16x32_bf16 v[36:39], v[162:165], v[226:229], v[36:39]
	v_mfma_f32_16x16x32_bf16 v[32:35], v[170:173], v[226:229], v[32:35]
	v_mfma_f32_16x16x32_bf16 v[20:23], v[162:165], v[234:237], v[20:23]
	v_mfma_f32_16x16x32_bf16 v[16:19], v[170:173], v[234:237], v[16:19]
	v_mfma_f32_16x16x32_bf16 v[4:7], v[162:165], v[242:245], v[4:7]
	v_mfma_f32_16x16x32_bf16 v[0:3], v[170:173], v[242:245], v[0:3]
	s_barrier
	s_setprio 1
	s_add_i32 s82, s82, 2
	s_add_u32 s78, s78, 0x100
	s_addc_u32 s79, s79, 0
	s_add_u32 s26, s26, 0x100
	s_addc_u32 s27, s27, 0
	s_cmp_gt_u32 s82, 13
	s_cbranch_scc0 .LBB0_995
	s_setprio 0
	v_lshl_add_u32 v228, s24, 8, v174
	v_mov_b32_e32 v144, v228
	v_ashrrev_i32_e32 v145, 31, v144
	v_lshlrev_b64 v[144:145], 6, v[144:145]
	v_lshl_add_u64 v[144:145], v[136:137], 0, v[144:145]
	global_load_dwordx4 v[144:147], v[144:145], off
	v_add_u32_e32 v148, 16, v228
	v_ashrrev_i32_e32 v149, 31, v148
	v_lshlrev_b64 v[148:149], 6, v[148:149]
	v_lshl_add_u64 v[148:149], v[136:137], 0, v[148:149]
	global_load_dwordx4 v[148:151], v[148:149], off
	v_add_u32_e32 v152, 32, v228
	v_ashrrev_i32_e32 v153, 31, v152
	v_lshlrev_b64 v[152:153], 6, v[152:153]
	v_lshl_add_u64 v[152:153], v[136:137], 0, v[152:153]
	global_load_dwordx4 v[152:155], v[152:153], off
	v_add_u32_e32 v156, 48, v228
	v_ashrrev_i32_e32 v157, 31, v156
	v_lshlrev_b64 v[156:157], 6, v[156:157]
	v_lshl_add_u64 v[156:157], v[136:137], 0, v[156:157]
	global_load_dwordx4 v[156:159], v[156:157], off
	v_add_u32_e32 v160, 0x80, v228
	v_ashrrev_i32_e32 v161, 31, v160
	v_lshlrev_b64 v[160:161], 6, v[160:161]
	v_lshl_add_u64 v[160:161], v[136:137], 0, v[160:161]
	global_load_dwordx4 v[160:163], v[160:161], off
	v_add_u32_e32 v164, 0x90, v228
	v_ashrrev_i32_e32 v165, 31, v164
	v_lshlrev_b64 v[164:165], 6, v[164:165]
	v_lshl_add_u64 v[164:165], v[136:137], 0, v[164:165]
	global_load_dwordx4 v[164:167], v[164:165], off
	v_add_u32_e32 v168, 0xa0, v228
	v_ashrrev_i32_e32 v169, 31, v168
	v_lshlrev_b64 v[168:169], 6, v[168:169]
	v_lshl_add_u64 v[168:169], v[136:137], 0, v[168:169]
	global_load_dwordx4 v[168:171], v[168:169], off
	v_add_u32_e32 v222, 0xb0, v228
	v_ashrrev_i32_e32 v223, 31, v222
	v_lshlrev_b64 v[222:223], 6, v[222:223]
	v_lshl_add_u64 v[222:223], v[136:137], 0, v[222:223]
	global_load_dwordx4 v[222:225], v[222:223], off
	v_xor_b32_e32 v226, 16, v215
	v_xor_b32_e32 v227, 32, v215
	v_lshlrev_b32_e32 v226, 2, v226
	v_lshlrev_b32_e32 v227, 2, v227
	s_and_b64 vcc, exec, s[12:13]
	s_cbranch_vccz .LBB0_998
	s_barrier

; #define PG8_STAGE(bufoff, gbase, voff) do { _Pragma("unroll") for (int _i = 0; _i < 2; ++_i) \
;         __builtin_amdgcn_global_load_lds((const unsigned*)((const char*)(gbase) + (voff)[_i]), (PG8_LAS unsigned*)(lds + (bufoff) + ldsw + _i * 8192), 16, 0, 0); } while (0)
; #define PG8_LDA(dst, b, h) do { _Pragma("unroll") for (int m = 0; m < 4; ++m) _Pragma("unroll") for (int k = 0; k < 2; ++k) dst[m][k] = *(const PG8_LAS bf16x8*)(lds + PG8_SA(b, h) + aoff + m * 2048 + k * 1024); } while (0)
; #define PG8_LDB(dst, b, h) do { _Pragma("unroll") for (int n = 0; n < 2; ++n) _Pragma("unroll") for (int k = 0; k < 2; ++k) dst[n][k] = *(const PG8_LAS bf16x8*)(lds + PG8_SB(b, h) + boff + n * 2048 + k * 1024); } while (0)
; #define PG8_MMA(ai, bj, At, Bt) do { __builtin_amdgcn_s_setprio(1); _Pragma("unroll") for (int m = 0; m < 4; ++m) _Pragma("unroll") for (int n = 0; n < 2; ++n) _Pragma("unroll") for (int k = 0; k < 2; ++k) \
;         acc[ai][bj][m][n] = __builtin_amdgcn_mfma_f32_16x16x32_bf16(Bt[n][k], At[m][k], acc[ai][bj][m][n], 0, 0, 0); __builtin_amdgcn_s_setprio(0); } while (0)
; #define PG8_WAIT_V(n) asm volatile("s_waitcnt vmcnt(" #n ")" ::: "memory")
; #define PG8_WAIT_L(n) asm volatile("s_waitcnt lgkmcnt(" #n ")" ::: "memory")
; #define PG8_BAR __builtin_amdgcn_s_barrier()
; #define PG8_SCHED __builtin_amdgcn_sched_barrier(0)
; template <class Epi, class Sched, bool ALIGN_EPI = false, bool SP2 = false>
; __device__ __forceinline__ void gemm_phase(PG8_LAS unsigned char* lds, const Gemm g, const Sched& S, const Epi& E) {
;     ...
;             PG8_LDB(B0, 0, 0); PG8_LDB(B1, 0, 1); PG8_SCHED; PG8_LDA(At, 0, 0); PG8_STAGE(PG8_SA(1, 1), a1 + hstepA, voffA);
;             PG8_WAIT_V(8); PG8_WAIT_L(0); PG8_BAR; PG8_MMA(0, 0, At, B0); PG8_MMA(0, 1, At, B1); PG8_BAR; PG8_SCHED;
;             PG8_LDA(At, 0, 1); PG8_STAGE(PG8_SB(0, 0), b2, voffB); PG8_STAGE(PG8_SB(0, 1), b2 + hstepB, voffB); PG8_STAGE(PG8_SA(0, 0), a2, voffA);
;             PG8_WAIT_V(8); PG8_WAIT_L(0); PG8_BAR; PG8_MMA(1, 0, At, B0); PG8_MMA(1, 1, At, B1); PG8_BAR; PG8_SCHED;
.LBB0_1121:
	s_setprio 1
	v_add_u32_e32 v142, s9, v145
	ds_read_b128 v[138:141], v142
	ds_read_b128 v[148:151], v142 offset:1024
	ds_read_b128 v[152:155], v142 offset:2048
	ds_read_b128 v[156:159], v142 offset:3072
	v_add_u32_e32 v142, s42, v145
	ds_read_b128 v[160:163], v142
	ds_read_b128 v[164:167], v142 offset:1024
	ds_read_b128 v[168:171], v142 offset:2048
	ds_read_b128 v[172:175], v142 offset:3072
	s_add_u32 s2, s28, 0xfffc0080
	s_addc_u32 s30, s29, -1
	s_cmp_eq_u32 s82, 12
	s_cselect_b32 s35, s21, s30
	s_cselect_b32 s34, s27, s2
	s_cselect_b32 s31, s19, s79
	s_cselect_b32 s30, s68, s78
	v_lshl_add_u64 v[142:143], s[28:29], 0, v[136:137]
	s_add_i32 m0, s45, 0xc000
	ds_read_b128 v[176:179], v147
	ds_read_b128 v[180:183], v147 offset:1024
	ds_read_b128 v[184:187], v147 offset:2048
	ds_read_b128 v[188:191], v147 offset:3072
	ds_read_b128 v[204:207], v147 offset:4096
	ds_read_b128 v[208:211], v147 offset:5120
	ds_read_b128 v[218:221], v147 offset:6144
	ds_read_b128 v[222:225], v147 offset:7168
	global_load_lds_dwordx4 v[142:143], off
	v_lshl_add_u64 v[142:143], s[28:29], 0, v[134:135]
	s_add_i32 m0, s45, 0xe000
	s_nop 0
	global_load_lds_dwordx4 v[142:143], off
	s_waitcnt vmcnt(8)
	s_waitcnt lgkmcnt(0)
	s_setprio 0
	s_barrier
	s_waitcnt lgkmcnt(0)
	v_mfma_f32_16x16x32_bf16 v[124:127], v[138:141], v[176:179], v[124:127]
	v_mfma_f32_16x16x32_bf16 v[120:123], v[152:155], v[176:179], v[120:123]
	v_mfma_f32_16x16x32_bf16 v[108:111], v[138:141], v[184:187], v[108:111]
	v_mfma_f32_16x16x32_bf16 v[104:107], v[152:155], v[184:187], v[104:107]
	v_mfma_f32_16x16x32_bf16 v[92:95], v[138:141], v[204:207], v[92:95]
	v_mfma_f32_16x16x32_bf16 v[88:91], v[152:155], v[204:207], v[88:91]
	v_mfma_f32_16x16x32_bf16 v[76:79], v[138:141], v[218:221], v[76:79]
	v_mfma_f32_16x16x32_bf16 v[72:75], v[152:155], v[218:221], v[72:75]
	v_mfma_f32_16x16x32_bf16 v[124:127], v[148:151], v[180:183], v[124:127]
	v_mfma_f32_16x16x32_bf16 v[120:123], v[156:159], v[180:183], v[120:123]
	v_mfma_f32_16x16x32_bf16 v[108:111], v[148:151], v[188:191], v[108:111]
	v_mfma_f32_16x16x32_bf16 v[104:107], v[156:159], v[188:191], v[104:107]
	v_mfma_f32_16x16x32_bf16 v[92:95], v[148:151], v[208:211], v[92:95]
	v_mfma_f32_16x16x32_bf16 v[88:91], v[156:159], v[208:211], v[88:91]
	v_mfma_f32_16x16x32_bf16 v[76:79], v[148:151], v[222:225], v[76:79]
	v_mfma_f32_16x16x32_bf16 v[72:75], v[156:159], v[222:225], v[72:75]
	v_mfma_f32_16x16x32_bf16 v[116:119], v[160:163], v[176:179], v[116:119]
	v_mfma_f32_16x16x32_bf16 v[112:115], v[168:171], v[176:179], v[112:115]
	v_mfma_f32_16x16x32_bf16 v[100:103], v[160:163], v[184:187], v[100:103]
	v_mfma_f32_16x16x32_bf16 v[96:99], v[168:171], v[184:187], v[96:99]
	v_mfma_f32_16x16x32_bf16 v[84:87], v[160:163], v[204:207], v[84:87]
	v_mfma_f32_16x16x32_bf16 v[80:83], v[168:171], v[204:207], v[80:83]
	v_mfma_f32_16x16x32_bf16 v[68:71], v[160:163], v[218:221], v[68:71]
	v_mfma_f32_16x16x32_bf16 v[64:67], v[168:171], v[218:221], v[64:67]
	v_mfma_f32_16x16x32_bf16 v[116:119], v[164:167], v[180:183], v[116:119]
	v_mfma_f32_16x16x32_bf16 v[112:115], v[172:175], v[180:183], v[112:115]
	v_mfma_f32_16x16x32_bf16 v[100:103], v[164:167], v[188:191], v[100:103]
	v_mfma_f32_16x16x32_bf16 v[96:99], v[172:175], v[188:191], v[96:99]
	v_mfma_f32_16x16x32_bf16 v[84:87], v[164:167], v[208:211], v[84:87]
	v_mfma_f32_16x16x32_bf16 v[80:83], v[172:175], v[208:211], v[80:83]
	v_mfma_f32_16x16x32_bf16 v[68:71], v[164:167], v[222:225], v[68:71]
	v_mfma_f32_16x16x32_bf16 v[64:67], v[172:175], v[222:225], v[64:67]
	s_barrier
	s_setprio 1
	s_mov_b32 m0, s40
	v_lshl_add_u64 v[142:143], s[30:31], 0, v[192:193]
	s_add_u32 s84, s30, 0x40000
	ds_read_b128 v[176:179], v147 offset:16384
	ds_read_b128 v[180:183], v147 offset:17408
	ds_read_b128 v[184:187], v147 offset:18432
	ds_read_b128 v[188:191], v147 offset:19456
	ds_read_b128 v[204:207], v147 offset:20480
	ds_read_b128 v[208:211], v147 offset:21504
	ds_read_b128 v[218:221], v147 offset:22528
	ds_read_b128 v[222:225], v147 offset:23552
	global_load_lds_dwordx4 v[142:143], off
	v_lshl_add_u64 v[194:195], s[30:31], 0, v[132:133]
	s_mov_b32 m0, s41
	s_addc_u32 s85, s31, 0
	global_load_lds_dwordx4 v[194:195], off
	v_lshl_add_u64 v[226:227], s[84:85], 0, v[192:193]
	s_mov_b32 m0, s43
	v_lshl_add_u64 v[228:229], s[34:35], 0, v[130:131]
	global_load_lds_dwordx4 v[226:227], off
	v_lshl_add_u64 v[226:227], s[84:85], 0, v[132:133]
	s_mov_b32 m0, s44
	s_nop 0
	global_load_lds_dwordx4 v[226:227], off
	v_lshl_add_u64 v[226:227], s[34:35], 0, v[128:129]
	s_mov_b32 m0, s45
	s_nop 0
	global_load_lds_dwordx4 v[226:227], off
	s_mov_b32 m0, s48
	s_nop 0
	global_load_lds_dwordx4 v[228:229], off
	s_waitcnt vmcnt(8)
	s_waitcnt lgkmcnt(0)
	s_setprio 0
	s_barrier
; #define PG8_STAGE(bufoff, gbase, voff) do { _Pragma("unroll") for (int _i = 0; _i < 2; ++_i) \
;         __builtin_amdgcn_global_load_lds((const unsigned*)((const char*)(gbase) + (voff)[_i]), (PG8_LAS unsigned*)(lds + (bufoff) + ldsw + _i * 8192), 16, 0, 0); } while (0)
; #define PG8_LDA(dst, b, h) do { _Pragma("unroll") for (int m = 0; m < 4; ++m) _Pragma("unroll") for (int k = 0; k < 2; ++k) dst[m][k] = *(const PG8_LAS bf16x8*)(lds + PG8_SA(b, h) + aoff + m * 2048 + k * 1024); } while (0)
; #define PG8_LDB(dst, b, h) do { _Pragma("unroll") for (int n = 0; n < 2; ++n) _Pragma("unroll") for (int k = 0; k < 2; ++k) dst[n][k] = *(const PG8_LAS bf16x8*)(lds + PG8_SB(b, h) + boff + n * 2048 + k * 1024); } while (0)
; #define PG8_MMA(ai, bj, At, Bt) do { __builtin_amdgcn_s_setprio(1); _Pragma("unroll") for (int m = 0; m < 4; ++m) _Pragma("unroll") for (int n = 0; n < 2; ++n) _Pragma("unroll") for (int k = 0; k < 2; ++k) \
;         acc[ai][bj][m][n] = __builtin_amdgcn_mfma_f32_16x16x32_bf16(Bt[n][k], At[m][k], acc[ai][bj][m][n], 0, 0, 0); __builtin_amdgcn_s_setprio(0); } while (0)
; #define PG8_WAIT_V(n) asm volatile("s_waitcnt vmcnt(" #n ")" ::: "memory")
; #define PG8_WAIT_L(n) asm volatile("s_waitcnt lgkmcnt(" #n ")" ::: "memory")
; #define PG8_BAR __builtin_amdgcn_s_barrier()
; #define PG8_SCHED __builtin_amdgcn_sched_barrier(0)
; template <class Epi, class Sched, bool ALIGN_EPI = false, bool SP2 = false>
; __device__ __forceinline__ void gemm_phase(PG8_LAS unsigned char* lds, const Gemm g, const Sched& S, const Epi& E) {
;     ...
;             PG8_WAIT_V(8); PG8_WAIT_L(0); PG8_BAR; PG8_MMA(1, 0, At, B0); PG8_MMA(1, 1, At, B1); PG8_BAR; PG8_SCHED;
;             PG8_LDB(B0, 1, 0); PG8_LDB(B1, 1, 1); PG8_SCHED; PG8_LDA(At, 1, 0); PG8_STAGE(PG8_SA(0, 1), a2 + hstepA, voffA);
;             PG8_WAIT_V(8); PG8_WAIT_L(0); PG8_BAR; PG8_MMA(0, 0, At, B0); PG8_MMA(0, 1, At, B1); PG8_BAR; PG8_SCHED;
	s_waitcnt lgkmcnt(0)
	v_mfma_f32_16x16x32_bf16 v[60:63], v[138:141], v[176:179], v[60:63]
	v_mfma_f32_16x16x32_bf16 v[56:59], v[152:155], v[176:179], v[56:59]
	v_mfma_f32_16x16x32_bf16 v[44:47], v[138:141], v[184:187], v[44:47]
	v_mfma_f32_16x16x32_bf16 v[40:43], v[152:155], v[184:187], v[40:43]
	v_mfma_f32_16x16x32_bf16 v[28:31], v[138:141], v[204:207], v[28:31]
	v_mfma_f32_16x16x32_bf16 v[24:27], v[152:155], v[204:207], v[24:27]
	v_mfma_f32_16x16x32_bf16 v[12:15], v[138:141], v[218:221], v[12:15]
	v_mfma_f32_16x16x32_bf16 v[8:11], v[152:155], v[218:221], v[8:11]
	v_mfma_f32_16x16x32_bf16 v[60:63], v[148:151], v[180:183], v[60:63]
	v_mfma_f32_16x16x32_bf16 v[56:59], v[156:159], v[180:183], v[56:59]
	v_mfma_f32_16x16x32_bf16 v[44:47], v[148:151], v[188:191], v[44:47]
	v_mfma_f32_16x16x32_bf16 v[40:43], v[156:159], v[188:191], v[40:43]
	v_mfma_f32_16x16x32_bf16 v[28:31], v[148:151], v[208:211], v[28:31]
	v_mfma_f32_16x16x32_bf16 v[24:27], v[156:159], v[208:211], v[24:27]
	v_mfma_f32_16x16x32_bf16 v[12:15], v[148:151], v[222:225], v[12:15]
	v_mfma_f32_16x16x32_bf16 v[8:11], v[156:159], v[222:225], v[8:11]
	v_mfma_f32_16x16x32_bf16 v[52:55], v[160:163], v[176:179], v[52:55]
	v_mfma_f32_16x16x32_bf16 v[48:51], v[168:171], v[176:179], v[48:51]
	v_mfma_f32_16x16x32_bf16 v[36:39], v[160:163], v[184:187], v[36:39]
	v_mfma_f32_16x16x32_bf16 v[32:35], v[168:171], v[184:187], v[32:35]
	v_mfma_f32_16x16x32_bf16 v[20:23], v[160:163], v[204:207], v[20:23]
	v_mfma_f32_16x16x32_bf16 v[16:19], v[168:171], v[204:207], v[16:19]
	v_mfma_f32_16x16x32_bf16 v[4:7], v[160:163], v[218:221], v[4:7]
	v_mfma_f32_16x16x32_bf16 v[0:3], v[168:171], v[218:221], v[0:3]
	v_mfma_f32_16x16x32_bf16 v[52:55], v[164:167], v[180:183], v[52:55]
	v_mfma_f32_16x16x32_bf16 v[48:51], v[172:175], v[180:183], v[48:51]
	v_mfma_f32_16x16x32_bf16 v[36:39], v[164:167], v[188:191], v[36:39]
	v_mfma_f32_16x16x32_bf16 v[32:35], v[172:175], v[188:191], v[32:35]
	v_mfma_f32_16x16x32_bf16 v[20:23], v[164:167], v[208:211], v[20:23]
	v_mfma_f32_16x16x32_bf16 v[16:19], v[172:175], v[208:211], v[16:19]
	v_mfma_f32_16x16x32_bf16 v[4:7], v[164:167], v[222:225], v[4:7]
	v_mfma_f32_16x16x32_bf16 v[0:3], v[172:175], v[222:225], v[0:3]
	s_barrier
	s_setprio 1
	v_add_u32_e32 v156, s60, v145
	v_add_u32_e32 v172, s67, v145
	ds_read_b128 v[138:141], v156
	ds_read_b128 v[148:151], v156 offset:1024
	ds_read_b128 v[152:155], v156 offset:2048
	ds_read_b128 v[156:159], v156 offset:3072
	ds_read_b128 v[160:163], v172
	ds_read_b128 v[164:167], v172 offset:1024
	ds_read_b128 v[168:171], v172 offset:2048
	ds_read_b128 v[172:175], v172 offset:3072
	s_add_u32 s34, s34, 0x40000
	s_addc_u32 s35, s35, 0
	s_mov_b32 m0, s49
	v_lshl_add_u64 v[230:231], s[34:35], 0, v[128:129]
	ds_read_b128 v[176:179], v147 offset:32768
	ds_read_b128 v[180:183], v147 offset:33792
	ds_read_b128 v[184:187], v147 offset:34816
	ds_read_b128 v[188:191], v147 offset:35840
	ds_read_b128 v[204:207], v147 offset:36864
	ds_read_b128 v[208:211], v147 offset:37888
	ds_read_b128 v[218:221], v147 offset:38912
	ds_read_b128 v[222:225], v147 offset:39936
	global_load_lds_dwordx4 v[230:231], off
	v_lshl_add_u64 v[230:231], s[34:35], 0, v[130:131]
	s_mov_b32 m0, s50
	s_nop 0
	global_load_lds_dwordx4 v[230:231], off
	s_waitcnt vmcnt(8)
	s_waitcnt lgkmcnt(0)
	s_setprio 0
	s_barrier
	s_waitcnt lgkmcnt(0)
	v_mfma_f32_16x16x32_bf16 v[124:127], v[138:141], v[176:179], v[124:127]
	v_mfma_f32_16x16x32_bf16 v[120:123], v[152:155], v[176:179], v[120:123]
	v_mfma_f32_16x16x32_bf16 v[108:111], v[138:141], v[184:187], v[108:111]
	v_mfma_f32_16x16x32_bf16 v[104:107], v[152:155], v[184:187], v[104:107]
	v_mfma_f32_16x16x32_bf16 v[92:95], v[138:141], v[204:207], v[92:95]
	v_mfma_f32_16x16x32_bf16 v[88:91], v[152:155], v[204:207], v[88:91]
	v_mfma_f32_16x16x32_bf16 v[76:79], v[138:141], v[218:221], v[76:79]
	v_mfma_f32_16x16x32_bf16 v[72:75], v[152:155], v[218:221], v[72:75]
	v_mfma_f32_16x16x32_bf16 v[124:127], v[148:151], v[180:183], v[124:127]
	v_mfma_f32_16x16x32_bf16 v[120:123], v[156:159], v[180:183], v[120:123]
	v_mfma_f32_16x16x32_bf16 v[108:111], v[148:151], v[188:191], v[108:111]
	v_mfma_f32_16x16x32_bf16 v[104:107], v[156:159], v[188:191], v[104:107]
	v_mfma_f32_16x16x32_bf16 v[92:95], v[148:151], v[208:211], v[92:95]
	v_mfma_f32_16x16x32_bf16 v[88:91], v[156:159], v[208:211], v[88:91]
	v_mfma_f32_16x16x32_bf16 v[76:79], v[148:151], v[222:225], v[76:79]
	v_mfma_f32_16x16x32_bf16 v[72:75], v[156:159], v[222:225], v[72:75]
	v_mfma_f32_16x16x32_bf16 v[116:119], v[160:163], v[176:179], v[116:119]
	v_mfma_f32_16x16x32_bf16 v[112:115], v[168:171], v[176:179], v[112:115]
	v_mfma_f32_16x16x32_bf16 v[100:103], v[160:163], v[184:187], v[100:103]
	v_mfma_f32_16x16x32_bf16 v[96:99], v[168:171], v[184:187], v[96:99]
	v_mfma_f32_16x16x32_bf16 v[84:87], v[160:163], v[204:207], v[84:87]
	v_mfma_f32_16x16x32_bf16 v[80:83], v[168:171], v[204:207], v[80:83]
	v_mfma_f32_16x16x32_bf16 v[68:71], v[160:163], v[218:221], v[68:71]
	v_mfma_f32_16x16x32_bf16 v[64:67], v[168:171], v[218:221], v[64:67]
	v_mfma_f32_16x16x32_bf16 v[116:119], v[164:167], v[180:183], v[116:119]
	v_mfma_f32_16x16x32_bf16 v[112:115], v[172:175], v[180:183], v[112:115]
	v_mfma_f32_16x16x32_bf16 v[100:103], v[164:167], v[188:191], v[100:103]
	v_mfma_f32_16x16x32_bf16 v[96:99], v[172:175], v[188:191], v[96:99]
	v_mfma_f32_16x16x32_bf16 v[84:87], v[164:167], v[208:211], v[84:87]
	v_mfma_f32_16x16x32_bf16 v[80:83], v[172:175], v[208:211], v[80:83]
	v_mfma_f32_16x16x32_bf16 v[68:71], v[164:167], v[222:225], v[68:71]
	v_mfma_f32_16x16x32_bf16 v[64:67], v[172:175], v[222:225], v[64:67]
	s_barrier
; #define PG8_STAGE(bufoff, gbase, voff) do { _Pragma("unroll") for (int _i = 0; _i < 2; ++_i) \
;         __builtin_amdgcn_global_load_lds((const unsigned*)((const char*)(gbase) + (voff)[_i]), (PG8_LAS unsigned*)(lds + (bufoff) + ldsw + _i * 8192), 16, 0, 0); } while (0)
; #define PG8_LDA(dst, b, h) do { _Pragma("unroll") for (int m = 0; m < 4; ++m) _Pragma("unroll") for (int k = 0; k < 2; ++k) dst[m][k] = *(const PG8_LAS bf16x8*)(lds + PG8_SA(b, h) + aoff + m * 2048 + k * 1024); } while (0)
; #define PG8_MMA(ai, bj, At, Bt) do { __builtin_amdgcn_s_setprio(1); _Pragma("unroll") for (int m = 0; m < 4; ++m) _Pragma("unroll") for (int n = 0; n < 2; ++n) _Pragma("unroll") for (int k = 0; k < 2; ++k) \
;         acc[ai][bj][m][n] = __builtin_amdgcn_mfma_f32_16x16x32_bf16(Bt[n][k], At[m][k], acc[ai][bj][m][n], 0, 0, 0); __builtin_amdgcn_s_setprio(0); } while (0)
; #define PG8_WAIT_V(n) asm volatile("s_waitcnt vmcnt(" #n ")" ::: "memory")
; #define PG8_WAIT_L(n) asm volatile("s_waitcnt lgkmcnt(" #n ")" ::: "memory")
; #define PG8_BAR __builtin_amdgcn_s_barrier()
; #define PG8_SCHED __builtin_amdgcn_sched_barrier(0)
; template <class Epi, class Sched, bool ALIGN_EPI = false, bool SP2 = false>
; __device__ __forceinline__ void gemm_phase(PG8_LAS unsigned char* lds, const Gemm g, const Sched& S, const Epi& E) {
;     ...
;             PG8_LDA(At, 1, 1); PG8_STAGE(PG8_SB(1, 0), b3, voffB); PG8_STAGE(PG8_SB(1, 1), b3 + hstepB, voffB); PG8_STAGE(PG8_SA(1, 0), a3, voffA);
;             PG8_WAIT_V(8); PG8_WAIT_L(0); PG8_BAR; PG8_MMA(1, 0, At, B0); PG8_MMA(1, 1, At, B1); PG8_BAR; PG8_SCHED;
;     __device__ __forceinline__ void operator()(const f32x4 (&acc)[2][2][4][2], const pg8::Unit& u, int wr, int wc, int fr, int fq) const {
;     ...
; #pragma unroll
;         for (int ai = 0; ai < 2; ++ai)
; #pragma unroll
;             for (int m = 0; m < 4; ++m) {
;                 const int row = row0 + ai * 128 + m * 16; float ss = 0.f;
; #pragma unroll
;                 for (int bj = 0; bj < 2; ++bj) {
;                     const size_t off = (size_t)row * DM + col0 + bj * 128;
;                     const v4u b = *(const v4u*)(xb + off);
	s_setprio 1
	s_mov_b32 m0, s61
	v_lshl_add_u64 v[142:143], v[142:143], 0, s[76:77]
	s_add_u32 s30, s30, 0x40080
	ds_read_b128 v[176:179], v147 offset:49152
	ds_read_b128 v[180:183], v147 offset:50176
	ds_read_b128 v[184:187], v147 offset:51200
	ds_read_b128 v[188:191], v147 offset:52224
	ds_read_b128 v[204:207], v147 offset:53248
	ds_read_b128 v[208:211], v147 offset:54272
	ds_read_b128 v[218:221], v147 offset:55296
	ds_read_b128 v[222:225], v147 offset:56320
	global_load_lds_dwordx4 v[142:143], off
	v_lshl_add_u64 v[142:143], v[194:195], 0, s[76:77]
	s_mov_b32 m0, s64
	s_addc_u32 s31, s31, 0
	global_load_lds_dwordx4 v[142:143], off
	v_lshl_add_u64 v[142:143], s[30:31], 0, v[192:193]
	s_mov_b32 m0, s70
	s_nop 0
	global_load_lds_dwordx4 v[142:143], off
	v_lshl_add_u64 v[142:143], s[30:31], 0, v[132:133]
	s_mov_b32 m0, s71
	s_nop 0
	global_load_lds_dwordx4 v[142:143], off
	v_lshl_add_u64 v[142:143], v[226:227], 0, s[76:77]
	s_mov_b32 m0, s65
	s_nop 0
	global_load_lds_dwordx4 v[142:143], off
	v_lshl_add_u64 v[142:143], v[228:229], 0, s[76:77]
	s_mov_b32 m0, s66
	s_nop 0
	global_load_lds_dwordx4 v[142:143], off
	s_waitcnt vmcnt(8)
	s_waitcnt lgkmcnt(0)
	s_setprio 0
	s_barrier
	s_waitcnt lgkmcnt(0)
	v_mfma_f32_16x16x32_bf16 v[60:63], v[138:141], v[176:179], v[60:63]
	v_mfma_f32_16x16x32_bf16 v[56:59], v[152:155], v[176:179], v[56:59]
	v_mfma_f32_16x16x32_bf16 v[44:47], v[138:141], v[184:187], v[44:47]
	v_mfma_f32_16x16x32_bf16 v[40:43], v[152:155], v[184:187], v[40:43]
	v_mfma_f32_16x16x32_bf16 v[28:31], v[138:141], v[204:207], v[28:31]
	v_mfma_f32_16x16x32_bf16 v[24:27], v[152:155], v[204:207], v[24:27]
	v_mfma_f32_16x16x32_bf16 v[12:15], v[138:141], v[218:221], v[12:15]
	v_mfma_f32_16x16x32_bf16 v[8:11], v[152:155], v[218:221], v[8:11]
	v_mfma_f32_16x16x32_bf16 v[60:63], v[148:151], v[180:183], v[60:63]
	v_mfma_f32_16x16x32_bf16 v[56:59], v[156:159], v[180:183], v[56:59]
	v_mfma_f32_16x16x32_bf16 v[44:47], v[148:151], v[188:191], v[44:47]
	v_mfma_f32_16x16x32_bf16 v[40:43], v[156:159], v[188:191], v[40:43]
	v_mfma_f32_16x16x32_bf16 v[28:31], v[148:151], v[208:211], v[28:31]
	v_mfma_f32_16x16x32_bf16 v[24:27], v[156:159], v[208:211], v[24:27]
	v_mfma_f32_16x16x32_bf16 v[12:15], v[148:151], v[222:225], v[12:15]
	v_mfma_f32_16x16x32_bf16 v[8:11], v[156:159], v[222:225], v[8:11]
	v_mfma_f32_16x16x32_bf16 v[52:55], v[160:163], v[176:179], v[52:55]
	v_mfma_f32_16x16x32_bf16 v[48:51], v[168:171], v[176:179], v[48:51]
	v_mfma_f32_16x16x32_bf16 v[36:39], v[160:163], v[184:187], v[36:39]
	v_mfma_f32_16x16x32_bf16 v[32:35], v[168:171], v[184:187], v[32:35]
	v_mfma_f32_16x16x32_bf16 v[20:23], v[160:163], v[204:207], v[20:23]
	v_mfma_f32_16x16x32_bf16 v[16:19], v[168:171], v[204:207], v[16:19]
	v_mfma_f32_16x16x32_bf16 v[4:7], v[160:163], v[218:221], v[4:7]
	v_mfma_f32_16x16x32_bf16 v[0:3], v[168:171], v[218:221], v[0:3]
	v_mfma_f32_16x16x32_bf16 v[52:55], v[164:167], v[180:183], v[52:55]
	v_mfma_f32_16x16x32_bf16 v[48:51], v[172:175], v[180:183], v[48:51]
	v_mfma_f32_16x16x32_bf16 v[36:39], v[164:167], v[188:191], v[36:39]
	v_mfma_f32_16x16x32_bf16 v[32:35], v[172:175], v[188:191], v[32:35]
	v_mfma_f32_16x16x32_bf16 v[20:23], v[164:167], v[208:211], v[20:23]
	v_mfma_f32_16x16x32_bf16 v[16:19], v[172:175], v[208:211], v[16:19]
	v_mfma_f32_16x16x32_bf16 v[4:7], v[164:167], v[222:225], v[4:7]
	v_mfma_f32_16x16x32_bf16 v[0:3], v[172:175], v[222:225], v[0:3]
	s_barrier
	s_setprio 1
	s_add_i32 s82, s82, 2
	s_add_u32 s78, s78, 0x100
	s_addc_u32 s79, s79, 0
	s_add_u32 s28, s28, 0x100
	s_addc_u32 s29, s29, 0
	s_cmp_gt_u32 s82, 13
	s_cbranch_scc0 .LBB0_1121
	s_setprio 0
	v_lshl_add_u32 v159, s26, 8, v144
	v_lshl_or_b32 v158, s8, 8, v146
	v_lshlrev_b32_e32 v159, 11, v159
	v_lshl_add_u32 v159, v158, 1, v159
	v_add_u32_e32 v218, 0x8000, v159
	v_add_u32_e32 v219, 0x10000, v159
	v_add_u32_e32 v240, 0x18000, v159
	v_add_u32_e32 v241, 0x40000, v159
	v_add_u32_e32 v245, 0x48000, v159
	v_add_u32_e32 v246, 0x50000, v159
	v_add_u32_e32 v247, 0x58000, v159
	global_load_dwordx4 v[160:163], v159, s[12:13]
	global_load_dwordx4 v[164:167], v159, s[12:13] offset:256
	global_load_dwordx4 v[168:171], v218, s[12:13]
	global_load_dwordx4 v[172:175], v218, s[12:13] offset:256
	global_load_dwordx4 v[176:179], v219, s[12:13]
	global_load_dwordx4 v[180:183], v219, s[12:13] offset:256
	global_load_dwordx4 v[184:187], v240, s[12:13]
	global_load_dwordx4 v[188:191], v240, s[12:13] offset:256
	global_load_dwordx4 v[204:207], v241, s[12:13]
	global_load_dwordx4 v[208:211], v241, s[12:13] offset:256
	global_load_dwordx4 v[220:223], v245, s[12:13]
	global_load_dwordx4 v[224:227], v245, s[12:13] offset:256
	global_load_dwordx4 v[228:231], v246, s[12:13]
	global_load_dwordx4 v[232:235], v246, s[12:13] offset:256
	global_load_dwordx4 v[236:239], v247, s[12:13]
	global_load_dwordx4 v[248:251], v247, s[12:13] offset:256
	s_and_b64 vcc, exec, s[16:17]
	s_cbranch_vccz .LBB0_1124
	s_barrier

; #define PG8_STAGE(bufoff, gbase, voff) do { _Pragma("unroll") for (int _i = 0; _i < 2; ++_i) \
;         __builtin_amdgcn_global_load_lds((const unsigned*)((const char*)(gbase) + (voff)[_i]), (PG8_LAS unsigned*)(lds + (bufoff) + ldsw + _i * 8192), 16, 0, 0); } while (0)
; #define PG8_LDA(dst, b, h) do { _Pragma("unroll") for (int m = 0; m < 4; ++m) _Pragma("unroll") for (int k = 0; k < 2; ++k) dst[m][k] = *(const PG8_LAS bf16x8*)(lds + PG8_SA(b, h) + aoff + m * 2048 + k * 1024); } while (0)
; #define PG8_LDB(dst, b, h) do { _Pragma("unroll") for (int n = 0; n < 2; ++n) _Pragma("unroll") for (int k = 0; k < 2; ++k) dst[n][k] = *(const PG8_LAS bf16x8*)(lds + PG8_SB(b, h) + boff + n * 2048 + k * 1024); } while (0)
; #define PG8_MMA(ai, bj, At, Bt) do { __builtin_amdgcn_s_setprio(1); _Pragma("unroll") for (int m = 0; m < 4; ++m) _Pragma("unroll") for (int n = 0; n < 2; ++n) _Pragma("unroll") for (int k = 0; k < 2; ++k) \
;         acc[ai][bj][m][n] = __builtin_amdgcn_mfma_f32_16x16x32_bf16(Bt[n][k], At[m][k], acc[ai][bj][m][n], 0, 0, 0); __builtin_amdgcn_s_setprio(0); } while (0)
; #define PG8_WAIT_V(n) asm volatile("s_waitcnt vmcnt(" #n ")" ::: "memory")
; #define PG8_WAIT_L(n) asm volatile("s_waitcnt lgkmcnt(" #n ")" ::: "memory")
; #define PG8_BAR __builtin_amdgcn_s_barrier()
; #define PG8_SCHED __builtin_amdgcn_sched_barrier(0)
; template <class Epi, class Sched, bool ALIGN_EPI = false, bool SP2 = false>
; __device__ __forceinline__ void gemm_phase(PG8_LAS unsigned char* lds, const Gemm g, const Sched& S, const Epi& E) {
;     ...
;             PG8_LDB(B0, 0, 0); PG8_LDB(B1, 0, 1); PG8_SCHED; PG8_LDA(At, 0, 0); PG8_STAGE(PG8_SA(1, 1), a1 + hstepA, voffA);
;             PG8_WAIT_V(8); PG8_WAIT_L(0); PG8_BAR; PG8_MMA(0, 0, At, B0); PG8_MMA(0, 1, At, B1); PG8_BAR; PG8_SCHED;
;             PG8_LDA(At, 0, 1); PG8_STAGE(PG8_SB(0, 0), b2, voffB); PG8_STAGE(PG8_SB(0, 1), b2 + hstepB, voffB); PG8_STAGE(PG8_SA(0, 0), a2, voffA);
;             PG8_WAIT_V(8); PG8_WAIT_L(0); PG8_BAR; PG8_MMA(1, 0, At, B0); PG8_MMA(1, 1, At, B1); PG8_BAR; PG8_SCHED;
.LBB0_1221:
	s_setprio 1
	v_add_u32_e32 v156, s21, v149
	v_add_u32_e32 v172, s37, v149
	ds_read_b128 v[140:143], v156
	ds_read_b128 v[144:147], v156 offset:1024
	ds_read_b128 v[152:155], v156 offset:2048
	ds_read_b128 v[156:159], v156 offset:3072
	ds_read_b128 v[160:163], v172
	ds_read_b128 v[164:167], v172 offset:1024
	ds_read_b128 v[168:171], v172 offset:2048
	ds_read_b128 v[172:175], v172 offset:3072
	s_add_u32 s2, s22, 0xfffc0080
	s_addc_u32 s24, s23, -1
	s_cmp_eq_u32 s72, 12
	s_cselect_b32 s27, s15, s24
	s_cselect_b32 s26, s67, s2
	s_cselect_b32 s25, s13, s71
	s_cselect_b32 s24, s68, s70
	v_lshl_add_u64 v[194:195], s[22:23], 0, v[138:139]
	s_add_i32 m0, s40, 0xc000
	ds_read_b128 v[176:179], v151
	ds_read_b128 v[180:183], v151 offset:1024
	ds_read_b128 v[184:187], v151 offset:2048
	ds_read_b128 v[188:191], v151 offset:3072
	ds_read_b128 v[204:207], v151 offset:4096
	ds_read_b128 v[208:211], v151 offset:5120
	ds_read_b128 v[218:221], v151 offset:6144
	ds_read_b128 v[222:225], v151 offset:7168
	global_load_lds_dwordx4 v[194:195], off
	v_lshl_add_u64 v[194:195], s[22:23], 0, v[136:137]
	s_add_i32 m0, s40, 0xe000
	s_nop 0
	global_load_lds_dwordx4 v[194:195], off
	s_waitcnt vmcnt(8)
	s_waitcnt lgkmcnt(0)
	s_setprio 0
	s_barrier
	s_waitcnt lgkmcnt(0)
	v_mfma_f32_16x16x32_bf16 v[116:119], v[140:143], v[176:179], v[116:119]
	v_mfma_f32_16x16x32_bf16 v[112:115], v[152:155], v[176:179], v[112:115]
	v_mfma_f32_16x16x32_bf16 v[108:111], v[140:143], v[184:187], v[108:111]
	v_mfma_f32_16x16x32_bf16 v[104:107], v[152:155], v[184:187], v[104:107]
	v_mfma_f32_16x16x32_bf16 v[92:95], v[140:143], v[204:207], v[92:95]
	v_mfma_f32_16x16x32_bf16 v[88:91], v[152:155], v[204:207], v[88:91]
	v_mfma_f32_16x16x32_bf16 v[76:79], v[140:143], v[218:221], v[76:79]
	v_mfma_f32_16x16x32_bf16 v[72:75], v[152:155], v[218:221], v[72:75]
	v_mfma_f32_16x16x32_bf16 v[116:119], v[144:147], v[180:183], v[116:119]
	v_mfma_f32_16x16x32_bf16 v[112:115], v[156:159], v[180:183], v[112:115]
	v_mfma_f32_16x16x32_bf16 v[108:111], v[144:147], v[188:191], v[108:111]
	v_mfma_f32_16x16x32_bf16 v[104:107], v[156:159], v[188:191], v[104:107]
	v_mfma_f32_16x16x32_bf16 v[92:95], v[144:147], v[208:211], v[92:95]
	v_mfma_f32_16x16x32_bf16 v[88:91], v[156:159], v[208:211], v[88:91]
	v_mfma_f32_16x16x32_bf16 v[76:79], v[144:147], v[222:225], v[76:79]
	v_mfma_f32_16x16x32_bf16 v[72:75], v[156:159], v[222:225], v[72:75]
	v_mfma_f32_16x16x32_bf16 v[124:127], v[160:163], v[176:179], v[124:127]
	v_mfma_f32_16x16x32_bf16 v[120:123], v[168:171], v[176:179], v[120:123]
	v_mfma_f32_16x16x32_bf16 v[100:103], v[160:163], v[184:187], v[100:103]
	v_mfma_f32_16x16x32_bf16 v[96:99], v[168:171], v[184:187], v[96:99]
	v_mfma_f32_16x16x32_bf16 v[84:87], v[160:163], v[204:207], v[84:87]
	v_mfma_f32_16x16x32_bf16 v[80:83], v[168:171], v[204:207], v[80:83]
	v_mfma_f32_16x16x32_bf16 v[68:71], v[160:163], v[218:221], v[68:71]
	v_mfma_f32_16x16x32_bf16 v[64:67], v[168:171], v[218:221], v[64:67]
	v_mfma_f32_16x16x32_bf16 v[124:127], v[164:167], v[180:183], v[124:127]
	v_mfma_f32_16x16x32_bf16 v[120:123], v[172:175], v[180:183], v[120:123]
	v_mfma_f32_16x16x32_bf16 v[100:103], v[164:167], v[188:191], v[100:103]
	v_mfma_f32_16x16x32_bf16 v[96:99], v[172:175], v[188:191], v[96:99]
	v_mfma_f32_16x16x32_bf16 v[84:87], v[164:167], v[208:211], v[84:87]
	v_mfma_f32_16x16x32_bf16 v[80:83], v[172:175], v[208:211], v[80:83]
	v_mfma_f32_16x16x32_bf16 v[68:71], v[164:167], v[222:225], v[68:71]
	v_mfma_f32_16x16x32_bf16 v[64:67], v[172:175], v[222:225], v[64:67]
	s_barrier
	s_setprio 1
	s_mov_b32 m0, s35
	v_lshl_add_u64 v[194:195], s[24:25], 0, v[192:193]
	s_add_u32 s74, s24, 0x40000
	ds_read_b128 v[176:179], v151 offset:16384
	ds_read_b128 v[180:183], v151 offset:17408
	ds_read_b128 v[184:187], v151 offset:18432
	ds_read_b128 v[188:191], v151 offset:19456
	ds_read_b128 v[204:207], v151 offset:20480
	ds_read_b128 v[208:211], v151 offset:21504
	ds_read_b128 v[218:221], v151 offset:22528
	ds_read_b128 v[222:225], v151 offset:23552
	global_load_lds_dwordx4 v[194:195], off
	v_lshl_add_u64 v[226:227], s[24:25], 0, v[128:129]
	s_mov_b32 m0, s36
	s_addc_u32 s75, s25, 0
	global_load_lds_dwordx4 v[226:227], off
	v_lshl_add_u64 v[228:229], s[74:75], 0, v[192:193]
	s_mov_b32 m0, s38
	v_lshl_add_u64 v[230:231], s[26:27], 0, v[130:131]
	global_load_lds_dwordx4 v[228:229], off
	v_lshl_add_u64 v[228:229], s[74:75], 0, v[128:129]
	s_mov_b32 m0, s39
	s_nop 0
	global_load_lds_dwordx4 v[228:229], off
	v_lshl_add_u64 v[228:229], s[26:27], 0, v[132:133]
	s_mov_b32 m0, s40
	s_nop 0
	global_load_lds_dwordx4 v[228:229], off
	s_mov_b32 m0, s41
	s_nop 0
	global_load_lds_dwordx4 v[230:231], off
	s_waitcnt vmcnt(8)
	s_waitcnt lgkmcnt(0)
	s_setprio 0
	s_barrier
; #define PG8_STAGE(bufoff, gbase, voff) do { _Pragma("unroll") for (int _i = 0; _i < 2; ++_i) \
;         __builtin_amdgcn_global_load_lds((const unsigned*)((const char*)(gbase) + (voff)[_i]), (PG8_LAS unsigned*)(lds + (bufoff) + ldsw + _i * 8192), 16, 0, 0); } while (0)
; #define PG8_LDA(dst, b, h) do { _Pragma("unroll") for (int m = 0; m < 4; ++m) _Pragma("unroll") for (int k = 0; k < 2; ++k) dst[m][k] = *(const PG8_LAS bf16x8*)(lds + PG8_SA(b, h) + aoff + m * 2048 + k * 1024); } while (0)
; #define PG8_LDB(dst, b, h) do { _Pragma("unroll") for (int n = 0; n < 2; ++n) _Pragma("unroll") for (int k = 0; k < 2; ++k) dst[n][k] = *(const PG8_LAS bf16x8*)(lds + PG8_SB(b, h) + boff + n * 2048 + k * 1024); } while (0)
; #define PG8_MMA(ai, bj, At, Bt) do { __builtin_amdgcn_s_setprio(1); _Pragma("unroll") for (int m = 0; m < 4; ++m) _Pragma("unroll") for (int n = 0; n < 2; ++n) _Pragma("unroll") for (int k = 0; k < 2; ++k) \
;         acc[ai][bj][m][n] = __builtin_amdgcn_mfma_f32_16x16x32_bf16(Bt[n][k], At[m][k], acc[ai][bj][m][n], 0, 0, 0); __builtin_amdgcn_s_setprio(0); } while (0)
; #define PG8_WAIT_V(n) asm volatile("s_waitcnt vmcnt(" #n ")" ::: "memory")
; #define PG8_WAIT_L(n) asm volatile("s_waitcnt lgkmcnt(" #n ")" ::: "memory")
; #define PG8_BAR __builtin_amdgcn_s_barrier()
; #define PG8_SCHED __builtin_amdgcn_sched_barrier(0)
; template <class Epi, class Sched, bool ALIGN_EPI = false, bool SP2 = false>
; __device__ __forceinline__ void gemm_phase(PG8_LAS unsigned char* lds, const Gemm g, const Sched& S, const Epi& E) {
;     ...
;             PG8_WAIT_V(8); PG8_WAIT_L(0); PG8_BAR; PG8_MMA(1, 0, At, B0); PG8_MMA(1, 1, At, B1); PG8_BAR; PG8_SCHED;
;             PG8_LDB(B0, 1, 0); PG8_LDB(B1, 1, 1); PG8_SCHED; PG8_LDA(At, 1, 0); PG8_STAGE(PG8_SA(0, 1), a2 + hstepA, voffA);
;             PG8_WAIT_V(8); PG8_WAIT_L(0); PG8_BAR; PG8_MMA(0, 0, At, B0); PG8_MMA(0, 1, At, B1); PG8_BAR; PG8_SCHED;
	s_waitcnt lgkmcnt(0)
	v_mfma_f32_16x16x32_bf16 v[60:63], v[140:143], v[176:179], v[60:63]
	v_mfma_f32_16x16x32_bf16 v[56:59], v[152:155], v[176:179], v[56:59]
	v_mfma_f32_16x16x32_bf16 v[44:47], v[140:143], v[184:187], v[44:47]
	v_mfma_f32_16x16x32_bf16 v[40:43], v[152:155], v[184:187], v[40:43]
	v_mfma_f32_16x16x32_bf16 v[28:31], v[140:143], v[204:207], v[28:31]
	v_mfma_f32_16x16x32_bf16 v[24:27], v[152:155], v[204:207], v[24:27]
	v_mfma_f32_16x16x32_bf16 v[12:15], v[140:143], v[218:221], v[12:15]
	v_mfma_f32_16x16x32_bf16 v[8:11], v[152:155], v[218:221], v[8:11]
	v_mfma_f32_16x16x32_bf16 v[60:63], v[144:147], v[180:183], v[60:63]
	v_mfma_f32_16x16x32_bf16 v[56:59], v[156:159], v[180:183], v[56:59]
	v_mfma_f32_16x16x32_bf16 v[44:47], v[144:147], v[188:191], v[44:47]
	v_mfma_f32_16x16x32_bf16 v[40:43], v[156:159], v[188:191], v[40:43]
	v_mfma_f32_16x16x32_bf16 v[28:31], v[144:147], v[208:211], v[28:31]
	v_mfma_f32_16x16x32_bf16 v[24:27], v[156:159], v[208:211], v[24:27]
	v_mfma_f32_16x16x32_bf16 v[12:15], v[144:147], v[222:225], v[12:15]
	v_mfma_f32_16x16x32_bf16 v[8:11], v[156:159], v[222:225], v[8:11]
	v_mfma_f32_16x16x32_bf16 v[52:55], v[160:163], v[176:179], v[52:55]
	v_mfma_f32_16x16x32_bf16 v[48:51], v[168:171], v[176:179], v[48:51]
	v_mfma_f32_16x16x32_bf16 v[36:39], v[160:163], v[184:187], v[36:39]
	v_mfma_f32_16x16x32_bf16 v[32:35], v[168:171], v[184:187], v[32:35]
	v_mfma_f32_16x16x32_bf16 v[20:23], v[160:163], v[204:207], v[20:23]
	v_mfma_f32_16x16x32_bf16 v[16:19], v[168:171], v[204:207], v[16:19]
	v_mfma_f32_16x16x32_bf16 v[4:7], v[160:163], v[218:221], v[4:7]
	v_mfma_f32_16x16x32_bf16 v[0:3], v[168:171], v[218:221], v[0:3]
	v_mfma_f32_16x16x32_bf16 v[52:55], v[164:167], v[180:183], v[52:55]
	v_mfma_f32_16x16x32_bf16 v[48:51], v[172:175], v[180:183], v[48:51]
	v_mfma_f32_16x16x32_bf16 v[36:39], v[164:167], v[188:191], v[36:39]
	v_mfma_f32_16x16x32_bf16 v[32:35], v[172:175], v[188:191], v[32:35]
	v_mfma_f32_16x16x32_bf16 v[20:23], v[164:167], v[208:211], v[20:23]
	v_mfma_f32_16x16x32_bf16 v[16:19], v[172:175], v[208:211], v[16:19]
	v_mfma_f32_16x16x32_bf16 v[4:7], v[164:167], v[222:225], v[4:7]
	v_mfma_f32_16x16x32_bf16 v[0:3], v[172:175], v[222:225], v[0:3]
	s_barrier
	s_setprio 1
	v_add_u32_e32 v156, s44, v149
	v_add_u32_e32 v172, s51, v149
	ds_read_b128 v[140:143], v156
	ds_read_b128 v[144:147], v156 offset:1024
	ds_read_b128 v[152:155], v156 offset:2048
	ds_read_b128 v[156:159], v156 offset:3072
	ds_read_b128 v[160:163], v172
	ds_read_b128 v[164:167], v172 offset:1024
	ds_read_b128 v[168:171], v172 offset:2048
	ds_read_b128 v[172:175], v172 offset:3072
	s_add_u32 s26, s26, 0x40000
	s_addc_u32 s27, s27, 0
	s_mov_b32 m0, s42
	v_lshl_add_u64 v[232:233], s[26:27], 0, v[132:133]
	ds_read_b128 v[176:179], v151 offset:32768
	ds_read_b128 v[180:183], v151 offset:33792
	ds_read_b128 v[184:187], v151 offset:34816
	ds_read_b128 v[188:191], v151 offset:35840
	ds_read_b128 v[204:207], v151 offset:36864
	ds_read_b128 v[208:211], v151 offset:37888
	ds_read_b128 v[218:221], v151 offset:38912
	ds_read_b128 v[222:225], v151 offset:39936
	global_load_lds_dwordx4 v[232:233], off
	v_lshl_add_u64 v[232:233], s[26:27], 0, v[130:131]
	s_mov_b32 m0, s43
	s_nop 0
	global_load_lds_dwordx4 v[232:233], off
	s_waitcnt vmcnt(8)
	s_waitcnt lgkmcnt(0)
	s_setprio 0
	s_barrier
	s_waitcnt lgkmcnt(0)
	v_mfma_f32_16x16x32_bf16 v[116:119], v[140:143], v[176:179], v[116:119]
	v_mfma_f32_16x16x32_bf16 v[112:115], v[152:155], v[176:179], v[112:115]
	v_mfma_f32_16x16x32_bf16 v[108:111], v[140:143], v[184:187], v[108:111]
	v_mfma_f32_16x16x32_bf16 v[104:107], v[152:155], v[184:187], v[104:107]
	v_mfma_f32_16x16x32_bf16 v[92:95], v[140:143], v[204:207], v[92:95]
	v_mfma_f32_16x16x32_bf16 v[88:91], v[152:155], v[204:207], v[88:91]
	v_mfma_f32_16x16x32_bf16 v[76:79], v[140:143], v[218:221], v[76:79]
	v_mfma_f32_16x16x32_bf16 v[72:75], v[152:155], v[218:221], v[72:75]
	v_mfma_f32_16x16x32_bf16 v[116:119], v[144:147], v[180:183], v[116:119]
	v_mfma_f32_16x16x32_bf16 v[112:115], v[156:159], v[180:183], v[112:115]
	v_mfma_f32_16x16x32_bf16 v[108:111], v[144:147], v[188:191], v[108:111]
	v_mfma_f32_16x16x32_bf16 v[104:107], v[156:159], v[188:191], v[104:107]
	v_mfma_f32_16x16x32_bf16 v[92:95], v[144:147], v[208:211], v[92:95]
	v_mfma_f32_16x16x32_bf16 v[88:91], v[156:159], v[208:211], v[88:91]
	v_mfma_f32_16x16x32_bf16 v[76:79], v[144:147], v[222:225], v[76:79]
	v_mfma_f32_16x16x32_bf16 v[72:75], v[156:159], v[222:225], v[72:75]
	v_mfma_f32_16x16x32_bf16 v[124:127], v[160:163], v[176:179], v[124:127]
	v_mfma_f32_16x16x32_bf16 v[120:123], v[168:171], v[176:179], v[120:123]
	v_mfma_f32_16x16x32_bf16 v[100:103], v[160:163], v[184:187], v[100:103]
	v_mfma_f32_16x16x32_bf16 v[96:99], v[168:171], v[184:187], v[96:99]
	v_mfma_f32_16x16x32_bf16 v[84:87], v[160:163], v[204:207], v[84:87]
	v_mfma_f32_16x16x32_bf16 v[80:83], v[168:171], v[204:207], v[80:83]
	v_mfma_f32_16x16x32_bf16 v[68:71], v[160:163], v[218:221], v[68:71]
	v_mfma_f32_16x16x32_bf16 v[64:67], v[168:171], v[218:221], v[64:67]
	v_mfma_f32_16x16x32_bf16 v[124:127], v[164:167], v[180:183], v[124:127]
	v_mfma_f32_16x16x32_bf16 v[120:123], v[172:175], v[180:183], v[120:123]
	v_mfma_f32_16x16x32_bf16 v[100:103], v[164:167], v[188:191], v[100:103]
	v_mfma_f32_16x16x32_bf16 v[96:99], v[172:175], v[188:191], v[96:99]
	v_mfma_f32_16x16x32_bf16 v[84:87], v[164:167], v[208:211], v[84:87]
	v_mfma_f32_16x16x32_bf16 v[80:83], v[172:175], v[208:211], v[80:83]
	v_mfma_f32_16x16x32_bf16 v[68:71], v[164:167], v[222:225], v[68:71]
	v_mfma_f32_16x16x32_bf16 v[64:67], v[172:175], v[222:225], v[64:67]
	s_barrier
; #define PG8_STAGE(bufoff, gbase, voff) do { _Pragma("unroll") for (int _i = 0; _i < 2; ++_i) \
;         __builtin_amdgcn_global_load_lds((const unsigned*)((const char*)(gbase) + (voff)[_i]), (PG8_LAS unsigned*)(lds + (bufoff) + ldsw + _i * 8192), 16, 0, 0); } while (0)
; #define PG8_LDA(dst, b, h) do { _Pragma("unroll") for (int m = 0; m < 4; ++m) _Pragma("unroll") for (int k = 0; k < 2; ++k) dst[m][k] = *(const PG8_LAS bf16x8*)(lds + PG8_SA(b, h) + aoff + m * 2048 + k * 1024); } while (0)
; #define PG8_MMA(ai, bj, At, Bt) do { __builtin_amdgcn_s_setprio(1); _Pragma("unroll") for (int m = 0; m < 4; ++m) _Pragma("unroll") for (int n = 0; n < 2; ++n) _Pragma("unroll") for (int k = 0; k < 2; ++k) \
;         acc[ai][bj][m][n] = __builtin_amdgcn_mfma_f32_16x16x32_bf16(Bt[n][k], At[m][k], acc[ai][bj][m][n], 0, 0, 0); __builtin_amdgcn_s_setprio(0); } while (0)
; #define PG8_WAIT_V(n) asm volatile("s_waitcnt vmcnt(" #n ")" ::: "memory")
; #define PG8_WAIT_L(n) asm volatile("s_waitcnt lgkmcnt(" #n ")" ::: "memory")
; #define PG8_BAR __builtin_amdgcn_s_barrier()
; #define PG8_SCHED __builtin_amdgcn_sched_barrier(0)
; template <class Epi, class Sched, bool ALIGN_EPI = false, bool SP2 = false>
; __device__ __forceinline__ void gemm_phase(PG8_LAS unsigned char* lds, const Gemm g, const Sched& S, const Epi& E) {
;     ...
;             PG8_LDA(At, 1, 1); PG8_STAGE(PG8_SB(1, 0), b3, voffB); PG8_STAGE(PG8_SB(1, 1), b3 + hstepB, voffB); PG8_STAGE(PG8_SA(1, 0), a3, voffA);
;             PG8_WAIT_V(8); PG8_WAIT_L(0); PG8_BAR; PG8_MMA(1, 0, At, B0); PG8_MMA(1, 1, At, B1); PG8_BAR; PG8_SCHED;
;     ...
;         if constexpr (ALIGN_EPI) { if (wr == 0) PG8_BAR; }
	s_setprio 1
	s_mov_b32 m0, s45
	v_lshl_add_u64 v[194:195], v[194:195], 0, s[76:77]
	s_add_u32 s24, s24, 0x40080
	ds_read_b128 v[176:179], v151 offset:49152
	ds_read_b128 v[180:183], v151 offset:50176
	ds_read_b128 v[184:187], v151 offset:51200
	ds_read_b128 v[188:191], v151 offset:52224
	ds_read_b128 v[204:207], v151 offset:53248
	ds_read_b128 v[208:211], v151 offset:54272
	ds_read_b128 v[218:221], v151 offset:55296
	ds_read_b128 v[222:225], v151 offset:56320
	global_load_lds_dwordx4 v[194:195], off
	v_lshl_add_u64 v[194:195], v[226:227], 0, s[76:77]
	s_mov_b32 m0, s48
	s_addc_u32 s25, s25, 0
	global_load_lds_dwordx4 v[194:195], off
	v_lshl_add_u64 v[194:195], s[24:25], 0, v[192:193]
	s_mov_b32 m0, s60
	s_nop 0
	global_load_lds_dwordx4 v[194:195], off
	v_lshl_add_u64 v[194:195], s[24:25], 0, v[128:129]
	s_mov_b32 m0, s61
	s_nop 0
	global_load_lds_dwordx4 v[194:195], off
	v_lshl_add_u64 v[194:195], v[228:229], 0, s[76:77]
	s_mov_b32 m0, s49
	s_nop 0
	global_load_lds_dwordx4 v[194:195], off
	v_lshl_add_u64 v[194:195], v[230:231], 0, s[76:77]
	s_mov_b32 m0, s50
	s_nop 0
	global_load_lds_dwordx4 v[194:195], off
	s_waitcnt vmcnt(8)
	s_waitcnt lgkmcnt(0)
	s_setprio 0
	s_barrier
	s_waitcnt lgkmcnt(0)
	v_mfma_f32_16x16x32_bf16 v[60:63], v[140:143], v[176:179], v[60:63]
	v_mfma_f32_16x16x32_bf16 v[56:59], v[152:155], v[176:179], v[56:59]
	v_mfma_f32_16x16x32_bf16 v[44:47], v[140:143], v[184:187], v[44:47]
	v_mfma_f32_16x16x32_bf16 v[40:43], v[152:155], v[184:187], v[40:43]
	v_mfma_f32_16x16x32_bf16 v[28:31], v[140:143], v[204:207], v[28:31]
	v_mfma_f32_16x16x32_bf16 v[24:27], v[152:155], v[204:207], v[24:27]
	v_mfma_f32_16x16x32_bf16 v[12:15], v[140:143], v[218:221], v[12:15]
	v_mfma_f32_16x16x32_bf16 v[8:11], v[152:155], v[218:221], v[8:11]
	v_mfma_f32_16x16x32_bf16 v[60:63], v[144:147], v[180:183], v[60:63]
	v_mfma_f32_16x16x32_bf16 v[56:59], v[156:159], v[180:183], v[56:59]
	v_mfma_f32_16x16x32_bf16 v[44:47], v[144:147], v[188:191], v[44:47]
	v_mfma_f32_16x16x32_bf16 v[40:43], v[156:159], v[188:191], v[40:43]
	v_mfma_f32_16x16x32_bf16 v[28:31], v[144:147], v[208:211], v[28:31]
	v_mfma_f32_16x16x32_bf16 v[24:27], v[156:159], v[208:211], v[24:27]
	v_mfma_f32_16x16x32_bf16 v[12:15], v[144:147], v[222:225], v[12:15]
	v_mfma_f32_16x16x32_bf16 v[8:11], v[156:159], v[222:225], v[8:11]
	v_mfma_f32_16x16x32_bf16 v[52:55], v[160:163], v[176:179], v[52:55]
	v_mfma_f32_16x16x32_bf16 v[48:51], v[168:171], v[176:179], v[48:51]
	v_mfma_f32_16x16x32_bf16 v[36:39], v[160:163], v[184:187], v[36:39]
	v_mfma_f32_16x16x32_bf16 v[32:35], v[168:171], v[184:187], v[32:35]
	v_mfma_f32_16x16x32_bf16 v[20:23], v[160:163], v[204:207], v[20:23]
	v_mfma_f32_16x16x32_bf16 v[16:19], v[168:171], v[204:207], v[16:19]
	v_mfma_f32_16x16x32_bf16 v[4:7], v[160:163], v[218:221], v[4:7]
	v_mfma_f32_16x16x32_bf16 v[0:3], v[168:171], v[218:221], v[0:3]
	v_mfma_f32_16x16x32_bf16 v[52:55], v[164:167], v[180:183], v[52:55]
	v_mfma_f32_16x16x32_bf16 v[48:51], v[172:175], v[180:183], v[48:51]
	v_mfma_f32_16x16x32_bf16 v[36:39], v[164:167], v[188:191], v[36:39]
	v_mfma_f32_16x16x32_bf16 v[32:35], v[172:175], v[188:191], v[32:35]
	v_mfma_f32_16x16x32_bf16 v[20:23], v[164:167], v[208:211], v[20:23]
	v_mfma_f32_16x16x32_bf16 v[16:19], v[172:175], v[208:211], v[16:19]
	v_mfma_f32_16x16x32_bf16 v[4:7], v[164:167], v[222:225], v[4:7]
	v_mfma_f32_16x16x32_bf16 v[0:3], v[172:175], v[222:225], v[0:3]
	s_barrier
	s_setprio 1
	s_add_i32 s72, s72, 2
	s_add_u32 s70, s70, 0x100
	s_addc_u32 s71, s71, 0
	s_add_u32 s22, s22, 0x100
	s_addc_u32 s23, s23, 0
	s_cmp_gt_u32 s72, 13
	s_cbranch_scc0 .LBB0_1221
	s_setprio 0
	s_and_b64 vcc, exec, s[10:11]
	s_cbranch_vccz .LBB0_1224
	s_barrier

; #define PG8_STAGE(bufoff, gbase, voff) do { _Pragma("unroll") for (int _i = 0; _i < 2; ++_i) \
;         __builtin_amdgcn_global_load_lds((const unsigned*)((const char*)(gbase) + (voff)[_i]), (PG8_LAS unsigned*)(lds + (bufoff) + ldsw + _i * 8192), 16, 0, 0); } while (0)
; #define PG8_LDA(dst, b, h) do { _Pragma("unroll") for (int m = 0; m < 4; ++m) _Pragma("unroll") for (int k = 0; k < 2; ++k) dst[m][k] = *(const PG8_LAS bf16x8*)(lds + PG8_SA(b, h) + aoff + m * 2048 + k * 1024); } while (0)
; #define PG8_LDB(dst, b, h) do { _Pragma("unroll") for (int n = 0; n < 2; ++n) _Pragma("unroll") for (int k = 0; k < 2; ++k) dst[n][k] = *(const PG8_LAS bf16x8*)(lds + PG8_SB(b, h) + boff + n * 2048 + k * 1024); } while (0)
; #define PG8_MMA(ai, bj, At, Bt) do { __builtin_amdgcn_s_setprio(1); _Pragma("unroll") for (int m = 0; m < 4; ++m) _Pragma("unroll") for (int n = 0; n < 2; ++n) _Pragma("unroll") for (int k = 0; k < 2; ++k) \
;         acc[ai][bj][m][n] = __builtin_amdgcn_mfma_f32_16x16x32_bf16(Bt[n][k], At[m][k], acc[ai][bj][m][n], 0, 0, 0); __builtin_amdgcn_s_setprio(0); } while (0)
; #define PG8_WAIT_V(n) asm volatile("s_waitcnt vmcnt(" #n ")" ::: "memory")
; #define PG8_WAIT_L(n) asm volatile("s_waitcnt lgkmcnt(" #n ")" ::: "memory")
; #define PG8_BAR __builtin_amdgcn_s_barrier()
; #define PG8_SCHED __builtin_amdgcn_sched_barrier(0)
; template <class Epi, class Sched, bool ALIGN_EPI = false, bool SP2 = false>
; __device__ __forceinline__ void gemm_phase(PG8_LAS unsigned char* lds, const Gemm g, const Sched& S, const Epi& E) {
;     ...
;             PG8_LDB(B0, 0, 0); PG8_LDB(B1, 0, 1); PG8_SCHED; PG8_LDA(At, 0, 0); PG8_STAGE(PG8_SA(1, 1), a1 + hstepA, voffA);
;             PG8_WAIT_V(8); PG8_WAIT_L(0); PG8_BAR; PG8_MMA(0, 0, At, B0); PG8_MMA(0, 1, At, B1); PG8_BAR; PG8_SCHED;
;             PG8_LDA(At, 0, 1); PG8_STAGE(PG8_SB(0, 0), b2, voffB); PG8_STAGE(PG8_SB(0, 1), b2 + hstepB, voffB); PG8_STAGE(PG8_SA(0, 0), a2, voffA);
;             PG8_WAIT_V(8); PG8_WAIT_L(0); PG8_BAR; PG8_MMA(1, 0, At, B0); PG8_MMA(1, 1, At, B1); PG8_BAR; PG8_SCHED;
.LBB0_1319:
	s_setprio 1
	v_add_u32_e32 v142, s35, v145
	ds_read_b128 v[138:141], v142
	ds_read_b128 v[148:151], v142 offset:1024
	ds_read_b128 v[152:155], v142 offset:2048
	ds_read_b128 v[156:159], v142 offset:3072
	v_add_u32_e32 v142, s38, v145
	ds_read_b128 v[160:163], v142
	ds_read_b128 v[164:167], v142 offset:1024
	ds_read_b128 v[168:171], v142 offset:2048
	ds_read_b128 v[172:175], v142 offset:3072
	s_add_u32 s22, s20, 0x100
	s_addc_u32 s23, s21, 0
	s_cmp_eq_u32 s78, 40
	s_cselect_b32 s27, s9, s23
	s_cselect_b32 s26, s8, s22
	s_cselect_b32 s25, s19, s75
	s_cselect_b32 s24, s18, s74
	v_lshl_add_u64 v[142:143], s[20:21], 0, v[136:137]
	s_add_i32 m0, s41, 0xc000
	ds_read_b128 v[176:179], v147
	ds_read_b128 v[180:183], v147 offset:1024
	ds_read_b128 v[184:187], v147 offset:2048
	ds_read_b128 v[188:191], v147 offset:3072
	ds_read_b128 v[204:207], v147 offset:4096
	ds_read_b128 v[208:211], v147 offset:5120
	ds_read_b128 v[218:221], v147 offset:6144
	ds_read_b128 v[222:225], v147 offset:7168
	global_load_lds_dwordx4 v[142:143], off
	v_lshl_add_u64 v[142:143], s[20:21], 0, v[134:135]
	s_add_i32 m0, s41, 0xe000
	s_nop 0
	global_load_lds_dwordx4 v[142:143], off
	s_waitcnt vmcnt(8)
	s_waitcnt lgkmcnt(0)
	s_setprio 0
	s_barrier
	s_waitcnt lgkmcnt(0)
	v_mfma_f32_16x16x32_bf16 v[124:127], v[138:141], v[176:179], v[124:127]
	v_mfma_f32_16x16x32_bf16 v[120:123], v[152:155], v[176:179], v[120:123]
	v_mfma_f32_16x16x32_bf16 v[108:111], v[138:141], v[184:187], v[108:111]
	v_mfma_f32_16x16x32_bf16 v[104:107], v[152:155], v[184:187], v[104:107]
	v_mfma_f32_16x16x32_bf16 v[92:95], v[138:141], v[204:207], v[92:95]
	v_mfma_f32_16x16x32_bf16 v[88:91], v[152:155], v[204:207], v[88:91]
	v_mfma_f32_16x16x32_bf16 v[76:79], v[138:141], v[218:221], v[76:79]
	v_mfma_f32_16x16x32_bf16 v[72:75], v[152:155], v[218:221], v[72:75]
	v_mfma_f32_16x16x32_bf16 v[124:127], v[148:151], v[180:183], v[124:127]
	v_mfma_f32_16x16x32_bf16 v[120:123], v[156:159], v[180:183], v[120:123]
	v_mfma_f32_16x16x32_bf16 v[108:111], v[148:151], v[188:191], v[108:111]
	v_mfma_f32_16x16x32_bf16 v[104:107], v[156:159], v[188:191], v[104:107]
	v_mfma_f32_16x16x32_bf16 v[92:95], v[148:151], v[208:211], v[92:95]
	v_mfma_f32_16x16x32_bf16 v[88:91], v[156:159], v[208:211], v[88:91]
	v_mfma_f32_16x16x32_bf16 v[76:79], v[148:151], v[222:225], v[76:79]
	v_mfma_f32_16x16x32_bf16 v[72:75], v[156:159], v[222:225], v[72:75]
	v_mfma_f32_16x16x32_bf16 v[116:119], v[160:163], v[176:179], v[116:119]
	v_mfma_f32_16x16x32_bf16 v[112:115], v[168:171], v[176:179], v[112:115]
	v_mfma_f32_16x16x32_bf16 v[100:103], v[160:163], v[184:187], v[100:103]
	v_mfma_f32_16x16x32_bf16 v[96:99], v[168:171], v[184:187], v[96:99]
	v_mfma_f32_16x16x32_bf16 v[84:87], v[160:163], v[204:207], v[84:87]
	v_mfma_f32_16x16x32_bf16 v[80:83], v[168:171], v[204:207], v[80:83]
	v_mfma_f32_16x16x32_bf16 v[68:71], v[160:163], v[218:221], v[68:71]
	v_mfma_f32_16x16x32_bf16 v[64:67], v[168:171], v[218:221], v[64:67]
	v_mfma_f32_16x16x32_bf16 v[116:119], v[164:167], v[180:183], v[116:119]
	v_mfma_f32_16x16x32_bf16 v[112:115], v[172:175], v[180:183], v[112:115]
	v_mfma_f32_16x16x32_bf16 v[100:103], v[164:167], v[188:191], v[100:103]
	v_mfma_f32_16x16x32_bf16 v[96:99], v[172:175], v[188:191], v[96:99]
	v_mfma_f32_16x16x32_bf16 v[84:87], v[164:167], v[208:211], v[84:87]
	v_mfma_f32_16x16x32_bf16 v[80:83], v[172:175], v[208:211], v[80:83]
	v_mfma_f32_16x16x32_bf16 v[68:71], v[164:167], v[222:225], v[68:71]
	v_mfma_f32_16x16x32_bf16 v[64:67], v[172:175], v[222:225], v[64:67]
	s_barrier
	s_setprio 1
	s_mov_b32 m0, s36
	v_lshl_add_u64 v[142:143], s[24:25], 0, v[192:193]
	s_add_u32 s20, s24, 0xb0000
	ds_read_b128 v[176:179], v147 offset:16384
	ds_read_b128 v[180:183], v147 offset:17408
	ds_read_b128 v[184:187], v147 offset:18432
	ds_read_b128 v[188:191], v147 offset:19456
	ds_read_b128 v[204:207], v147 offset:20480
	ds_read_b128 v[208:211], v147 offset:21504
	ds_read_b128 v[218:221], v147 offset:22528
	ds_read_b128 v[222:225], v147 offset:23552
	global_load_lds_dwordx4 v[142:143], off
	v_lshl_add_u64 v[194:195], s[24:25], 0, v[132:133]
	s_mov_b32 m0, s37
	s_addc_u32 s21, s25, 0
	global_load_lds_dwordx4 v[194:195], off
	v_lshl_add_u64 v[226:227], s[20:21], 0, v[192:193]
	s_mov_b32 m0, s39
	v_lshl_add_u64 v[228:229], s[26:27], 0, v[130:131]
	global_load_lds_dwordx4 v[226:227], off
	v_lshl_add_u64 v[226:227], s[20:21], 0, v[132:133]
	s_mov_b32 m0, s40
	s_nop 0
	global_load_lds_dwordx4 v[226:227], off
	v_lshl_add_u64 v[226:227], s[26:27], 0, v[128:129]
	s_mov_b32 m0, s41
	s_nop 0
	global_load_lds_dwordx4 v[226:227], off
	s_mov_b32 m0, s42
	s_nop 0
	global_load_lds_dwordx4 v[228:229], off
	s_waitcnt vmcnt(8)
	s_waitcnt lgkmcnt(0)
	s_setprio 0
	s_barrier
; #define PG8_STAGE(bufoff, gbase, voff) do { _Pragma("unroll") for (int _i = 0; _i < 2; ++_i) \
;         __builtin_amdgcn_global_load_lds((const unsigned*)((const char*)(gbase) + (voff)[_i]), (PG8_LAS unsigned*)(lds + (bufoff) + ldsw + _i * 8192), 16, 0, 0); } while (0)
; #define PG8_LDA(dst, b, h) do { _Pragma("unroll") for (int m = 0; m < 4; ++m) _Pragma("unroll") for (int k = 0; k < 2; ++k) dst[m][k] = *(const PG8_LAS bf16x8*)(lds + PG8_SA(b, h) + aoff + m * 2048 + k * 1024); } while (0)
; #define PG8_LDB(dst, b, h) do { _Pragma("unroll") for (int n = 0; n < 2; ++n) _Pragma("unroll") for (int k = 0; k < 2; ++k) dst[n][k] = *(const PG8_LAS bf16x8*)(lds + PG8_SB(b, h) + boff + n * 2048 + k * 1024); } while (0)
; #define PG8_MMA(ai, bj, At, Bt) do { __builtin_amdgcn_s_setprio(1); _Pragma("unroll") for (int m = 0; m < 4; ++m) _Pragma("unroll") for (int n = 0; n < 2; ++n) _Pragma("unroll") for (int k = 0; k < 2; ++k) \
;         acc[ai][bj][m][n] = __builtin_amdgcn_mfma_f32_16x16x32_bf16(Bt[n][k], At[m][k], acc[ai][bj][m][n], 0, 0, 0); __builtin_amdgcn_s_setprio(0); } while (0)
; #define PG8_WAIT_V(n) asm volatile("s_waitcnt vmcnt(" #n ")" ::: "memory")
; #define PG8_WAIT_L(n) asm volatile("s_waitcnt lgkmcnt(" #n ")" ::: "memory")
; #define PG8_BAR __builtin_amdgcn_s_barrier()
; #define PG8_SCHED __builtin_amdgcn_sched_barrier(0)
; template <class Epi, class Sched, bool ALIGN_EPI = false, bool SP2 = false>
; __device__ __forceinline__ void gemm_phase(PG8_LAS unsigned char* lds, const Gemm g, const Sched& S, const Epi& E) {
;     ...
;             PG8_WAIT_V(8); PG8_WAIT_L(0); PG8_BAR; PG8_MMA(1, 0, At, B0); PG8_MMA(1, 1, At, B1); PG8_BAR; PG8_SCHED;
;             PG8_LDB(B0, 1, 0); PG8_LDB(B1, 1, 1); PG8_SCHED; PG8_LDA(At, 1, 0); PG8_STAGE(PG8_SA(0, 1), a2 + hstepA, voffA);
;             PG8_WAIT_V(8); PG8_WAIT_L(0); PG8_BAR; PG8_MMA(0, 0, At, B0); PG8_MMA(0, 1, At, B1); PG8_BAR; PG8_SCHED;
	s_waitcnt lgkmcnt(0)
	v_mfma_f32_16x16x32_bf16 v[60:63], v[138:141], v[176:179], v[60:63]
	v_mfma_f32_16x16x32_bf16 v[56:59], v[152:155], v[176:179], v[56:59]
	v_mfma_f32_16x16x32_bf16 v[44:47], v[138:141], v[184:187], v[44:47]
	v_mfma_f32_16x16x32_bf16 v[40:43], v[152:155], v[184:187], v[40:43]
	v_mfma_f32_16x16x32_bf16 v[28:31], v[138:141], v[204:207], v[28:31]
	v_mfma_f32_16x16x32_bf16 v[24:27], v[152:155], v[204:207], v[24:27]
	v_mfma_f32_16x16x32_bf16 v[12:15], v[138:141], v[218:221], v[12:15]
	v_mfma_f32_16x16x32_bf16 v[8:11], v[152:155], v[218:221], v[8:11]
	v_mfma_f32_16x16x32_bf16 v[60:63], v[148:151], v[180:183], v[60:63]
	v_mfma_f32_16x16x32_bf16 v[56:59], v[156:159], v[180:183], v[56:59]
	v_mfma_f32_16x16x32_bf16 v[44:47], v[148:151], v[188:191], v[44:47]
	v_mfma_f32_16x16x32_bf16 v[40:43], v[156:159], v[188:191], v[40:43]
	v_mfma_f32_16x16x32_bf16 v[28:31], v[148:151], v[208:211], v[28:31]
	v_mfma_f32_16x16x32_bf16 v[24:27], v[156:159], v[208:211], v[24:27]
	v_mfma_f32_16x16x32_bf16 v[12:15], v[148:151], v[222:225], v[12:15]
	v_mfma_f32_16x16x32_bf16 v[8:11], v[156:159], v[222:225], v[8:11]
	v_mfma_f32_16x16x32_bf16 v[52:55], v[160:163], v[176:179], v[52:55]
	v_mfma_f32_16x16x32_bf16 v[48:51], v[168:171], v[176:179], v[48:51]
	v_mfma_f32_16x16x32_bf16 v[36:39], v[160:163], v[184:187], v[36:39]
	v_mfma_f32_16x16x32_bf16 v[32:35], v[168:171], v[184:187], v[32:35]
	v_mfma_f32_16x16x32_bf16 v[20:23], v[160:163], v[204:207], v[20:23]
	v_mfma_f32_16x16x32_bf16 v[16:19], v[168:171], v[204:207], v[16:19]
	v_mfma_f32_16x16x32_bf16 v[4:7], v[160:163], v[218:221], v[4:7]
	v_mfma_f32_16x16x32_bf16 v[0:3], v[168:171], v[218:221], v[0:3]
	v_mfma_f32_16x16x32_bf16 v[52:55], v[164:167], v[180:183], v[52:55]
	v_mfma_f32_16x16x32_bf16 v[48:51], v[172:175], v[180:183], v[48:51]
	v_mfma_f32_16x16x32_bf16 v[36:39], v[164:167], v[188:191], v[36:39]
	v_mfma_f32_16x16x32_bf16 v[32:35], v[172:175], v[188:191], v[32:35]
	v_mfma_f32_16x16x32_bf16 v[20:23], v[164:167], v[208:211], v[20:23]
	v_mfma_f32_16x16x32_bf16 v[16:19], v[172:175], v[208:211], v[16:19]
	v_mfma_f32_16x16x32_bf16 v[4:7], v[164:167], v[222:225], v[4:7]
	v_mfma_f32_16x16x32_bf16 v[0:3], v[172:175], v[222:225], v[0:3]
	s_barrier
	s_setprio 1
	v_add_u32_e32 v156, s48, v145
	v_add_u32_e32 v172, s61, v145
	ds_read_b128 v[138:141], v156
	ds_read_b128 v[148:151], v156 offset:1024
	ds_read_b128 v[152:155], v156 offset:2048
	ds_read_b128 v[156:159], v156 offset:3072
	ds_read_b128 v[160:163], v172
	ds_read_b128 v[164:167], v172 offset:1024
	ds_read_b128 v[168:171], v172 offset:2048
	ds_read_b128 v[172:175], v172 offset:3072
	s_add_u32 s20, s26, 0xb0000
	s_addc_u32 s21, s27, 0
	s_mov_b32 m0, s43
	v_lshl_add_u64 v[230:231], s[20:21], 0, v[128:129]
	ds_read_b128 v[176:179], v147 offset:32768
	ds_read_b128 v[180:183], v147 offset:33792
	ds_read_b128 v[184:187], v147 offset:34816
	ds_read_b128 v[188:191], v147 offset:35840
	ds_read_b128 v[204:207], v147 offset:36864
	ds_read_b128 v[208:211], v147 offset:37888
	ds_read_b128 v[218:221], v147 offset:38912
	ds_read_b128 v[222:225], v147 offset:39936
	global_load_lds_dwordx4 v[230:231], off
	v_lshl_add_u64 v[230:231], s[20:21], 0, v[130:131]
	s_mov_b32 m0, s44
	s_nop 0
	global_load_lds_dwordx4 v[230:231], off
	s_waitcnt vmcnt(8)
	s_waitcnt lgkmcnt(0)
	s_setprio 0
	s_barrier
	s_waitcnt lgkmcnt(0)
	v_mfma_f32_16x16x32_bf16 v[124:127], v[138:141], v[176:179], v[124:127]
	v_mfma_f32_16x16x32_bf16 v[120:123], v[152:155], v[176:179], v[120:123]
	v_mfma_f32_16x16x32_bf16 v[108:111], v[138:141], v[184:187], v[108:111]
	v_mfma_f32_16x16x32_bf16 v[104:107], v[152:155], v[184:187], v[104:107]
	v_mfma_f32_16x16x32_bf16 v[92:95], v[138:141], v[204:207], v[92:95]
	v_mfma_f32_16x16x32_bf16 v[88:91], v[152:155], v[204:207], v[88:91]
	v_mfma_f32_16x16x32_bf16 v[76:79], v[138:141], v[218:221], v[76:79]
	v_mfma_f32_16x16x32_bf16 v[72:75], v[152:155], v[218:221], v[72:75]
	v_mfma_f32_16x16x32_bf16 v[124:127], v[148:151], v[180:183], v[124:127]
	v_mfma_f32_16x16x32_bf16 v[120:123], v[156:159], v[180:183], v[120:123]
	v_mfma_f32_16x16x32_bf16 v[108:111], v[148:151], v[188:191], v[108:111]
	v_mfma_f32_16x16x32_bf16 v[104:107], v[156:159], v[188:191], v[104:107]
	v_mfma_f32_16x16x32_bf16 v[92:95], v[148:151], v[208:211], v[92:95]
	v_mfma_f32_16x16x32_bf16 v[88:91], v[156:159], v[208:211], v[88:91]
	v_mfma_f32_16x16x32_bf16 v[76:79], v[148:151], v[222:225], v[76:79]
	v_mfma_f32_16x16x32_bf16 v[72:75], v[156:159], v[222:225], v[72:75]
	v_mfma_f32_16x16x32_bf16 v[116:119], v[160:163], v[176:179], v[116:119]
	v_mfma_f32_16x16x32_bf16 v[112:115], v[168:171], v[176:179], v[112:115]
	v_mfma_f32_16x16x32_bf16 v[100:103], v[160:163], v[184:187], v[100:103]
	v_mfma_f32_16x16x32_bf16 v[96:99], v[168:171], v[184:187], v[96:99]
	v_mfma_f32_16x16x32_bf16 v[84:87], v[160:163], v[204:207], v[84:87]
	v_mfma_f32_16x16x32_bf16 v[80:83], v[168:171], v[204:207], v[80:83]
	v_mfma_f32_16x16x32_bf16 v[68:71], v[160:163], v[218:221], v[68:71]
	v_mfma_f32_16x16x32_bf16 v[64:67], v[168:171], v[218:221], v[64:67]
	v_mfma_f32_16x16x32_bf16 v[116:119], v[164:167], v[180:183], v[116:119]
	v_mfma_f32_16x16x32_bf16 v[112:115], v[172:175], v[180:183], v[112:115]
	v_mfma_f32_16x16x32_bf16 v[100:103], v[164:167], v[188:191], v[100:103]
	v_mfma_f32_16x16x32_bf16 v[96:99], v[172:175], v[188:191], v[96:99]
	v_mfma_f32_16x16x32_bf16 v[84:87], v[164:167], v[208:211], v[84:87]
	v_mfma_f32_16x16x32_bf16 v[80:83], v[172:175], v[208:211], v[80:83]
	v_mfma_f32_16x16x32_bf16 v[68:71], v[164:167], v[222:225], v[68:71]
	v_mfma_f32_16x16x32_bf16 v[64:67], v[172:175], v[222:225], v[64:67]
	s_barrier
; #define PG8_STAGE(bufoff, gbase, voff) do { _Pragma("unroll") for (int _i = 0; _i < 2; ++_i) \
;         __builtin_amdgcn_global_load_lds((const unsigned*)((const char*)(gbase) + (voff)[_i]), (PG8_LAS unsigned*)(lds + (bufoff) + ldsw + _i * 8192), 16, 0, 0); } while (0)
; #define PG8_LDA(dst, b, h) do { _Pragma("unroll") for (int m = 0; m < 4; ++m) _Pragma("unroll") for (int k = 0; k < 2; ++k) dst[m][k] = *(const PG8_LAS bf16x8*)(lds + PG8_SA(b, h) + aoff + m * 2048 + k * 1024); } while (0)
; #define PG8_MMA(ai, bj, At, Bt) do { __builtin_amdgcn_s_setprio(1); _Pragma("unroll") for (int m = 0; m < 4; ++m) _Pragma("unroll") for (int n = 0; n < 2; ++n) _Pragma("unroll") for (int k = 0; k < 2; ++k) \
;         acc[ai][bj][m][n] = __builtin_amdgcn_mfma_f32_16x16x32_bf16(Bt[n][k], At[m][k], acc[ai][bj][m][n], 0, 0, 0); __builtin_amdgcn_s_setprio(0); } while (0)
; #define PG8_WAIT_V(n) asm volatile("s_waitcnt vmcnt(" #n ")" ::: "memory")
; #define PG8_WAIT_L(n) asm volatile("s_waitcnt lgkmcnt(" #n ")" ::: "memory")
; #define PG8_BAR __builtin_amdgcn_s_barrier()
; #define PG8_SCHED __builtin_amdgcn_sched_barrier(0)
; template <class Epi, class Sched, bool ALIGN_EPI = false, bool SP2 = false>
; __device__ __forceinline__ void gemm_phase(PG8_LAS unsigned char* lds, const Gemm g, const Sched& S, const Epi& E) {
;     ...
;             PG8_LDA(At, 1, 1); PG8_STAGE(PG8_SB(1, 0), b3, voffB); PG8_STAGE(PG8_SB(1, 1), b3 + hstepB, voffB); PG8_STAGE(PG8_SA(1, 0), a3, voffA);
;             PG8_WAIT_V(8); PG8_WAIT_L(0); PG8_BAR; PG8_MMA(1, 0, At, B0); PG8_MMA(1, 1, At, B1); PG8_BAR; PG8_SCHED;
;     __device__ __forceinline__ void operator()(const f32x4 (&acc)[2][2][4][2], const pg8::Unit& u, int wr, int wc, int fr, int fq) const {
;     ...
; #pragma unroll
;         for (int ai = 0; ai < 2; ++ai)
; #pragma unroll
;             for (int m = 0; m < 4; ++m) {
;                 const int row = row0 + ai * 128 + m * 16; float ss = 0.f;
; #pragma unroll
;                 for (int bj = 0; bj < 2; ++bj) {
;                     const size_t off = (size_t)row * DM + col0 + bj * 128;
;                     const v4u b = *(const v4u*)(xb + off);
	s_setprio 1
	s_mov_b32 m0, s49
	v_lshl_add_u64 v[142:143], v[142:143], 0, s[76:77]
	s_add_u32 s20, s24, 0xb0080
	ds_read_b128 v[176:179], v147 offset:49152
	ds_read_b128 v[180:183], v147 offset:50176
	ds_read_b128 v[184:187], v147 offset:51200
	ds_read_b128 v[188:191], v147 offset:52224
	ds_read_b128 v[204:207], v147 offset:53248
	ds_read_b128 v[208:211], v147 offset:54272
	ds_read_b128 v[218:221], v147 offset:55296
	ds_read_b128 v[222:225], v147 offset:56320
	global_load_lds_dwordx4 v[142:143], off
	v_lshl_add_u64 v[142:143], v[194:195], 0, s[76:77]
	s_mov_b32 m0, s50
	s_addc_u32 s21, s25, 0
	global_load_lds_dwordx4 v[142:143], off
	v_lshl_add_u64 v[142:143], s[20:21], 0, v[192:193]
	s_mov_b32 m0, s64
	s_nop 0
	global_load_lds_dwordx4 v[142:143], off
	v_lshl_add_u64 v[142:143], s[20:21], 0, v[132:133]
	s_mov_b32 m0, s65
	s_nop 0
	global_load_lds_dwordx4 v[142:143], off
	v_lshl_add_u64 v[142:143], v[226:227], 0, s[76:77]
	s_mov_b32 m0, s51
	s_nop 0
	global_load_lds_dwordx4 v[142:143], off
	v_lshl_add_u64 v[142:143], v[228:229], 0, s[76:77]
	s_mov_b32 m0, s60
	s_nop 0
	global_load_lds_dwordx4 v[142:143], off
	s_waitcnt vmcnt(8)
	s_waitcnt lgkmcnt(0)
	s_setprio 0
	s_barrier
	s_waitcnt lgkmcnt(0)
	v_mfma_f32_16x16x32_bf16 v[60:63], v[138:141], v[176:179], v[60:63]
	v_mfma_f32_16x16x32_bf16 v[56:59], v[152:155], v[176:179], v[56:59]
	v_mfma_f32_16x16x32_bf16 v[44:47], v[138:141], v[184:187], v[44:47]
	v_mfma_f32_16x16x32_bf16 v[40:43], v[152:155], v[184:187], v[40:43]
	v_mfma_f32_16x16x32_bf16 v[28:31], v[138:141], v[204:207], v[28:31]
	v_mfma_f32_16x16x32_bf16 v[24:27], v[152:155], v[204:207], v[24:27]
	v_mfma_f32_16x16x32_bf16 v[12:15], v[138:141], v[218:221], v[12:15]
	v_mfma_f32_16x16x32_bf16 v[8:11], v[152:155], v[218:221], v[8:11]
	v_mfma_f32_16x16x32_bf16 v[60:63], v[148:151], v[180:183], v[60:63]
	v_mfma_f32_16x16x32_bf16 v[56:59], v[156:159], v[180:183], v[56:59]
	v_mfma_f32_16x16x32_bf16 v[44:47], v[148:151], v[188:191], v[44:47]
	v_mfma_f32_16x16x32_bf16 v[40:43], v[156:159], v[188:191], v[40:43]
	v_mfma_f32_16x16x32_bf16 v[28:31], v[148:151], v[208:211], v[28:31]
	v_mfma_f32_16x16x32_bf16 v[24:27], v[156:159], v[208:211], v[24:27]
	v_mfma_f32_16x16x32_bf16 v[12:15], v[148:151], v[222:225], v[12:15]
	v_mfma_f32_16x16x32_bf16 v[8:11], v[156:159], v[222:225], v[8:11]
	v_mfma_f32_16x16x32_bf16 v[52:55], v[160:163], v[176:179], v[52:55]
	v_mfma_f32_16x16x32_bf16 v[48:51], v[168:171], v[176:179], v[48:51]
	v_mfma_f32_16x16x32_bf16 v[36:39], v[160:163], v[184:187], v[36:39]
	v_mfma_f32_16x16x32_bf16 v[32:35], v[168:171], v[184:187], v[32:35]
	v_mfma_f32_16x16x32_bf16 v[20:23], v[160:163], v[204:207], v[20:23]
	v_mfma_f32_16x16x32_bf16 v[16:19], v[168:171], v[204:207], v[16:19]
	v_mfma_f32_16x16x32_bf16 v[4:7], v[160:163], v[218:221], v[4:7]
	v_mfma_f32_16x16x32_bf16 v[0:3], v[168:171], v[218:221], v[0:3]
	v_mfma_f32_16x16x32_bf16 v[52:55], v[164:167], v[180:183], v[52:55]
	v_mfma_f32_16x16x32_bf16 v[48:51], v[172:175], v[180:183], v[48:51]
	v_mfma_f32_16x16x32_bf16 v[36:39], v[164:167], v[188:191], v[36:39]
	v_mfma_f32_16x16x32_bf16 v[32:35], v[172:175], v[188:191], v[32:35]
	v_mfma_f32_16x16x32_bf16 v[20:23], v[164:167], v[208:211], v[20:23]
	v_mfma_f32_16x16x32_bf16 v[16:19], v[172:175], v[208:211], v[16:19]
	v_mfma_f32_16x16x32_bf16 v[4:7], v[164:167], v[222:225], v[4:7]
	v_mfma_f32_16x16x32_bf16 v[0:3], v[172:175], v[222:225], v[0:3]
	s_barrier
	s_setprio 1
	s_add_i32 s78, s78, 2
	s_add_u32 s74, s74, 0x100
	s_addc_u32 s75, s75, 0
	s_cmp_gt_u32 s78, 41
	s_mov_b64 s[20:21], s[22:23]
	s_cbranch_scc0 .LBB0_1319
	s_setprio 0
	v_lshl_add_u32 v159, s68, 8, v144
	v_lshl_or_b32 v158, s34, 8, v146
	v_lshlrev_b32_e32 v159, 11, v159
	v_lshl_add_u32 v159, v158, 1, v159
	v_add_u32_e32 v218, 0x8000, v159
	v_add_u32_e32 v219, 0x10000, v159
	v_add_u32_e32 v240, 0x18000, v159
	v_add_u32_e32 v241, 0x40000, v159
	v_add_u32_e32 v245, 0x48000, v159
	v_add_u32_e32 v246, 0x50000, v159
	v_add_u32_e32 v247, 0x58000, v159
	global_load_dwordx4 v[160:163], v159, s[12:13]
	global_load_dwordx4 v[164:167], v159, s[12:13] offset:256
	global_load_dwordx4 v[168:171], v218, s[12:13]
	global_load_dwordx4 v[172:175], v218, s[12:13] offset:256
	global_load_dwordx4 v[176:179], v219, s[12:13]
	global_load_dwordx4 v[180:183], v219, s[12:13] offset:256
	global_load_dwordx4 v[184:187], v240, s[12:13]
	global_load_dwordx4 v[188:191], v240, s[12:13] offset:256
	global_load_dwordx4 v[204:207], v241, s[12:13]
	global_load_dwordx4 v[208:211], v241, s[12:13] offset:256
	global_load_dwordx4 v[220:223], v245, s[12:13]
	global_load_dwordx4 v[224:227], v245, s[12:13] offset:256
	global_load_dwordx4 v[228:231], v246, s[12:13]
	global_load_dwordx4 v[232:235], v246, s[12:13] offset:256
	global_load_dwordx4 v[236:239], v247, s[12:13]
	global_load_dwordx4 v[248:251], v247, s[12:13] offset:256
	s_and_b64 vcc, exec, s[16:17]
	s_cbranch_vccz .LBB0_1322
	s_barrier
